# DPP wave sums in sgu/finalize + sgu W loads batched, on cooperative ws_unit + head-major sb
# speedup vs baseline: 1.0123x; 1.0123x over previous
.LBB0_133:
	v_ashrrev_i32_e32 v57, 31, v56
	v_lshlrev_b64 v[32:33], 13, v[56:57]
	v_lshl_add_u64 v[32:33], v[58:59], 0, v[32:33]
	global_load_dwordx4 v[72:75], v[32:33], off offset:16
	global_load_dwordx4 v[76:79], v[32:33], off
	global_load_dwordx4 v[48:51], v[32:33], off offset:2064
	global_load_dwordx4 v[52:55], v[32:33], off offset:2048
	v_lshlrev_b64 v[62:63], 12, v[56:57]
	v_add_co_u32_e32 v36, vcc, s76, v32
	v_lshl_add_u64 v[34:35], v[32:33], 0, s[56:57]
	s_nop 0
	v_addc_co_u32_e32 v37, vcc, 0, v33, vcc
	global_load_dwordx4 v[44:47], v[36:37], off
	global_load_dwordx4 v[40:43], v[34:35], off offset:16
	v_lshl_add_u64 v[32:33], v[32:33], 0, s[8:9]
	global_load_dwordx4 v[36:39], v[36:37], off offset:2048
	s_nop 0
	global_load_dwordx4 v[32:35], v[32:33], off offset:16
	v_lshl_add_u64 v[62:63], v[60:61], 0, v[62:63]
	v_add_u32_e32 v56, s65, v56
	s_waitcnt vmcnt(0)
	v_pk_mul_f32 v[82:83], v[72:73], v[72:73]
	v_mul_f32_e32 v57, v77, v77
	v_fmac_f32_e32 v57, v76, v76
	v_fmac_f32_e32 v57, v78, v78
	v_fmac_f32_e32 v57, v79, v79
	v_add_f32_e32 v57, v82, v57
	v_pk_mul_f32 v[80:81], v[74:75], v[74:75]
	v_add_f32_e32 v57, v83, v57
	v_add_f32_e32 v57, v80, v57
	v_add_f32_e32 v57, v81, v57
	s_nop 1
	v_add_f32_dpp v57, v57, v57 quad_perm:[1,0,3,2] row_mask:0xf bank_mask:0xf
	s_nop 1
	v_add_f32_dpp v57, v57, v57 quad_perm:[2,3,0,1] row_mask:0xf bank_mask:0xf
	s_nop 1
	v_add_f32_dpp v57, v57, v57 row_half_mirror row_mask:0xf bank_mask:0xf
	s_nop 1
	v_add_f32_dpp v57, v57, v57 row_mirror row_mask:0xf bank_mask:0xf
	s_nop 1
	v_add_f32_dpp v57, v57, v57 row_bcast:15 row_mask:0xa bank_mask:0xf
	s_nop 1
	v_add_f32_dpp v57, v57, v57 row_bcast:31 row_mask:0xc bank_mask:0xf
	s_nop 1
	v_readlane_b32 s98, v57, 63
	s_nop 1
	v_mov_b32_e32 v57, s98
	v_fmamk_f32 v57, v57, 0x3b000000, v188
	v_cmp_gt_f32_e32 vcc, s33, v57
	v_mul_f32_e32 v64, 0x4b800000, v57
	s_nop 0
	v_cndmask_b32_e32 v57, v57, v64, vcc
	v_rsq_f32_e32 v57, v57
	s_nop 0
	v_mul_f32_e32 v64, 0x45800000, v57
	v_cndmask_b32_e32 v57, v57, v64, vcc
	v_mul_f32_e32 v72, v72, v57
	v_mul_f32_e32 v64, v76, v57
	v_mul_f32_e32 v76, v77, v57
	v_mul_f32_e32 v77, v78, v57
	v_mul_f32_e32 v78, v79, v57
	v_mul_f32_e32 v79, v28, v72
	v_mul_f32_e32 v72, v73, v57
	v_mul_f32_e32 v80, v29, v72
	v_mul_f32_e32 v72, v74, v57
	v_mul_f32_e32 v57, v75, v57
	v_mul_f32_e32 v57, v31, v57
	v_mul_f32_e32 v64, v24, v64
	v_mul_f32_e32 v76, v25, v76
	v_mul_f32_e32 v77, v26, v77
	v_mul_f32_e32 v78, v27, v78
	v_mul_f32_e32 v81, v30, v72
	v_cvt_pk_bf16_f32 v72, v64, v76
	v_cvt_pk_bf16_f32 v73, v77, v78
	v_cvt_pk_bf16_f32 v74, v79, v80
	v_cvt_pk_bf16_f32 v75, v81, v57
	v_mul_f32_e32 v57, v53, v53
	v_fmac_f32_e32 v57, v52, v52
	v_fmac_f32_e32 v57, v54, v54
	global_store_dwordx4 v[62:63], v[72:75], off
	v_fmac_f32_e32 v57, v55, v55
	s_nop 0
	v_pk_mul_f32 v[74:75], v[48:49], v[48:49]
	v_pk_mul_f32 v[72:73], v[50:51], v[50:51]
	v_add_f32_e32 v57, v74, v57
	v_add_f32_e32 v57, v75, v57
	v_add_f32_e32 v57, v72, v57
	v_add_f32_e32 v57, v73, v57
	s_nop 1
	v_add_f32_dpp v57, v57, v57 quad_perm:[1,0,3,2] row_mask:0xf bank_mask:0xf
	s_nop 1
	v_add_f32_dpp v57, v57, v57 quad_perm:[2,3,0,1] row_mask:0xf bank_mask:0xf
	s_nop 1
	v_add_f32_dpp v57, v57, v57 row_half_mirror row_mask:0xf bank_mask:0xf
	s_nop 1
	v_add_f32_dpp v57, v57, v57 row_mirror row_mask:0xf bank_mask:0xf
	s_nop 1
	v_add_f32_dpp v57, v57, v57 row_bcast:15 row_mask:0xa bank_mask:0xf
	s_nop 1
	v_add_f32_dpp v57, v57, v57 row_bcast:31 row_mask:0xc bank_mask:0xf
	s_nop 1
	v_readlane_b32 s98, v57, 63
	s_nop 1
	v_mov_b32_e32 v57, s98
	v_fmamk_f32 v57, v57, 0x3b000000, v188
	v_cmp_gt_f32_e32 vcc, s33, v57
	v_mul_f32_e32 v64, 0x4b800000, v57
	s_nop 0
	v_cndmask_b32_e32 v57, v57, v64, vcc
	v_rsq_f32_e32 v57, v57
	s_nop 0
	v_mul_f32_e32 v64, 0x45800000, v57
	v_cndmask_b32_e32 v57, v57, v64, vcc
	v_mul_f32_e32 v48, v48, v57
	v_mul_f32_e32 v64, v20, v48
	v_mul_f32_e32 v48, v49, v57
	v_mul_f32_e32 v52, v52, v57
	v_mul_f32_e32 v72, v21, v48
	v_mul_f32_e32 v48, v50, v57
	v_mul_f32_e32 v52, v16, v52
	v_mul_f32_e32 v53, v53, v57
	v_mul_f32_e32 v73, v22, v48
	v_mul_f32_e32 v48, v51, v57
	v_mul_f32_e32 v53, v17, v53
	v_mul_f32_e32 v51, v23, v48
	v_cvt_pk_bf16_f32 v48, v52, v53
	v_mul_f32_e32 v52, v45, v45
	v_mul_f32_e32 v54, v54, v57
	v_mul_f32_e32 v55, v55, v57
	v_fmac_f32_e32 v52, v44, v44
	v_mul_f32_e32 v54, v18, v54
	v_mul_f32_e32 v55, v19, v55
	v_cvt_pk_bf16_f32 v49, v54, v55
	v_cvt_pk_bf16_f32 v50, v64, v72
	v_cvt_pk_bf16_f32 v51, v73, v51
	v_fmac_f32_e32 v52, v46, v46
	global_store_dwordx4 v[62:63], v[48:51], off offset:1024
	v_fmac_f32_e32 v52, v47, v47
	s_nop 0
	v_pk_mul_f32 v[50:51], v[40:41], v[40:41]
	v_pk_mul_f32 v[48:49], v[42:43], v[42:43]
	v_add_f32_e32 v50, v50, v52
	v_add_f32_e32 v50, v51, v50
	v_add_f32_e32 v48, v48, v50
	v_add_f32_e32 v48, v49, v48
	s_nop 1
	v_add_f32_dpp v48, v48, v48 quad_perm:[1,0,3,2] row_mask:0xf bank_mask:0xf
	s_nop 1
	v_add_f32_dpp v48, v48, v48 quad_perm:[2,3,0,1] row_mask:0xf bank_mask:0xf
	s_nop 1
	v_add_f32_dpp v48, v48, v48 row_half_mirror row_mask:0xf bank_mask:0xf
	s_nop 1
	v_add_f32_dpp v48, v48, v48 row_mirror row_mask:0xf bank_mask:0xf
	s_nop 1
	v_add_f32_dpp v48, v48, v48 row_bcast:15 row_mask:0xa bank_mask:0xf
	s_nop 1
	v_add_f32_dpp v48, v48, v48 row_bcast:31 row_mask:0xc bank_mask:0xf
	s_nop 1
	v_readlane_b32 s98, v48, 63
	s_nop 1
	v_mov_b32_e32 v48, s98
	v_fmamk_f32 v48, v48, 0x3b000000, v188
	v_cmp_gt_f32_e32 vcc, s33, v48
	v_mul_f32_e32 v49, 0x4b800000, v48
	s_nop 0
	v_cndmask_b32_e32 v48, v48, v49, vcc
	v_rsq_f32_e32 v48, v48
	s_nop 0
	v_mul_f32_e32 v49, 0x45800000, v48
	v_cndmask_b32_e32 v48, v48, v49, vcc
	v_mul_f32_e32 v40, v40, v48
	v_mul_f32_e32 v49, v12, v40
	v_mul_f32_e32 v40, v41, v48
	v_mul_f32_e32 v44, v44, v48
	v_mul_f32_e32 v50, v13, v40
	v_mul_f32_e32 v40, v42, v48
	v_mul_f32_e32 v44, v4, v44
	v_mul_f32_e32 v45, v45, v48
	v_mul_f32_e32 v51, v14, v40
	v_mul_f32_e32 v40, v43, v48
	v_mul_f32_e32 v45, v5, v45
	v_mul_f32_e32 v43, v15, v40
	v_cvt_pk_bf16_f32 v40, v44, v45
	v_mul_f32_e32 v44, v37, v37
	v_mul_f32_e32 v46, v46, v48
	v_mul_f32_e32 v47, v47, v48
	v_fmac_f32_e32 v44, v36, v36
	v_mul_f32_e32 v46, v6, v46
	v_mul_f32_e32 v47, v7, v47
	v_cvt_pk_bf16_f32 v41, v46, v47
	v_cvt_pk_bf16_f32 v42, v49, v50
	v_cvt_pk_bf16_f32 v43, v51, v43
	v_fmac_f32_e32 v44, v38, v38
	global_store_dwordx4 v[62:63], v[40:43], off offset:2048
	v_fmac_f32_e32 v44, v39, v39
	s_nop 0
	v_pk_mul_f32 v[42:43], v[32:33], v[32:33]
	v_pk_mul_f32 v[40:41], v[34:35], v[34:35]
	v_add_f32_e32 v42, v42, v44
	v_add_f32_e32 v42, v43, v42
	v_add_f32_e32 v40, v40, v42
	v_add_f32_e32 v40, v41, v40
	s_nop 1
	v_add_f32_dpp v40, v40, v40 quad_perm:[1,0,3,2] row_mask:0xf bank_mask:0xf
	s_nop 1
	v_add_f32_dpp v40, v40, v40 quad_perm:[2,3,0,1] row_mask:0xf bank_mask:0xf
	s_nop 1
	v_add_f32_dpp v40, v40, v40 row_half_mirror row_mask:0xf bank_mask:0xf
	s_nop 1
	v_add_f32_dpp v40, v40, v40 row_mirror row_mask:0xf bank_mask:0xf
	s_nop 1
	v_add_f32_dpp v40, v40, v40 row_bcast:15 row_mask:0xa bank_mask:0xf
	s_nop 1
	v_add_f32_dpp v40, v40, v40 row_bcast:31 row_mask:0xc bank_mask:0xf
	s_nop 1
	v_readlane_b32 s98, v40, 63
	s_nop 1
	v_mov_b32_e32 v40, s98
	v_fmamk_f32 v40, v40, 0x3b000000, v188
	v_cmp_gt_f32_e32 vcc, s33, v40
	v_mul_f32_e32 v41, 0x4b800000, v40
	s_nop 0
	v_cndmask_b32_e32 v40, v40, v41, vcc
	v_rsq_f32_e32 v40, v40
	s_nop 0
	v_mul_f32_e32 v41, 0x45800000, v40
	v_cndmask_b32_e32 v40, v40, v41, vcc
	v_mul_f32_e32 v32, v32, v40
	v_mul_f32_e32 v41, v0, v32
	v_mul_f32_e32 v32, v33, v40
	v_mul_f32_e32 v42, v1, v32
	v_mul_f32_e32 v32, v34, v40
	v_mul_f32_e32 v43, v2, v32
	v_mul_f32_e32 v32, v35, v40
	v_cmp_lt_i32_e32 vcc, s68, v56
	v_mul_f32_e32 v36, v36, v40
	v_mul_f32_e32 v37, v37, v40
	v_mul_f32_e32 v38, v38, v40
	v_mul_f32_e32 v39, v39, v40
	v_mul_f32_e32 v35, v3, v32
	s_or_b64 s[6:7], vcc, s[6:7]
	v_mul_f32_e32 v36, v8, v36
	v_mul_f32_e32 v37, v9, v37
	v_mul_f32_e32 v38, v10, v38
	v_mul_f32_e32 v39, v11, v39
	v_cvt_pk_bf16_f32 v32, v36, v37
	v_cvt_pk_bf16_f32 v33, v38, v39
	v_cvt_pk_bf16_f32 v34, v41, v42
	v_cvt_pk_bf16_f32 v35, v43, v35
	global_store_dwordx4 v[62:63], v[32:35], off offset:3072
	s_andn2_b64 exec, exec, s[6:7]
	s_cbranch_execnz .LBB0_133

.LBB0_215:
	s_or_b64 exec, exec, s[0:1]
	v_readlane_b32 s0, v254, 54
	s_waitcnt vmcnt(0) lgkmcnt(0)
	s_barrier
	v_mov_b32_e32 v0, s0
	ds_read_b32 v0, v0
	s_mov_b64 s[0:1], -1
	s_waitcnt lgkmcnt(0)
	v_cmp_lt_i32_e32 vcc, 63, v0
	v_readfirstlane_b32 s2, v0
	s_cbranch_vccnz .LBB0_210
	s_and_b32 s3, s2, 1
	s_lshl_b32 s0, s3, 2
	s_add_i32 s40, s0, s20
	s_and_b32 s0, s2, -2
	s_sub_i32 s39, 63, s0
	s_sub_i32 s41, s39, s21
	s_lshl_b32 s35, s41, 5
	v_readlane_b32 s0, v253, 31
	s_mul_i32 s38, s40, 0x2980
	v_and_b32_e32 v149, 31, v186
	v_bfe_u32 v147, v186, 5, 1
	s_or_b32 s2, s3, s0
	v_or_b32_e32 v150, s35, v149
	s_lshl_b32 s1, s0, 10
	v_add_u32_e32 v151, s1, v150
	s_lshl_b32 s1, s2, 13
	s_add_u32 s16, s28, s1
	s_addc_u32 s17, s29, 0
	v_lshlrev_b32_e32 v152, 2, v150
	global_load_dword v140, v152, s[16:17]
	s_sub_i32 s1, s39, 1
	s_lshl_b32 s1, s1, 7
	v_and_b32_e32 v144, 63, v186
	v_lshl_add_u32 v155, v144, 2, s1
	global_load_dword v100, v155, s[16:17]
	v_lshlrev_b32_e32 v153, 10, v151
	v_lshl_add_u32 v153, v147, 4, v153
	s_lshl_b32 s1, s40, 7
	s_add_u32 s16, s10, s1
	s_addc_u32 s17, s11, 0
	global_load_dwordx4 v[48:51], v153, s[16:17]
	global_load_dwordx4 v[52:55], v153, s[16:17] offset:32
	global_load_dwordx4 v[56:59], v153, s[16:17] offset:64
	global_load_dwordx4 v[60:63], v153, s[16:17] offset:96
	v_mul_u32_u24_e32 v154, s66, v151
	s_mul_i32 s1, s40, 6
	v_add_u32_e32 v154, s1, v154
	global_load_dword v141, v154, s[12:13] offset:2
	v_lshlrev_b32_e32 v144, 4, v144
	v_xor_b32_e32 v102, 48, v144
	v_lshlrev_b32_e32 v145, 5, v149
	v_lshl_add_u32 v145, v147, 4, v145
	s_lshl_b32 s0, s2, 18
	s_lshl_b32 s1, s20, 10
	s_add_u32 s0, s0, s1
	s_cmp_eq_u32 s21, 0
	s_cselect_b32 s16, s22, s26
	s_cselect_b32 s17, s23, s27
	s_cselect_b32 s18, s30, s24
	s_cselect_b32 s3, s31, s25
	s_cselect_b64 vcc, -1, 0
	s_add_u32 s42, s16, s0
	s_addc_u32 s43, s17, 0
	s_add_u32 s44, s18, s0
	s_addc_u32 s45, s3, 0
	v_cndmask_b32_e32 v98, v145, v144, vcc
	s_lshl_b32 s0, s21, 2
	s_add_i32 s0, s0, s20
	s_lshl_b32 s0, s0, 10
	s_add_i32 s36, s0, 0x15000
	s_sub_i32 s14, s39, 17
	s_max_i32 s14, s14, 0
	s_mov_b32 s46, 0
	s_mov_b32 s47, s14
	s_mov_b32 s49, 0
	s_mov_b32 s15, 0
	s_mov_b32 s48, 0
	s_lshl_b32 s16, s47, 12
	s_cmp_eq_u32 s46, 0
	s_cselect_b32 s0, s42, s44
	s_cselect_b32 s1, s43, s45
	s_add_u32 s0, s0, s16
	s_addc_u32 s1, s1, 0
	s_and_b32 s16, s49, 7
	s_lshl_b32 s16, s16, 13
	s_add_i32 m0, s16, s36
	s_add_i32 s49, s49, 1
	global_load_lds_dwordx4 v98, s[0:1]
	s_cmp_eq_u32 s46, 0
	s_cbranch_scc0 .Lws_ga1_sel
	s_add_i32 s47, s47, 1
	s_cmp_le_i32 s47, s39
	s_cbranch_scc1 .Lws_ga1_done
	s_mov_b32 s46, 1
	s_branch .Lws_ga1_blk

.LBB0_407:
	s_or_b64 exec, exec, s[0:1]
	v_lshlrev_b32_e32 v62, 16, v56
	v_mul_f32_e32 v63, 0x3d372713, v62
	v_mul_f32_e32 v63, v63, v62
	v_fma_f32 v63, v63, v62, v62
	v_mul_f32_e32 v63, 0x3f4c422a, v63
	v_add_f32_e32 v63, v63, v63
	v_mul_f32_e32 v63, 0x3fb8aa3b, v63
	v_exp_f32_e32 v63, v63
	v_lshlrev_b32_e32 v67, 16, v58
	v_and_b32_e32 v56, 0xffff0000, v56
	v_and_b32_e32 v58, 0xffff0000, v58
	v_add_f32_e32 v63, 1.0, v63
	v_div_scale_f32 v69, s[0:1], v63, v63, 2.0
	v_rcp_f32_e32 v70, v69
	v_lshlrev_b32_e32 v64, 16, v57
	v_lshlrev_b32_e32 v71, 16, v59
	v_and_b32_e32 v57, 0xffff0000, v57
	v_fma_f32 v72, -v69, v70, 1.0
	v_fmac_f32_e32 v70, v72, v70
	v_div_scale_f32 v72, vcc, 2.0, v63, 2.0
	v_mul_f32_e32 v73, v72, v70
	s_waitcnt lgkmcnt(0)
	v_fma_f32 v74, -v69, v73, v72
	v_fmac_f32_e32 v73, v74, v70
	v_fma_f32 v69, -v69, v73, v72
	v_mul_f32_e32 v72, 0x3d372713, v67
	v_mul_f32_e32 v72, v72, v67
	v_fma_f32 v72, v72, v67, v67
	v_mul_f32_e32 v72, 0x3f4c422a, v72
	v_add_f32_e32 v72, v72, v72
	v_mul_f32_e32 v72, 0x3fb8aa3b, v72
	v_exp_f32_e32 v72, v72
	v_div_fmas_f32 v69, v69, v70, v73
	v_div_fixup_f32 v63, v69, v63, 2.0
	v_and_b32_e32 v59, 0xffff0000, v59
	v_add_f32_e32 v69, 1.0, v72
	v_div_scale_f32 v70, s[0:1], v69, v69, 2.0
	v_rcp_f32_e32 v72, v70
	v_sub_f32_e32 v63, 1.0, v63
	v_mul_f32_e32 v62, 0.5, v62
	v_add_f32_e32 v63, 1.0, v63
	v_fma_f32 v73, -v70, v72, 1.0
	v_fmac_f32_e32 v72, v73, v72
	v_div_scale_f32 v73, vcc, 2.0, v69, 2.0
	v_mul_f32_e32 v74, v73, v72
	v_fma_f32 v75, -v70, v74, v73
	v_fmac_f32_e32 v74, v75, v72
	v_fma_f32 v70, -v70, v74, v73
	v_mul_f32_e32 v73, 0x3d372713, v56
	v_mul_f32_e32 v73, v73, v56
	v_fma_f32 v73, v73, v56, v56
	v_mul_f32_e32 v73, 0x3f4c422a, v73
	v_add_f32_e32 v73, v73, v73
	v_mul_f32_e32 v73, 0x3fb8aa3b, v73
	v_exp_f32_e32 v73, v73
	v_div_fmas_f32 v70, v70, v72, v74
	v_div_fixup_f32 v69, v70, v69, 2.0
	v_mul_f32_e32 v74, 0.5, v67
	v_add_f32_e32 v70, 1.0, v73
	v_div_scale_f32 v72, s[0:1], v70, v70, 2.0
	v_rcp_f32_e32 v73, v72
	v_sub_f32_e32 v69, 1.0, v69
	v_add_f32_e32 v69, 1.0, v69
	v_fma_f32 v67, -v72, v73, 1.0
	v_fmac_f32_e32 v73, v67, v73
	v_div_scale_f32 v67, vcc, 2.0, v70, 2.0
	v_mul_f32_e32 v75, v67, v73
	v_fma_f32 v76, -v72, v75, v67
	v_fmac_f32_e32 v75, v76, v73
	v_fma_f32 v67, -v72, v75, v67
	v_mul_f32_e32 v72, 0x3d372713, v58
	v_mul_f32_e32 v72, v72, v58
	v_fma_f32 v72, v72, v58, v58
	v_mul_f32_e32 v72, 0x3f4c422a, v72
	v_add_f32_e32 v72, v72, v72
	v_mul_f32_e32 v72, 0x3fb8aa3b, v72
	v_exp_f32_e32 v72, v72
	v_div_fmas_f32 v67, v67, v73, v75
	v_div_fixup_f32 v67, v67, v70, 2.0
	v_mul_f32_e32 v75, 0.5, v56
	v_add_f32_e32 v70, 1.0, v72
	v_div_scale_f32 v72, s[0:1], v70, v70, 2.0
	v_rcp_f32_e32 v73, v72
	v_sub_f32_e32 v67, 1.0, v67
	v_add_f32_e32 v76, 1.0, v67
	v_fma_f32 v56, -v72, v73, 1.0
	v_fmac_f32_e32 v73, v56, v73
	v_div_scale_f32 v56, vcc, 2.0, v70, 2.0
	v_mul_f32_e32 v67, v56, v73
	v_fma_f32 v77, -v72, v67, v56
	v_fmac_f32_e32 v67, v77, v73
	v_fma_f32 v56, -v72, v67, v56
	v_mul_f32_e32 v72, 0x3d372713, v64
	v_mul_f32_e32 v72, v72, v64
	v_fma_f32 v72, v72, v64, v64
	v_mul_f32_e32 v72, 0x3f4c422a, v72
	v_add_f32_e32 v72, v72, v72
	v_mul_f32_e32 v72, 0x3fb8aa3b, v72
	v_exp_f32_e32 v72, v72
	v_div_fmas_f32 v56, v56, v73, v67
	v_div_fixup_f32 v56, v56, v70, 2.0
	v_sub_f32_e32 v56, 1.0, v56
	v_add_f32_e32 v67, 1.0, v72
	v_div_scale_f32 v70, s[0:1], v67, v67, 2.0
	v_rcp_f32_e32 v72, v70
	v_add_f32_e32 v77, 1.0, v56
	v_mul_f32_e32 v73, 0.5, v58
	v_fma_f32 v56, -v70, v72, 1.0
	v_fmac_f32_e32 v72, v56, v72
	v_div_scale_f32 v56, vcc, 2.0, v67, 2.0
	v_mul_f32_e32 v58, v56, v72
	v_fma_f32 v78, -v70, v58, v56
	v_fmac_f32_e32 v58, v78, v72
	v_fma_f32 v56, -v70, v58, v56
	v_mul_f32_e32 v70, 0x3d372713, v71
	v_mul_f32_e32 v70, v70, v71
	v_fma_f32 v70, v70, v71, v71
	v_mul_f32_e32 v70, 0x3f4c422a, v70
	v_add_f32_e32 v70, v70, v70
	v_mul_f32_e32 v70, 0x3fb8aa3b, v70
	v_exp_f32_e32 v70, v70
	v_div_fmas_f32 v56, v56, v72, v58
	v_div_fixup_f32 v56, v56, v67, 2.0
	v_sub_f32_e32 v56, 1.0, v56
	v_add_f32_e32 v58, 1.0, v70
	v_div_scale_f32 v67, s[0:1], v58, v58, 2.0
	v_rcp_f32_e32 v70, v67
	v_add_f32_e32 v78, 1.0, v56
	v_mul_f32_e32 v72, 0.5, v64
	v_fma_f32 v56, -v67, v70, 1.0
	v_fmac_f32_e32 v70, v56, v70
	v_div_scale_f32 v56, vcc, 2.0, v58, 2.0
	v_mul_f32_e32 v64, v56, v70
	v_fma_f32 v79, -v67, v64, v56
	v_fmac_f32_e32 v64, v79, v70
	v_fma_f32 v56, -v67, v64, v56
	v_mul_f32_e32 v67, 0x3d372713, v57
	v_mul_f32_e32 v67, v67, v57
	v_fma_f32 v67, v67, v57, v57
	v_mul_f32_e32 v67, 0x3f4c422a, v67
	v_add_f32_e32 v67, v67, v67
	v_mul_f32_e32 v67, 0x3fb8aa3b, v67
	v_exp_f32_e32 v67, v67
	v_div_fmas_f32 v56, v56, v70, v64
	v_div_fixup_f32 v56, v56, v58, 2.0
	v_sub_f32_e32 v56, 1.0, v56
	v_add_f32_e32 v58, 1.0, v67
	v_div_scale_f32 v64, s[0:1], v58, v58, 2.0
	v_rcp_f32_e32 v67, v64
	v_mul_f32_e32 v70, 0.5, v71
	v_add_f32_e32 v71, 1.0, v56
	v_fma_f32 v56, -v64, v67, 1.0
	v_fmac_f32_e32 v67, v56, v67
	v_div_scale_f32 v56, vcc, 2.0, v58, 2.0
	v_mul_f32_e32 v79, v56, v67
	v_fma_f32 v80, -v64, v79, v56
	v_fmac_f32_e32 v79, v80, v67
	v_fma_f32 v56, -v64, v79, v56
	v_mul_f32_e32 v64, 0x3d372713, v59
	v_mul_f32_e32 v64, v64, v59
	v_fma_f32 v64, v64, v59, v59
	v_mul_f32_e32 v64, 0x3f4c422a, v64
	v_add_f32_e32 v64, v64, v64
	v_mul_f32_e32 v64, 0x3fb8aa3b, v64
	v_exp_f32_e32 v64, v64
	v_div_fmas_f32 v56, v56, v67, v79
	v_div_fixup_f32 v56, v56, v58, 2.0
	v_sub_f32_e32 v56, 1.0, v56
	v_add_f32_e32 v58, 1.0, v64
	v_div_scale_f32 v64, s[0:1], v58, v58, 2.0
	v_rcp_f32_e32 v67, v64
	v_add_f32_e32 v80, 1.0, v56
	v_mul_f32_e32 v79, 0.5, v57
	v_fma_f32 v56, -v64, v67, 1.0
	v_fmac_f32_e32 v67, v56, v67
	v_div_scale_f32 v56, vcc, 2.0, v58, 2.0
	v_mul_f32_e32 v57, v56, v67
	v_fma_f32 v81, -v64, v57, v56
	v_fmac_f32_e32 v57, v81, v67
	v_fma_f32 v56, -v64, v57, v56
	v_div_fmas_f32 v56, v56, v67, v57
	v_div_fixup_f32 v56, v56, v58, 2.0
	v_sub_f32_e32 v56, 1.0, v56
	v_add_f32_e32 v82, 1.0, v56
	v_fma_f32 v56, v62, v63, 0
	v_fmac_f32_e32 v56, v75, v76
	v_fmac_f32_e32 v56, v72, v78
	v_fmac_f32_e32 v56, v79, v80
	v_fmac_f32_e32 v56, v74, v69
	v_fmac_f32_e32 v56, v73, v77
	v_mul_f32_e32 v81, 0.5, v59
	v_fmac_f32_e32 v56, v70, v71
	v_fmac_f32_e32 v56, v81, v82
	s_nop 1
	v_add_f32_dpp v56, v56, v56 quad_perm:[1,0,3,2] row_mask:0xf bank_mask:0xf
	s_nop 1
	v_add_f32_dpp v56, v56, v56 quad_perm:[2,3,0,1] row_mask:0xf bank_mask:0xf
	s_nop 1
	v_add_f32_dpp v56, v56, v56 row_half_mirror row_mask:0xf bank_mask:0xf
	s_nop 1
	v_add_f32_dpp v56, v56, v56 row_mirror row_mask:0xf bank_mask:0xf
	s_nop 1
	v_add_f32_dpp v56, v56, v56 row_bcast:15 row_mask:0xa bank_mask:0xf
	s_nop 1
	v_add_f32_dpp v56, v56, v56 row_bcast:31 row_mask:0xc bank_mask:0xf
	s_nop 1
	v_readlane_b32 s98, v56, 63
	s_nop 1
	v_mov_b32_e32 v56, s98
	v_mul_f32_e32 v56, 0xbb000000, v56
	v_fma_f32 v64, v75, v76, v56
	v_fma_f32 v67, v62, v63, v56
	v_mul_f32_e32 v75, v64, v64
	v_fmac_f32_e32 v75, v67, v67
	v_fma_f32 v57, v72, v78, v56
	v_fmac_f32_e32 v75, v57, v57
	v_fma_f32 v58, v79, v80, v56
	v_fmac_f32_e32 v75, v58, v58
	v_fma_f32 v59, v74, v69, v56
	v_fmac_f32_e32 v75, v59, v59
	v_fma_f32 v62, v73, v77, v56
	v_fmac_f32_e32 v75, v62, v62
	v_fma_f32 v63, v70, v71, v56
	v_fmac_f32_e32 v75, v63, v63
	v_fmac_f32_e32 v56, v81, v82
	v_fmac_f32_e32 v75, v56, v56
	s_nop 1
	v_add_f32_dpp v69, v75, v75 quad_perm:[1,0,3,2] row_mask:0xf bank_mask:0xf
	s_nop 1
	v_add_f32_dpp v69, v69, v69 quad_perm:[2,3,0,1] row_mask:0xf bank_mask:0xf
	s_nop 1
	v_add_f32_dpp v69, v69, v69 row_half_mirror row_mask:0xf bank_mask:0xf
	s_nop 1
	v_add_f32_dpp v69, v69, v69 row_mirror row_mask:0xf bank_mask:0xf
	s_nop 1
	v_add_f32_dpp v69, v69, v69 row_bcast:15 row_mask:0xa bank_mask:0xf
	s_nop 1
	v_add_f32_dpp v69, v69, v69 row_bcast:31 row_mask:0xc bank_mask:0xf
	s_nop 1
	v_readlane_b32 s98, v69, 63
	s_nop 1
	v_mov_b32_e32 v69, s98
	v_mov_b32_e32 v70, 0
	s_and_saveexec_b64 s[0:1], s[38:39]
	s_cbranch_execz .LBB0_409
	s_waitcnt lgkmcnt(0)
	v_add_f32_e32 v69, v69, v70
	v_fmamk_f32 v69, v69, 0x3b000000, v189
	v_mul_f32_e32 v70, 0x4b800000, v69
	v_cmp_gt_f32_e32 vcc, s33, v69
	s_nop 1
	v_cndmask_b32_e32 v69, v69, v70, vcc
	v_rsq_f32_e32 v69, v69
	s_nop 0
	v_mul_f32_e32 v70, 0x45800000, v69
	v_cndmask_b32_e32 v69, v69, v70, vcc
	v_mul_f32_e32 v67, v67, v69
	v_mul_f32_e32 v64, v64, v69
	v_mul_f32_e32 v57, v57, v69
	v_cvt_pk_bf16_f32 v67, v67, v65
	ds_write_b16 v61, v67 offset:2
	v_cvt_pk_bf16_f32 v64, v64, v65
	ds_write_b16 v61, v64 offset:274
	v_cvt_pk_bf16_f32 v57, v57, v65
	ds_write_b16 v61, v57 offset:546
	v_mul_f32_e32 v57, v58, v69
	v_cvt_pk_bf16_f32 v57, v57, v65
	ds_write_b16 v61, v57 offset:818
	v_mul_f32_e32 v57, v59, v69
	v_cvt_pk_bf16_f32 v57, v57, v65
	ds_write_b16 v61, v57 offset:1090
	v_mul_f32_e32 v57, v62, v69
	v_cvt_pk_bf16_f32 v57, v57, v65
	ds_write_b16 v61, v57 offset:1362
	v_mul_f32_e32 v57, v63, v69
	v_mul_f32_e32 v56, v56, v69
	v_cvt_pk_bf16_f32 v57, v57, v65
	ds_write_b16 v61, v57 offset:1634
	v_cvt_pk_bf16_f32 v56, v56, v65
	ds_write_b16 v61, v56 offset:1906
.LBB0_409:
	s_or_b64 exec, exec, s[0:1]
	v_lshlrev_b32_e32 v56, 16, v52
	v_mul_f32_e32 v57, 0x3d372713, v56
	v_mul_f32_e32 v57, v57, v56
	v_fma_f32 v57, v57, v56, v56
	v_mul_f32_e32 v57, 0x3f4c422a, v57
	v_add_f32_e32 v57, v57, v57
	v_mul_f32_e32 v57, 0x3fb8aa3b, v57
	v_exp_f32_e32 v57, v57
	v_lshlrev_b32_e32 v59, 16, v54
	v_and_b32_e32 v52, 0xffff0000, v52
	v_and_b32_e32 v54, 0xffff0000, v54
	v_add_f32_e32 v57, 1.0, v57
	v_div_scale_f32 v62, s[0:1], v57, v57, 2.0
	v_rcp_f32_e32 v63, v62
	v_lshlrev_b32_e32 v58, 16, v53
	v_lshlrev_b32_e32 v64, 16, v55
	v_and_b32_e32 v53, 0xffff0000, v53
	v_fma_f32 v67, -v62, v63, 1.0
	v_fmac_f32_e32 v63, v67, v63
	v_div_scale_f32 v67, vcc, 2.0, v57, 2.0
	v_mul_f32_e32 v69, v67, v63
	s_waitcnt lgkmcnt(0)
	v_fma_f32 v70, -v62, v69, v67
	v_fmac_f32_e32 v69, v70, v63
	v_fma_f32 v62, -v62, v69, v67
	v_mul_f32_e32 v67, 0x3d372713, v59
	v_mul_f32_e32 v67, v67, v59
	v_fma_f32 v67, v67, v59, v59
	v_mul_f32_e32 v67, 0x3f4c422a, v67
	v_add_f32_e32 v67, v67, v67
	v_mul_f32_e32 v67, 0x3fb8aa3b, v67
	v_exp_f32_e32 v67, v67
	v_div_fmas_f32 v62, v62, v63, v69
	v_div_fixup_f32 v57, v62, v57, 2.0
	v_and_b32_e32 v55, 0xffff0000, v55
	v_add_f32_e32 v62, 1.0, v67
	v_div_scale_f32 v63, s[0:1], v62, v62, 2.0
	v_rcp_f32_e32 v67, v63
	v_sub_f32_e32 v57, 1.0, v57
	v_mul_f32_e32 v56, 0.5, v56
	v_add_f32_e32 v57, 1.0, v57
	v_fma_f32 v69, -v63, v67, 1.0
	v_fmac_f32_e32 v67, v69, v67
	v_div_scale_f32 v69, vcc, 2.0, v62, 2.0
	v_mul_f32_e32 v70, v69, v67
	v_fma_f32 v71, -v63, v70, v69
	v_fmac_f32_e32 v70, v71, v67
	v_fma_f32 v63, -v63, v70, v69
	v_mul_f32_e32 v69, 0x3d372713, v52
	v_mul_f32_e32 v69, v69, v52
	v_fma_f32 v69, v69, v52, v52
	v_mul_f32_e32 v69, 0x3f4c422a, v69
	v_add_f32_e32 v69, v69, v69
	v_mul_f32_e32 v69, 0x3fb8aa3b, v69
	v_exp_f32_e32 v69, v69
	v_div_fmas_f32 v63, v63, v67, v70
	v_div_fixup_f32 v62, v63, v62, 2.0
	v_mul_f32_e32 v70, 0.5, v59
	v_add_f32_e32 v63, 1.0, v69
	v_div_scale_f32 v67, s[0:1], v63, v63, 2.0
	v_rcp_f32_e32 v69, v67
	v_sub_f32_e32 v62, 1.0, v62
	v_add_f32_e32 v62, 1.0, v62
	v_fma_f32 v59, -v67, v69, 1.0
	v_fmac_f32_e32 v69, v59, v69
	v_div_scale_f32 v59, vcc, 2.0, v63, 2.0
	v_mul_f32_e32 v71, v59, v69
	v_fma_f32 v72, -v67, v71, v59
	v_fmac_f32_e32 v71, v72, v69
	v_fma_f32 v59, -v67, v71, v59
	v_mul_f32_e32 v67, 0x3d372713, v54
	v_mul_f32_e32 v67, v67, v54
	v_fma_f32 v67, v67, v54, v54
	v_mul_f32_e32 v67, 0x3f4c422a, v67
	v_add_f32_e32 v67, v67, v67
	v_mul_f32_e32 v67, 0x3fb8aa3b, v67
	v_exp_f32_e32 v67, v67
	v_div_fmas_f32 v59, v59, v69, v71
	v_div_fixup_f32 v59, v59, v63, 2.0
	v_mul_f32_e32 v71, 0.5, v52
	v_add_f32_e32 v63, 1.0, v67
	v_div_scale_f32 v67, s[0:1], v63, v63, 2.0
	v_rcp_f32_e32 v69, v67
	v_sub_f32_e32 v59, 1.0, v59
	v_add_f32_e32 v72, 1.0, v59
	v_fma_f32 v52, -v67, v69, 1.0
	v_fmac_f32_e32 v69, v52, v69
	v_div_scale_f32 v52, vcc, 2.0, v63, 2.0
	v_mul_f32_e32 v59, v52, v69
	v_fma_f32 v73, -v67, v59, v52
	v_fmac_f32_e32 v59, v73, v69
	v_fma_f32 v52, -v67, v59, v52
	v_mul_f32_e32 v67, 0x3d372713, v58
	v_mul_f32_e32 v67, v67, v58
	v_fma_f32 v67, v67, v58, v58
	v_mul_f32_e32 v67, 0x3f4c422a, v67
	v_add_f32_e32 v67, v67, v67
	v_mul_f32_e32 v67, 0x3fb8aa3b, v67
	v_exp_f32_e32 v67, v67
	v_div_fmas_f32 v52, v52, v69, v59
	v_div_fixup_f32 v52, v52, v63, 2.0
	v_sub_f32_e32 v52, 1.0, v52
	v_add_f32_e32 v59, 1.0, v67
	v_div_scale_f32 v63, s[0:1], v59, v59, 2.0
	v_rcp_f32_e32 v67, v63
	v_add_f32_e32 v73, 1.0, v52
	v_mul_f32_e32 v69, 0.5, v54
	v_fma_f32 v52, -v63, v67, 1.0
	v_fmac_f32_e32 v67, v52, v67
	v_div_scale_f32 v52, vcc, 2.0, v59, 2.0
	v_mul_f32_e32 v54, v52, v67
	v_fma_f32 v74, -v63, v54, v52
	v_fmac_f32_e32 v54, v74, v67
	v_fma_f32 v52, -v63, v54, v52
	v_mul_f32_e32 v63, 0x3d372713, v64
	v_mul_f32_e32 v63, v63, v64
	v_fma_f32 v63, v63, v64, v64
	v_mul_f32_e32 v63, 0x3f4c422a, v63
	v_add_f32_e32 v63, v63, v63
	v_mul_f32_e32 v63, 0x3fb8aa3b, v63
	v_exp_f32_e32 v63, v63
	v_div_fmas_f32 v52, v52, v67, v54
	v_div_fixup_f32 v52, v52, v59, 2.0
	v_sub_f32_e32 v52, 1.0, v52
	v_add_f32_e32 v54, 1.0, v63
	v_div_scale_f32 v59, s[0:1], v54, v54, 2.0
	v_rcp_f32_e32 v63, v59
	v_add_f32_e32 v74, 1.0, v52
	v_mul_f32_e32 v67, 0.5, v58
	v_fma_f32 v52, -v59, v63, 1.0
	v_fmac_f32_e32 v63, v52, v63
	v_div_scale_f32 v52, vcc, 2.0, v54, 2.0
	v_mul_f32_e32 v58, v52, v63
	v_fma_f32 v75, -v59, v58, v52
	v_fmac_f32_e32 v58, v75, v63
	v_fma_f32 v52, -v59, v58, v52
	v_mul_f32_e32 v59, 0x3d372713, v53
	v_mul_f32_e32 v59, v59, v53
	v_fma_f32 v59, v59, v53, v53
	v_mul_f32_e32 v59, 0x3f4c422a, v59
	v_add_f32_e32 v59, v59, v59
	v_mul_f32_e32 v59, 0x3fb8aa3b, v59
	v_exp_f32_e32 v59, v59
	v_div_fmas_f32 v52, v52, v63, v58
	v_div_fixup_f32 v52, v52, v54, 2.0
	v_sub_f32_e32 v52, 1.0, v52
	v_add_f32_e32 v54, 1.0, v59
	v_div_scale_f32 v58, s[0:1], v54, v54, 2.0
	v_rcp_f32_e32 v59, v58
	v_mul_f32_e32 v63, 0.5, v64
	v_add_f32_e32 v64, 1.0, v52
	v_fma_f32 v52, -v58, v59, 1.0
	v_fmac_f32_e32 v59, v52, v59
	v_div_scale_f32 v52, vcc, 2.0, v54, 2.0
	v_mul_f32_e32 v75, v52, v59
	v_fma_f32 v76, -v58, v75, v52
	v_fmac_f32_e32 v75, v76, v59
	v_fma_f32 v52, -v58, v75, v52
	v_mul_f32_e32 v58, 0x3d372713, v55
	v_mul_f32_e32 v58, v58, v55
	v_fma_f32 v58, v58, v55, v55
	v_mul_f32_e32 v58, 0x3f4c422a, v58
	v_add_f32_e32 v58, v58, v58
	v_mul_f32_e32 v58, 0x3fb8aa3b, v58
	v_exp_f32_e32 v58, v58
	v_div_fmas_f32 v52, v52, v59, v75
	v_div_fixup_f32 v52, v52, v54, 2.0
	v_sub_f32_e32 v52, 1.0, v52
	v_add_f32_e32 v54, 1.0, v58
	v_div_scale_f32 v58, s[0:1], v54, v54, 2.0
	v_rcp_f32_e32 v59, v58
	v_add_f32_e32 v76, 1.0, v52
	v_mul_f32_e32 v75, 0.5, v53
	v_fma_f32 v52, -v58, v59, 1.0
	v_fmac_f32_e32 v59, v52, v59
	v_div_scale_f32 v52, vcc, 2.0, v54, 2.0
	v_mul_f32_e32 v53, v52, v59
	v_fma_f32 v77, -v58, v53, v52
	v_fmac_f32_e32 v53, v77, v59
	v_fma_f32 v52, -v58, v53, v52
	v_div_fmas_f32 v52, v52, v59, v53
	v_div_fixup_f32 v52, v52, v54, 2.0
	v_sub_f32_e32 v52, 1.0, v52
	v_add_f32_e32 v78, 1.0, v52
	v_fma_f32 v52, v56, v57, 0
	v_fmac_f32_e32 v52, v71, v72
	v_fmac_f32_e32 v52, v67, v74
	v_fmac_f32_e32 v52, v75, v76
	v_fmac_f32_e32 v52, v70, v62
	v_fmac_f32_e32 v52, v69, v73
	v_mul_f32_e32 v77, 0.5, v55
	v_fmac_f32_e32 v52, v63, v64
	v_fmac_f32_e32 v52, v77, v78
	s_nop 1
	v_add_f32_dpp v52, v52, v52 quad_perm:[1,0,3,2] row_mask:0xf bank_mask:0xf
	s_nop 1
	v_add_f32_dpp v52, v52, v52 quad_perm:[2,3,0,1] row_mask:0xf bank_mask:0xf
	s_nop 1
	v_add_f32_dpp v52, v52, v52 row_half_mirror row_mask:0xf bank_mask:0xf
	s_nop 1
	v_add_f32_dpp v52, v52, v52 row_mirror row_mask:0xf bank_mask:0xf
	s_nop 1
	v_add_f32_dpp v52, v52, v52 row_bcast:15 row_mask:0xa bank_mask:0xf
	s_nop 1
	v_add_f32_dpp v52, v52, v52 row_bcast:31 row_mask:0xc bank_mask:0xf
	s_nop 1
	v_readlane_b32 s98, v52, 63
	s_nop 1
	v_mov_b32_e32 v52, s98
	v_mul_f32_e32 v52, 0xbb000000, v52
	v_fma_f32 v58, v71, v72, v52
	v_fma_f32 v59, v56, v57, v52
	v_mul_f32_e32 v71, v58, v58
	v_fmac_f32_e32 v71, v59, v59
	v_fma_f32 v53, v67, v74, v52
	v_fmac_f32_e32 v71, v53, v53
	v_fma_f32 v54, v75, v76, v52
	v_fmac_f32_e32 v71, v54, v54
	v_fma_f32 v55, v70, v62, v52
	v_fmac_f32_e32 v71, v55, v55
	v_fma_f32 v56, v69, v73, v52
	v_fmac_f32_e32 v71, v56, v56
	v_fma_f32 v57, v63, v64, v52
	v_fmac_f32_e32 v71, v57, v57
	v_fmac_f32_e32 v52, v77, v78
	v_fmac_f32_e32 v71, v52, v52
	s_nop 1
	v_add_f32_dpp v62, v71, v71 quad_perm:[1,0,3,2] row_mask:0xf bank_mask:0xf
	s_nop 1
	v_add_f32_dpp v62, v62, v62 quad_perm:[2,3,0,1] row_mask:0xf bank_mask:0xf
	s_nop 1
	v_add_f32_dpp v62, v62, v62 row_half_mirror row_mask:0xf bank_mask:0xf
	s_nop 1
	v_add_f32_dpp v62, v62, v62 row_mirror row_mask:0xf bank_mask:0xf
	s_nop 1
	v_add_f32_dpp v62, v62, v62 row_bcast:15 row_mask:0xa bank_mask:0xf
	s_nop 1
	v_add_f32_dpp v62, v62, v62 row_bcast:31 row_mask:0xc bank_mask:0xf
	s_nop 1
	v_readlane_b32 s98, v62, 63
	s_nop 1
	v_mov_b32_e32 v62, s98
	v_mov_b32_e32 v63, 0
	s_and_saveexec_b64 s[0:1], s[38:39]
	s_cbranch_execz .LBB0_411
	s_waitcnt lgkmcnt(0)
	v_add_f32_e32 v62, v62, v63
	v_fmamk_f32 v62, v62, 0x3b000000, v189
	v_mul_f32_e32 v63, 0x4b800000, v62
	v_cmp_gt_f32_e32 vcc, s33, v62
	s_nop 1
	v_cndmask_b32_e32 v62, v62, v63, vcc
	v_rsq_f32_e32 v62, v62
	s_nop 0
	v_mul_f32_e32 v63, 0x45800000, v62
	v_cndmask_b32_e32 v62, v62, v63, vcc
	v_mul_f32_e32 v59, v59, v62
	v_mul_f32_e32 v58, v58, v62
	v_mul_f32_e32 v53, v53, v62
	v_cvt_pk_bf16_f32 v59, v59, v65
	ds_write_b16 v61, v59 offset:4
	v_cvt_pk_bf16_f32 v58, v58, v65
	ds_write_b16 v61, v58 offset:276
	v_cvt_pk_bf16_f32 v53, v53, v65
	ds_write_b16 v61, v53 offset:548
	v_mul_f32_e32 v53, v54, v62
	v_cvt_pk_bf16_f32 v53, v53, v65
	ds_write_b16 v61, v53 offset:820
	v_mul_f32_e32 v53, v55, v62
	v_cvt_pk_bf16_f32 v53, v53, v65
	ds_write_b16 v61, v53 offset:1092
	v_mul_f32_e32 v53, v56, v62
	v_cvt_pk_bf16_f32 v53, v53, v65
	ds_write_b16 v61, v53 offset:1364
	v_mul_f32_e32 v53, v57, v62
	v_mul_f32_e32 v52, v52, v62
	v_cvt_pk_bf16_f32 v53, v53, v65
	ds_write_b16 v61, v53 offset:1636
	v_cvt_pk_bf16_f32 v52, v52, v65
	ds_write_b16 v61, v52 offset:1908
.LBB0_411:
	s_or_b64 exec, exec, s[0:1]
	v_lshlrev_b32_e32 v52, 16, v48
	v_mul_f32_e32 v53, 0x3d372713, v52
	v_mul_f32_e32 v53, v53, v52
	v_fma_f32 v53, v53, v52, v52
	v_mul_f32_e32 v53, 0x3f4c422a, v53
	v_add_f32_e32 v53, v53, v53
	v_mul_f32_e32 v53, 0x3fb8aa3b, v53
	v_exp_f32_e32 v53, v53
	v_lshlrev_b32_e32 v55, 16, v50
	v_and_b32_e32 v48, 0xffff0000, v48
	v_and_b32_e32 v50, 0xffff0000, v50
	v_add_f32_e32 v53, 1.0, v53
	v_div_scale_f32 v56, s[0:1], v53, v53, 2.0
	v_rcp_f32_e32 v57, v56
	v_lshlrev_b32_e32 v54, 16, v49
	v_lshlrev_b32_e32 v58, 16, v51
	v_and_b32_e32 v49, 0xffff0000, v49
	v_fma_f32 v59, -v56, v57, 1.0
	v_fmac_f32_e32 v57, v59, v57
	v_div_scale_f32 v59, vcc, 2.0, v53, 2.0
	v_mul_f32_e32 v62, v59, v57
	s_waitcnt lgkmcnt(0)
	v_fma_f32 v63, -v56, v62, v59
	v_fmac_f32_e32 v62, v63, v57
	v_fma_f32 v56, -v56, v62, v59
	v_mul_f32_e32 v59, 0x3d372713, v55
	v_mul_f32_e32 v59, v59, v55
	v_fma_f32 v59, v59, v55, v55
	v_mul_f32_e32 v59, 0x3f4c422a, v59
	v_add_f32_e32 v59, v59, v59
	v_mul_f32_e32 v59, 0x3fb8aa3b, v59
	v_exp_f32_e32 v59, v59
	v_div_fmas_f32 v56, v56, v57, v62
	v_div_fixup_f32 v53, v56, v53, 2.0
	v_and_b32_e32 v51, 0xffff0000, v51
	v_add_f32_e32 v56, 1.0, v59
	v_div_scale_f32 v57, s[0:1], v56, v56, 2.0
	v_rcp_f32_e32 v59, v57
	v_sub_f32_e32 v53, 1.0, v53
	v_mul_f32_e32 v52, 0.5, v52
	v_add_f32_e32 v53, 1.0, v53
	v_fma_f32 v62, -v57, v59, 1.0
	v_fmac_f32_e32 v59, v62, v59
	v_div_scale_f32 v62, vcc, 2.0, v56, 2.0
	v_mul_f32_e32 v63, v62, v59
	v_fma_f32 v64, -v57, v63, v62
	v_fmac_f32_e32 v63, v64, v59
	v_fma_f32 v57, -v57, v63, v62
	v_mul_f32_e32 v62, 0x3d372713, v48
	v_mul_f32_e32 v62, v62, v48
	v_fma_f32 v62, v62, v48, v48
	v_mul_f32_e32 v62, 0x3f4c422a, v62
	v_add_f32_e32 v62, v62, v62
	v_mul_f32_e32 v62, 0x3fb8aa3b, v62
	v_exp_f32_e32 v62, v62
	v_div_fmas_f32 v57, v57, v59, v63
	v_div_fixup_f32 v56, v57, v56, 2.0
	v_mul_f32_e32 v63, 0.5, v55
	v_add_f32_e32 v57, 1.0, v62
	v_div_scale_f32 v59, s[0:1], v57, v57, 2.0
	v_rcp_f32_e32 v62, v59
	v_sub_f32_e32 v56, 1.0, v56
	v_add_f32_e32 v56, 1.0, v56
	v_fma_f32 v55, -v59, v62, 1.0
	v_fmac_f32_e32 v62, v55, v62
	v_div_scale_f32 v55, vcc, 2.0, v57, 2.0
	v_mul_f32_e32 v64, v55, v62
	v_fma_f32 v67, -v59, v64, v55
	v_fmac_f32_e32 v64, v67, v62
	v_fma_f32 v55, -v59, v64, v55
	v_mul_f32_e32 v59, 0x3d372713, v50
	v_mul_f32_e32 v59, v59, v50
	v_fma_f32 v59, v59, v50, v50
	v_mul_f32_e32 v59, 0x3f4c422a, v59
	v_add_f32_e32 v59, v59, v59
	v_mul_f32_e32 v59, 0x3fb8aa3b, v59
	v_exp_f32_e32 v59, v59
	v_div_fmas_f32 v55, v55, v62, v64
	v_div_fixup_f32 v55, v55, v57, 2.0
	v_mul_f32_e32 v64, 0.5, v48
	v_add_f32_e32 v57, 1.0, v59
	v_div_scale_f32 v59, s[0:1], v57, v57, 2.0
	v_rcp_f32_e32 v62, v59
	v_sub_f32_e32 v55, 1.0, v55
	v_add_f32_e32 v67, 1.0, v55
	v_fma_f32 v48, -v59, v62, 1.0
	v_fmac_f32_e32 v62, v48, v62
	v_div_scale_f32 v48, vcc, 2.0, v57, 2.0
	v_mul_f32_e32 v55, v48, v62
	v_fma_f32 v69, -v59, v55, v48
	v_fmac_f32_e32 v55, v69, v62
	v_fma_f32 v48, -v59, v55, v48
	v_mul_f32_e32 v59, 0x3d372713, v54
	v_mul_f32_e32 v59, v59, v54
	v_fma_f32 v59, v59, v54, v54
	v_mul_f32_e32 v59, 0x3f4c422a, v59
	v_add_f32_e32 v59, v59, v59
	v_mul_f32_e32 v59, 0x3fb8aa3b, v59
	v_exp_f32_e32 v59, v59
	v_div_fmas_f32 v48, v48, v62, v55
	v_div_fixup_f32 v48, v48, v57, 2.0
	v_sub_f32_e32 v48, 1.0, v48
	v_add_f32_e32 v55, 1.0, v59
	v_div_scale_f32 v57, s[0:1], v55, v55, 2.0
	v_rcp_f32_e32 v59, v57
	v_add_f32_e32 v69, 1.0, v48
	v_mul_f32_e32 v62, 0.5, v50
	v_fma_f32 v48, -v57, v59, 1.0
	v_fmac_f32_e32 v59, v48, v59
	v_div_scale_f32 v48, vcc, 2.0, v55, 2.0
	v_mul_f32_e32 v50, v48, v59
	v_fma_f32 v70, -v57, v50, v48
	v_fmac_f32_e32 v50, v70, v59
	v_fma_f32 v48, -v57, v50, v48
	v_mul_f32_e32 v57, 0x3d372713, v58
	v_mul_f32_e32 v57, v57, v58
	v_fma_f32 v57, v57, v58, v58
	v_mul_f32_e32 v57, 0x3f4c422a, v57
	v_add_f32_e32 v57, v57, v57
	v_mul_f32_e32 v57, 0x3fb8aa3b, v57
	v_exp_f32_e32 v57, v57
	v_div_fmas_f32 v48, v48, v59, v50
	v_div_fixup_f32 v48, v48, v55, 2.0
	v_sub_f32_e32 v48, 1.0, v48
	v_add_f32_e32 v50, 1.0, v57
	v_div_scale_f32 v55, s[0:1], v50, v50, 2.0
	v_rcp_f32_e32 v57, v55
	v_add_f32_e32 v70, 1.0, v48
	v_mul_f32_e32 v59, 0.5, v54
	v_fma_f32 v48, -v55, v57, 1.0
	v_fmac_f32_e32 v57, v48, v57
	v_div_scale_f32 v48, vcc, 2.0, v50, 2.0
	v_mul_f32_e32 v54, v48, v57
	v_fma_f32 v71, -v55, v54, v48
	v_fmac_f32_e32 v54, v71, v57
	v_fma_f32 v48, -v55, v54, v48
	v_mul_f32_e32 v55, 0x3d372713, v49
	v_mul_f32_e32 v55, v55, v49
	v_fma_f32 v55, v55, v49, v49
	v_mul_f32_e32 v55, 0x3f4c422a, v55
	v_add_f32_e32 v55, v55, v55
	v_mul_f32_e32 v55, 0x3fb8aa3b, v55
	v_exp_f32_e32 v55, v55
	v_div_fmas_f32 v48, v48, v57, v54
	v_div_fixup_f32 v48, v48, v50, 2.0
	v_sub_f32_e32 v48, 1.0, v48
	v_add_f32_e32 v50, 1.0, v55
	v_div_scale_f32 v54, s[0:1], v50, v50, 2.0
	v_rcp_f32_e32 v55, v54
	v_mul_f32_e32 v57, 0.5, v58
	v_add_f32_e32 v58, 1.0, v48
	v_fma_f32 v48, -v54, v55, 1.0
	v_fmac_f32_e32 v55, v48, v55
	v_div_scale_f32 v48, vcc, 2.0, v50, 2.0
	v_mul_f32_e32 v71, v48, v55
	v_fma_f32 v72, -v54, v71, v48
	v_fmac_f32_e32 v71, v72, v55
	v_fma_f32 v48, -v54, v71, v48
	v_mul_f32_e32 v54, 0x3d372713, v51
	v_mul_f32_e32 v54, v54, v51
	v_fma_f32 v54, v54, v51, v51
	v_mul_f32_e32 v54, 0x3f4c422a, v54
	v_add_f32_e32 v54, v54, v54
	v_mul_f32_e32 v54, 0x3fb8aa3b, v54
	v_exp_f32_e32 v54, v54
	v_div_fmas_f32 v48, v48, v55, v71
	v_div_fixup_f32 v48, v48, v50, 2.0
	v_sub_f32_e32 v48, 1.0, v48
	v_add_f32_e32 v50, 1.0, v54
	v_div_scale_f32 v54, s[0:1], v50, v50, 2.0
	v_rcp_f32_e32 v55, v54
	v_add_f32_e32 v72, 1.0, v48
	v_mul_f32_e32 v71, 0.5, v49
	v_fma_f32 v48, -v54, v55, 1.0
	v_fmac_f32_e32 v55, v48, v55
	v_div_scale_f32 v48, vcc, 2.0, v50, 2.0
	v_mul_f32_e32 v49, v48, v55
	v_fma_f32 v73, -v54, v49, v48
	v_fmac_f32_e32 v49, v73, v55
	v_fma_f32 v48, -v54, v49, v48
	v_div_fmas_f32 v48, v48, v55, v49
	v_div_fixup_f32 v48, v48, v50, 2.0
	v_sub_f32_e32 v48, 1.0, v48
	v_add_f32_e32 v74, 1.0, v48
	v_fma_f32 v48, v52, v53, 0
	v_fmac_f32_e32 v48, v64, v67
	v_fmac_f32_e32 v48, v59, v70
	v_fmac_f32_e32 v48, v71, v72
	v_fmac_f32_e32 v48, v63, v56
	v_fmac_f32_e32 v48, v62, v69
	v_mul_f32_e32 v73, 0.5, v51
	v_fmac_f32_e32 v48, v57, v58
	v_fmac_f32_e32 v48, v73, v74
	s_nop 1
	v_add_f32_dpp v48, v48, v48 quad_perm:[1,0,3,2] row_mask:0xf bank_mask:0xf
	s_nop 1
	v_add_f32_dpp v48, v48, v48 quad_perm:[2,3,0,1] row_mask:0xf bank_mask:0xf
	s_nop 1
	v_add_f32_dpp v48, v48, v48 row_half_mirror row_mask:0xf bank_mask:0xf
	s_nop 1
	v_add_f32_dpp v48, v48, v48 row_mirror row_mask:0xf bank_mask:0xf
	s_nop 1
	v_add_f32_dpp v48, v48, v48 row_bcast:15 row_mask:0xa bank_mask:0xf
	s_nop 1
	v_add_f32_dpp v48, v48, v48 row_bcast:31 row_mask:0xc bank_mask:0xf
	s_nop 1
	v_readlane_b32 s98, v48, 63
	s_nop 1
	v_mov_b32_e32 v48, s98
	v_mul_f32_e32 v48, 0xbb000000, v48
	v_fma_f32 v54, v64, v67, v48
	v_fma_f32 v55, v52, v53, v48
	v_mul_f32_e32 v64, v54, v54
	v_fmac_f32_e32 v64, v55, v55
	v_fma_f32 v49, v59, v70, v48
	v_fmac_f32_e32 v64, v49, v49
	v_fma_f32 v50, v71, v72, v48
	v_fmac_f32_e32 v64, v50, v50
	v_fma_f32 v51, v63, v56, v48
	v_fmac_f32_e32 v64, v51, v51
	v_fma_f32 v52, v62, v69, v48
	v_fmac_f32_e32 v64, v52, v52
	v_fma_f32 v53, v57, v58, v48
	v_fmac_f32_e32 v64, v53, v53
	v_fmac_f32_e32 v48, v73, v74
	v_fmac_f32_e32 v64, v48, v48
	s_nop 1
	v_add_f32_dpp v56, v64, v64 quad_perm:[1,0,3,2] row_mask:0xf bank_mask:0xf
	s_nop 1
	v_add_f32_dpp v56, v56, v56 quad_perm:[2,3,0,1] row_mask:0xf bank_mask:0xf
	s_nop 1
	v_add_f32_dpp v56, v56, v56 row_half_mirror row_mask:0xf bank_mask:0xf
	s_nop 1
	v_add_f32_dpp v56, v56, v56 row_mirror row_mask:0xf bank_mask:0xf
	s_nop 1
	v_add_f32_dpp v56, v56, v56 row_bcast:15 row_mask:0xa bank_mask:0xf
	s_nop 1
	v_add_f32_dpp v56, v56, v56 row_bcast:31 row_mask:0xc bank_mask:0xf
	s_nop 1
	v_readlane_b32 s98, v56, 63
	s_nop 1
	v_mov_b32_e32 v56, s98
	v_mov_b32_e32 v57, 0
	s_and_saveexec_b64 s[0:1], s[38:39]
	s_cbranch_execz .LBB0_413
	s_waitcnt lgkmcnt(0)
	v_add_f32_e32 v56, v56, v57
	v_fmamk_f32 v56, v56, 0x3b000000, v189
	v_mul_f32_e32 v57, 0x4b800000, v56
	v_cmp_gt_f32_e32 vcc, s33, v56
	s_nop 1
	v_cndmask_b32_e32 v56, v56, v57, vcc
	v_rsq_f32_e32 v56, v56
	s_nop 0
	v_mul_f32_e32 v57, 0x45800000, v56
	v_cndmask_b32_e32 v56, v56, v57, vcc
	v_mul_f32_e32 v55, v55, v56
	v_mul_f32_e32 v54, v54, v56
	v_mul_f32_e32 v49, v49, v56
	v_cvt_pk_bf16_f32 v55, v55, v65
	ds_write_b16 v61, v55 offset:6
	v_cvt_pk_bf16_f32 v54, v54, v65
	ds_write_b16 v61, v54 offset:278
	v_cvt_pk_bf16_f32 v49, v49, v65
	ds_write_b16 v61, v49 offset:550
	v_mul_f32_e32 v49, v50, v56
	v_cvt_pk_bf16_f32 v49, v49, v65
	ds_write_b16 v61, v49 offset:822
	v_mul_f32_e32 v49, v51, v56
	v_cvt_pk_bf16_f32 v49, v49, v65
	ds_write_b16 v61, v49 offset:1094
	v_mul_f32_e32 v49, v52, v56
	v_cvt_pk_bf16_f32 v49, v49, v65
	ds_write_b16 v61, v49 offset:1366
	v_mul_f32_e32 v49, v53, v56
	v_mul_f32_e32 v48, v48, v56
	v_cvt_pk_bf16_f32 v49, v49, v65
	ds_write_b16 v61, v49 offset:1638
	v_cvt_pk_bf16_f32 v48, v48, v65
	ds_write_b16 v61, v48 offset:1910
.LBB0_413:
	s_or_b64 exec, exec, s[0:1]
	v_lshlrev_b32_e32 v48, 16, v44
	v_mul_f32_e32 v49, 0x3d372713, v48
	v_mul_f32_e32 v49, v49, v48
	v_fma_f32 v49, v49, v48, v48
	v_mul_f32_e32 v49, 0x3f4c422a, v49
	v_add_f32_e32 v49, v49, v49
	v_mul_f32_e32 v49, 0x3fb8aa3b, v49
	v_exp_f32_e32 v49, v49
	v_lshlrev_b32_e32 v51, 16, v46
	v_and_b32_e32 v44, 0xffff0000, v44
	v_and_b32_e32 v46, 0xffff0000, v46
	v_add_f32_e32 v49, 1.0, v49
	v_div_scale_f32 v52, s[0:1], v49, v49, 2.0
	v_rcp_f32_e32 v53, v52
	v_lshlrev_b32_e32 v50, 16, v45
	v_lshlrev_b32_e32 v54, 16, v47
	v_and_b32_e32 v45, 0xffff0000, v45
	v_fma_f32 v55, -v52, v53, 1.0
	v_fmac_f32_e32 v53, v55, v53
	v_div_scale_f32 v55, vcc, 2.0, v49, 2.0
	v_mul_f32_e32 v56, v55, v53
	s_waitcnt lgkmcnt(0)
	v_fma_f32 v57, -v52, v56, v55
	v_fmac_f32_e32 v56, v57, v53
	v_fma_f32 v52, -v52, v56, v55
	v_mul_f32_e32 v55, 0x3d372713, v51
	v_mul_f32_e32 v55, v55, v51
	v_fma_f32 v55, v55, v51, v51
	v_mul_f32_e32 v55, 0x3f4c422a, v55
	v_add_f32_e32 v55, v55, v55
	v_mul_f32_e32 v55, 0x3fb8aa3b, v55
	v_exp_f32_e32 v55, v55
	v_div_fmas_f32 v52, v52, v53, v56
	v_div_fixup_f32 v49, v52, v49, 2.0
	v_and_b32_e32 v47, 0xffff0000, v47
	v_add_f32_e32 v52, 1.0, v55
	v_div_scale_f32 v53, s[0:1], v52, v52, 2.0
	v_rcp_f32_e32 v55, v53
	v_sub_f32_e32 v49, 1.0, v49
	v_mul_f32_e32 v48, 0.5, v48
	v_add_f32_e32 v49, 1.0, v49
	v_fma_f32 v56, -v53, v55, 1.0
	v_fmac_f32_e32 v55, v56, v55
	v_div_scale_f32 v56, vcc, 2.0, v52, 2.0
	v_mul_f32_e32 v57, v56, v55
	v_fma_f32 v58, -v53, v57, v56
	v_fmac_f32_e32 v57, v58, v55
	v_fma_f32 v53, -v53, v57, v56
	v_mul_f32_e32 v56, 0x3d372713, v44
	v_mul_f32_e32 v56, v56, v44
	v_fma_f32 v56, v56, v44, v44
	v_mul_f32_e32 v56, 0x3f4c422a, v56
	v_add_f32_e32 v56, v56, v56
	v_mul_f32_e32 v56, 0x3fb8aa3b, v56
	v_exp_f32_e32 v56, v56
	v_div_fmas_f32 v53, v53, v55, v57
	v_div_fixup_f32 v52, v53, v52, 2.0
	v_mul_f32_e32 v57, 0.5, v51
	v_add_f32_e32 v53, 1.0, v56
	v_div_scale_f32 v55, s[0:1], v53, v53, 2.0
	v_rcp_f32_e32 v56, v55
	v_sub_f32_e32 v52, 1.0, v52
	v_add_f32_e32 v52, 1.0, v52
	v_fma_f32 v51, -v55, v56, 1.0
	v_fmac_f32_e32 v56, v51, v56
	v_div_scale_f32 v51, vcc, 2.0, v53, 2.0
	v_mul_f32_e32 v58, v51, v56
	v_fma_f32 v59, -v55, v58, v51
	v_fmac_f32_e32 v58, v59, v56
	v_fma_f32 v51, -v55, v58, v51
	v_mul_f32_e32 v55, 0x3d372713, v46
	v_mul_f32_e32 v55, v55, v46
	v_fma_f32 v55, v55, v46, v46
	v_mul_f32_e32 v55, 0x3f4c422a, v55
	v_add_f32_e32 v55, v55, v55
	v_mul_f32_e32 v55, 0x3fb8aa3b, v55
	v_exp_f32_e32 v55, v55
	v_div_fmas_f32 v51, v51, v56, v58
	v_div_fixup_f32 v51, v51, v53, 2.0
	v_mul_f32_e32 v58, 0.5, v44
	v_add_f32_e32 v53, 1.0, v55
	v_div_scale_f32 v55, s[0:1], v53, v53, 2.0
	v_rcp_f32_e32 v56, v55
	v_sub_f32_e32 v51, 1.0, v51
	v_add_f32_e32 v59, 1.0, v51
	v_fma_f32 v44, -v55, v56, 1.0
	v_fmac_f32_e32 v56, v44, v56
	v_div_scale_f32 v44, vcc, 2.0, v53, 2.0
	v_mul_f32_e32 v51, v44, v56
	v_fma_f32 v62, -v55, v51, v44
	v_fmac_f32_e32 v51, v62, v56
	v_fma_f32 v44, -v55, v51, v44
	v_mul_f32_e32 v55, 0x3d372713, v50
	v_mul_f32_e32 v55, v55, v50
	v_fma_f32 v55, v55, v50, v50
	v_mul_f32_e32 v55, 0x3f4c422a, v55
	v_add_f32_e32 v55, v55, v55
	v_mul_f32_e32 v55, 0x3fb8aa3b, v55
	v_exp_f32_e32 v55, v55
	v_div_fmas_f32 v44, v44, v56, v51
	v_div_fixup_f32 v44, v44, v53, 2.0
	v_sub_f32_e32 v44, 1.0, v44
	v_add_f32_e32 v51, 1.0, v55
	v_div_scale_f32 v53, s[0:1], v51, v51, 2.0
	v_rcp_f32_e32 v55, v53
	v_add_f32_e32 v62, 1.0, v44
	v_mul_f32_e32 v56, 0.5, v46
	v_fma_f32 v44, -v53, v55, 1.0
	v_fmac_f32_e32 v55, v44, v55
	v_div_scale_f32 v44, vcc, 2.0, v51, 2.0
	v_mul_f32_e32 v46, v44, v55
	v_fma_f32 v63, -v53, v46, v44
	v_fmac_f32_e32 v46, v63, v55
	v_fma_f32 v44, -v53, v46, v44
	v_mul_f32_e32 v53, 0x3d372713, v54
	v_mul_f32_e32 v53, v53, v54
	v_fma_f32 v53, v53, v54, v54
	v_mul_f32_e32 v53, 0x3f4c422a, v53
	v_add_f32_e32 v53, v53, v53
	v_mul_f32_e32 v53, 0x3fb8aa3b, v53
	v_exp_f32_e32 v53, v53
	v_div_fmas_f32 v44, v44, v55, v46
	v_div_fixup_f32 v44, v44, v51, 2.0
	v_sub_f32_e32 v44, 1.0, v44
	v_add_f32_e32 v46, 1.0, v53
	v_div_scale_f32 v51, s[0:1], v46, v46, 2.0
	v_rcp_f32_e32 v53, v51
	v_add_f32_e32 v63, 1.0, v44
	v_mul_f32_e32 v55, 0.5, v50
	v_fma_f32 v44, -v51, v53, 1.0
	v_fmac_f32_e32 v53, v44, v53
	v_div_scale_f32 v44, vcc, 2.0, v46, 2.0
	v_mul_f32_e32 v50, v44, v53
	v_fma_f32 v64, -v51, v50, v44
	v_fmac_f32_e32 v50, v64, v53
	v_fma_f32 v44, -v51, v50, v44
	v_mul_f32_e32 v51, 0x3d372713, v45
	v_mul_f32_e32 v51, v51, v45
	v_fma_f32 v51, v51, v45, v45
	v_mul_f32_e32 v51, 0x3f4c422a, v51
	v_add_f32_e32 v51, v51, v51
	v_mul_f32_e32 v51, 0x3fb8aa3b, v51
	v_exp_f32_e32 v51, v51
	v_div_fmas_f32 v44, v44, v53, v50
	v_div_fixup_f32 v44, v44, v46, 2.0
	v_sub_f32_e32 v44, 1.0, v44
	v_add_f32_e32 v46, 1.0, v51
	v_div_scale_f32 v50, s[0:1], v46, v46, 2.0
	v_rcp_f32_e32 v51, v50
	v_mul_f32_e32 v53, 0.5, v54
	v_add_f32_e32 v54, 1.0, v44
	v_fma_f32 v44, -v50, v51, 1.0
	v_fmac_f32_e32 v51, v44, v51
	v_div_scale_f32 v44, vcc, 2.0, v46, 2.0
	v_mul_f32_e32 v64, v44, v51
	v_fma_f32 v67, -v50, v64, v44
	v_fmac_f32_e32 v64, v67, v51
	v_fma_f32 v44, -v50, v64, v44
	v_mul_f32_e32 v50, 0x3d372713, v47
	v_mul_f32_e32 v50, v50, v47
	v_fma_f32 v50, v50, v47, v47
	v_mul_f32_e32 v50, 0x3f4c422a, v50
	v_add_f32_e32 v50, v50, v50
	v_mul_f32_e32 v50, 0x3fb8aa3b, v50
	v_exp_f32_e32 v50, v50
	v_div_fmas_f32 v44, v44, v51, v64
	v_div_fixup_f32 v44, v44, v46, 2.0
	v_sub_f32_e32 v44, 1.0, v44
	v_add_f32_e32 v46, 1.0, v50
	v_div_scale_f32 v50, s[0:1], v46, v46, 2.0
	v_rcp_f32_e32 v51, v50
	v_add_f32_e32 v67, 1.0, v44
	v_mul_f32_e32 v64, 0.5, v45
	v_fma_f32 v44, -v50, v51, 1.0
	v_fmac_f32_e32 v51, v44, v51
	v_div_scale_f32 v44, vcc, 2.0, v46, 2.0
	v_mul_f32_e32 v45, v44, v51
	v_fma_f32 v69, -v50, v45, v44
	v_fmac_f32_e32 v45, v69, v51
	v_fma_f32 v44, -v50, v45, v44
	v_div_fmas_f32 v44, v44, v51, v45
	v_div_fixup_f32 v44, v44, v46, 2.0
	v_sub_f32_e32 v44, 1.0, v44
	v_add_f32_e32 v70, 1.0, v44
	v_fma_f32 v44, v48, v49, 0
	v_fmac_f32_e32 v44, v58, v59
	v_fmac_f32_e32 v44, v55, v63
	v_fmac_f32_e32 v44, v64, v67
	v_fmac_f32_e32 v44, v57, v52
	v_fmac_f32_e32 v44, v56, v62
	v_mul_f32_e32 v69, 0.5, v47
	v_fmac_f32_e32 v44, v53, v54
	v_fmac_f32_e32 v44, v69, v70
	s_nop 1
	v_add_f32_dpp v44, v44, v44 quad_perm:[1,0,3,2] row_mask:0xf bank_mask:0xf
	s_nop 1
	v_add_f32_dpp v44, v44, v44 quad_perm:[2,3,0,1] row_mask:0xf bank_mask:0xf
	s_nop 1
	v_add_f32_dpp v44, v44, v44 row_half_mirror row_mask:0xf bank_mask:0xf
	s_nop 1
	v_add_f32_dpp v44, v44, v44 row_mirror row_mask:0xf bank_mask:0xf
	s_nop 1
	v_add_f32_dpp v44, v44, v44 row_bcast:15 row_mask:0xa bank_mask:0xf
	s_nop 1
	v_add_f32_dpp v44, v44, v44 row_bcast:31 row_mask:0xc bank_mask:0xf
	s_nop 1
	v_readlane_b32 s98, v44, 63
	s_nop 1
	v_mov_b32_e32 v44, s98
	v_mul_f32_e32 v44, 0xbb000000, v44
	v_fma_f32 v50, v58, v59, v44
	v_fma_f32 v51, v48, v49, v44
	v_mul_f32_e32 v58, v50, v50
	v_fmac_f32_e32 v58, v51, v51
	v_fma_f32 v45, v55, v63, v44
	v_fmac_f32_e32 v58, v45, v45
	v_fma_f32 v46, v64, v67, v44
	v_fmac_f32_e32 v58, v46, v46
	v_fma_f32 v47, v57, v52, v44
	v_fmac_f32_e32 v58, v47, v47
	v_fma_f32 v48, v56, v62, v44
	v_fmac_f32_e32 v58, v48, v48
	v_fma_f32 v49, v53, v54, v44
	v_fmac_f32_e32 v58, v49, v49
	v_fmac_f32_e32 v44, v69, v70
	v_fmac_f32_e32 v58, v44, v44
	s_nop 1
	v_add_f32_dpp v52, v58, v58 quad_perm:[1,0,3,2] row_mask:0xf bank_mask:0xf
	s_nop 1
	v_add_f32_dpp v52, v52, v52 quad_perm:[2,3,0,1] row_mask:0xf bank_mask:0xf
	s_nop 1
	v_add_f32_dpp v52, v52, v52 row_half_mirror row_mask:0xf bank_mask:0xf
	s_nop 1
	v_add_f32_dpp v52, v52, v52 row_mirror row_mask:0xf bank_mask:0xf
	s_nop 1
	v_add_f32_dpp v52, v52, v52 row_bcast:15 row_mask:0xa bank_mask:0xf
	s_nop 1
	v_add_f32_dpp v52, v52, v52 row_bcast:31 row_mask:0xc bank_mask:0xf
	s_nop 1
	v_readlane_b32 s98, v52, 63
	s_nop 1
	v_mov_b32_e32 v52, s98
	v_mov_b32_e32 v53, 0
	s_and_saveexec_b64 s[0:1], s[38:39]
	s_cbranch_execz .LBB0_415
	s_waitcnt lgkmcnt(0)
	v_add_f32_e32 v52, v52, v53
	v_fmamk_f32 v52, v52, 0x3b000000, v189
	v_mul_f32_e32 v53, 0x4b800000, v52
	v_cmp_gt_f32_e32 vcc, s33, v52
	s_nop 1
	v_cndmask_b32_e32 v52, v52, v53, vcc
	v_rsq_f32_e32 v52, v52
	s_nop 0
	v_mul_f32_e32 v53, 0x45800000, v52
	v_cndmask_b32_e32 v52, v52, v53, vcc
	v_mul_f32_e32 v51, v51, v52
	v_mul_f32_e32 v50, v50, v52
	v_mul_f32_e32 v45, v45, v52
	v_cvt_pk_bf16_f32 v51, v51, v65
	ds_write_b16 v61, v51 offset:8
	v_cvt_pk_bf16_f32 v50, v50, v65
	ds_write_b16 v61, v50 offset:280
	v_cvt_pk_bf16_f32 v45, v45, v65
	ds_write_b16 v61, v45 offset:552
	v_mul_f32_e32 v45, v46, v52
	v_cvt_pk_bf16_f32 v45, v45, v65
	ds_write_b16 v61, v45 offset:824
	v_mul_f32_e32 v45, v47, v52
	v_cvt_pk_bf16_f32 v45, v45, v65
	ds_write_b16 v61, v45 offset:1096
	v_mul_f32_e32 v45, v48, v52
	v_cvt_pk_bf16_f32 v45, v45, v65
	ds_write_b16 v61, v45 offset:1368
	v_mul_f32_e32 v45, v49, v52
	v_mul_f32_e32 v44, v44, v52
	v_cvt_pk_bf16_f32 v45, v45, v65
	ds_write_b16 v61, v45 offset:1640
	v_cvt_pk_bf16_f32 v44, v44, v65
	ds_write_b16 v61, v44 offset:1912
.LBB0_415:
	s_or_b64 exec, exec, s[0:1]
	v_lshlrev_b32_e32 v44, 16, v40
	v_mul_f32_e32 v45, 0x3d372713, v44
	v_mul_f32_e32 v45, v45, v44
	v_fma_f32 v45, v45, v44, v44
	v_mul_f32_e32 v45, 0x3f4c422a, v45
	v_add_f32_e32 v45, v45, v45
	v_mul_f32_e32 v45, 0x3fb8aa3b, v45
	v_exp_f32_e32 v45, v45
	v_lshlrev_b32_e32 v47, 16, v42
	v_and_b32_e32 v40, 0xffff0000, v40
	v_and_b32_e32 v42, 0xffff0000, v42
	v_add_f32_e32 v45, 1.0, v45
	v_div_scale_f32 v48, s[0:1], v45, v45, 2.0
	v_rcp_f32_e32 v49, v48
	v_lshlrev_b32_e32 v46, 16, v41
	v_lshlrev_b32_e32 v50, 16, v43
	v_and_b32_e32 v41, 0xffff0000, v41
	v_fma_f32 v51, -v48, v49, 1.0
	v_fmac_f32_e32 v49, v51, v49
	v_div_scale_f32 v51, vcc, 2.0, v45, 2.0
	v_mul_f32_e32 v52, v51, v49
	s_waitcnt lgkmcnt(0)
	v_fma_f32 v53, -v48, v52, v51
	v_fmac_f32_e32 v52, v53, v49
	v_fma_f32 v48, -v48, v52, v51
	v_mul_f32_e32 v51, 0x3d372713, v47
	v_mul_f32_e32 v51, v51, v47
	v_fma_f32 v51, v51, v47, v47
	v_mul_f32_e32 v51, 0x3f4c422a, v51
	v_add_f32_e32 v51, v51, v51
	v_mul_f32_e32 v51, 0x3fb8aa3b, v51
	v_exp_f32_e32 v51, v51
	v_div_fmas_f32 v48, v48, v49, v52
	v_div_fixup_f32 v45, v48, v45, 2.0
	v_and_b32_e32 v43, 0xffff0000, v43
	v_add_f32_e32 v48, 1.0, v51
	v_div_scale_f32 v49, s[0:1], v48, v48, 2.0
	v_rcp_f32_e32 v51, v49
	v_sub_f32_e32 v45, 1.0, v45
	v_mul_f32_e32 v44, 0.5, v44
	v_add_f32_e32 v45, 1.0, v45
	v_fma_f32 v52, -v49, v51, 1.0
	v_fmac_f32_e32 v51, v52, v51
	v_div_scale_f32 v52, vcc, 2.0, v48, 2.0
	v_mul_f32_e32 v53, v52, v51
	v_fma_f32 v54, -v49, v53, v52
	v_fmac_f32_e32 v53, v54, v51
	v_fma_f32 v49, -v49, v53, v52
	v_mul_f32_e32 v52, 0x3d372713, v40
	v_mul_f32_e32 v52, v52, v40
	v_fma_f32 v52, v52, v40, v40
	v_mul_f32_e32 v52, 0x3f4c422a, v52
	v_add_f32_e32 v52, v52, v52
	v_mul_f32_e32 v52, 0x3fb8aa3b, v52
	v_exp_f32_e32 v52, v52
	v_div_fmas_f32 v49, v49, v51, v53
	v_div_fixup_f32 v48, v49, v48, 2.0
	v_mul_f32_e32 v53, 0.5, v47
	v_add_f32_e32 v49, 1.0, v52
	v_div_scale_f32 v51, s[0:1], v49, v49, 2.0
	v_rcp_f32_e32 v52, v51
	v_sub_f32_e32 v48, 1.0, v48
	v_add_f32_e32 v48, 1.0, v48
	v_fma_f32 v47, -v51, v52, 1.0
	v_fmac_f32_e32 v52, v47, v52
	v_div_scale_f32 v47, vcc, 2.0, v49, 2.0
	v_mul_f32_e32 v54, v47, v52
	v_fma_f32 v55, -v51, v54, v47
	v_fmac_f32_e32 v54, v55, v52
	v_fma_f32 v47, -v51, v54, v47
	v_mul_f32_e32 v51, 0x3d372713, v42
	v_mul_f32_e32 v51, v51, v42
	v_fma_f32 v51, v51, v42, v42
	v_mul_f32_e32 v51, 0x3f4c422a, v51
	v_add_f32_e32 v51, v51, v51
	v_mul_f32_e32 v51, 0x3fb8aa3b, v51
	v_exp_f32_e32 v51, v51
	v_div_fmas_f32 v47, v47, v52, v54
	v_div_fixup_f32 v47, v47, v49, 2.0
	v_mul_f32_e32 v54, 0.5, v40
	v_add_f32_e32 v49, 1.0, v51
	v_div_scale_f32 v51, s[0:1], v49, v49, 2.0
	v_rcp_f32_e32 v52, v51
	v_sub_f32_e32 v47, 1.0, v47
	v_add_f32_e32 v55, 1.0, v47
	v_fma_f32 v40, -v51, v52, 1.0
	v_fmac_f32_e32 v52, v40, v52
	v_div_scale_f32 v40, vcc, 2.0, v49, 2.0
	v_mul_f32_e32 v47, v40, v52
	v_fma_f32 v56, -v51, v47, v40
	v_fmac_f32_e32 v47, v56, v52
	v_fma_f32 v40, -v51, v47, v40
	v_mul_f32_e32 v51, 0x3d372713, v46
	v_mul_f32_e32 v51, v51, v46
	v_fma_f32 v51, v51, v46, v46
	v_mul_f32_e32 v51, 0x3f4c422a, v51
	v_add_f32_e32 v51, v51, v51
	v_mul_f32_e32 v51, 0x3fb8aa3b, v51
	v_exp_f32_e32 v51, v51
	v_div_fmas_f32 v40, v40, v52, v47
	v_div_fixup_f32 v40, v40, v49, 2.0
	v_sub_f32_e32 v40, 1.0, v40
	v_add_f32_e32 v47, 1.0, v51
	v_div_scale_f32 v49, s[0:1], v47, v47, 2.0
	v_rcp_f32_e32 v51, v49
	v_add_f32_e32 v56, 1.0, v40
	v_mul_f32_e32 v52, 0.5, v42
	v_fma_f32 v40, -v49, v51, 1.0
	v_fmac_f32_e32 v51, v40, v51
	v_div_scale_f32 v40, vcc, 2.0, v47, 2.0
	v_mul_f32_e32 v42, v40, v51
	v_fma_f32 v57, -v49, v42, v40
	v_fmac_f32_e32 v42, v57, v51
	v_fma_f32 v40, -v49, v42, v40
	v_mul_f32_e32 v49, 0x3d372713, v50
	v_mul_f32_e32 v49, v49, v50
	v_fma_f32 v49, v49, v50, v50
	v_mul_f32_e32 v49, 0x3f4c422a, v49
	v_add_f32_e32 v49, v49, v49
	v_mul_f32_e32 v49, 0x3fb8aa3b, v49
	v_exp_f32_e32 v49, v49
	v_div_fmas_f32 v40, v40, v51, v42
	v_div_fixup_f32 v40, v40, v47, 2.0
	v_sub_f32_e32 v40, 1.0, v40
	v_add_f32_e32 v42, 1.0, v49
	v_div_scale_f32 v47, s[0:1], v42, v42, 2.0
	v_rcp_f32_e32 v49, v47
	v_add_f32_e32 v57, 1.0, v40
	v_mul_f32_e32 v51, 0.5, v46
	v_fma_f32 v40, -v47, v49, 1.0
	v_fmac_f32_e32 v49, v40, v49
	v_div_scale_f32 v40, vcc, 2.0, v42, 2.0
	v_mul_f32_e32 v46, v40, v49
	v_fma_f32 v58, -v47, v46, v40
	v_fmac_f32_e32 v46, v58, v49
	v_fma_f32 v40, -v47, v46, v40
	v_mul_f32_e32 v47, 0x3d372713, v41
	v_mul_f32_e32 v47, v47, v41
	v_fma_f32 v47, v47, v41, v41
	v_mul_f32_e32 v47, 0x3f4c422a, v47
	v_add_f32_e32 v47, v47, v47
	v_mul_f32_e32 v47, 0x3fb8aa3b, v47
	v_exp_f32_e32 v47, v47
	v_div_fmas_f32 v40, v40, v49, v46
	v_div_fixup_f32 v40, v40, v42, 2.0
	v_sub_f32_e32 v40, 1.0, v40
	v_add_f32_e32 v42, 1.0, v47
	v_div_scale_f32 v46, s[0:1], v42, v42, 2.0
	v_rcp_f32_e32 v47, v46
	v_mul_f32_e32 v49, 0.5, v50
	v_add_f32_e32 v50, 1.0, v40
	v_fma_f32 v40, -v46, v47, 1.0
	v_fmac_f32_e32 v47, v40, v47
	v_div_scale_f32 v40, vcc, 2.0, v42, 2.0
	v_mul_f32_e32 v58, v40, v47
	v_fma_f32 v59, -v46, v58, v40
	v_fmac_f32_e32 v58, v59, v47
	v_fma_f32 v40, -v46, v58, v40
	v_mul_f32_e32 v46, 0x3d372713, v43
	v_mul_f32_e32 v46, v46, v43
	v_fma_f32 v46, v46, v43, v43
	v_mul_f32_e32 v46, 0x3f4c422a, v46
	v_add_f32_e32 v46, v46, v46
	v_mul_f32_e32 v46, 0x3fb8aa3b, v46
	v_exp_f32_e32 v46, v46
	v_div_fmas_f32 v40, v40, v47, v58
	v_div_fixup_f32 v40, v40, v42, 2.0
	v_sub_f32_e32 v40, 1.0, v40
	v_add_f32_e32 v42, 1.0, v46
	v_div_scale_f32 v46, s[0:1], v42, v42, 2.0
	v_rcp_f32_e32 v47, v46
	v_add_f32_e32 v59, 1.0, v40
	v_mul_f32_e32 v58, 0.5, v41
	v_fma_f32 v40, -v46, v47, 1.0
	v_fmac_f32_e32 v47, v40, v47
	v_div_scale_f32 v40, vcc, 2.0, v42, 2.0
	v_mul_f32_e32 v41, v40, v47
	v_fma_f32 v62, -v46, v41, v40
	v_fmac_f32_e32 v41, v62, v47
	v_fma_f32 v40, -v46, v41, v40
	v_div_fmas_f32 v40, v40, v47, v41
	v_div_fixup_f32 v40, v40, v42, 2.0
	v_sub_f32_e32 v40, 1.0, v40
	v_add_f32_e32 v63, 1.0, v40
	v_fma_f32 v40, v44, v45, 0
	v_fmac_f32_e32 v40, v54, v55
	v_fmac_f32_e32 v40, v51, v57
	v_fmac_f32_e32 v40, v58, v59
	v_fmac_f32_e32 v40, v53, v48
	v_fmac_f32_e32 v40, v52, v56
	v_mul_f32_e32 v62, 0.5, v43
	v_fmac_f32_e32 v40, v49, v50
	v_fmac_f32_e32 v40, v62, v63
	s_nop 1
	v_add_f32_dpp v40, v40, v40 quad_perm:[1,0,3,2] row_mask:0xf bank_mask:0xf
	s_nop 1
	v_add_f32_dpp v40, v40, v40 quad_perm:[2,3,0,1] row_mask:0xf bank_mask:0xf
	s_nop 1
	v_add_f32_dpp v40, v40, v40 row_half_mirror row_mask:0xf bank_mask:0xf
	s_nop 1
	v_add_f32_dpp v40, v40, v40 row_mirror row_mask:0xf bank_mask:0xf
	s_nop 1
	v_add_f32_dpp v40, v40, v40 row_bcast:15 row_mask:0xa bank_mask:0xf
	s_nop 1
	v_add_f32_dpp v40, v40, v40 row_bcast:31 row_mask:0xc bank_mask:0xf
	s_nop 1
	v_readlane_b32 s98, v40, 63
	s_nop 1
	v_mov_b32_e32 v40, s98
	v_mul_f32_e32 v40, 0xbb000000, v40
	v_fma_f32 v46, v54, v55, v40
	v_fma_f32 v47, v44, v45, v40
	v_mul_f32_e32 v54, v46, v46
	v_fmac_f32_e32 v54, v47, v47
	v_fma_f32 v41, v51, v57, v40
	v_fmac_f32_e32 v54, v41, v41
	v_fma_f32 v42, v58, v59, v40
	v_fmac_f32_e32 v54, v42, v42
	v_fma_f32 v43, v53, v48, v40
	v_fmac_f32_e32 v54, v43, v43
	v_fma_f32 v44, v52, v56, v40
	v_fmac_f32_e32 v54, v44, v44
	v_fma_f32 v45, v49, v50, v40
	v_fmac_f32_e32 v54, v45, v45
	v_fmac_f32_e32 v40, v62, v63
	v_fmac_f32_e32 v54, v40, v40
	s_nop 1
	v_add_f32_dpp v48, v54, v54 quad_perm:[1,0,3,2] row_mask:0xf bank_mask:0xf
	s_nop 1
	v_add_f32_dpp v48, v48, v48 quad_perm:[2,3,0,1] row_mask:0xf bank_mask:0xf
	s_nop 1
	v_add_f32_dpp v48, v48, v48 row_half_mirror row_mask:0xf bank_mask:0xf
	s_nop 1
	v_add_f32_dpp v48, v48, v48 row_mirror row_mask:0xf bank_mask:0xf
	s_nop 1
	v_add_f32_dpp v48, v48, v48 row_bcast:15 row_mask:0xa bank_mask:0xf
	s_nop 1
	v_add_f32_dpp v48, v48, v48 row_bcast:31 row_mask:0xc bank_mask:0xf
	s_nop 1
	v_readlane_b32 s98, v48, 63
	s_nop 1
	v_mov_b32_e32 v48, s98
	v_mov_b32_e32 v49, 0
	s_and_saveexec_b64 s[0:1], s[38:39]
	s_cbranch_execz .LBB0_417
	s_waitcnt lgkmcnt(0)
	v_add_f32_e32 v48, v48, v49
	v_fmamk_f32 v48, v48, 0x3b000000, v189
	v_mul_f32_e32 v49, 0x4b800000, v48
	v_cmp_gt_f32_e32 vcc, s33, v48
	s_nop 1
	v_cndmask_b32_e32 v48, v48, v49, vcc
	v_rsq_f32_e32 v48, v48
	s_nop 0
	v_mul_f32_e32 v49, 0x45800000, v48
	v_cndmask_b32_e32 v48, v48, v49, vcc
	v_mul_f32_e32 v47, v47, v48
	v_mul_f32_e32 v46, v46, v48
	v_mul_f32_e32 v41, v41, v48
	v_cvt_pk_bf16_f32 v47, v47, v65
	ds_write_b16 v61, v47 offset:10
	v_cvt_pk_bf16_f32 v46, v46, v65
	ds_write_b16 v61, v46 offset:282
	v_cvt_pk_bf16_f32 v41, v41, v65
	ds_write_b16 v61, v41 offset:554
	v_mul_f32_e32 v41, v42, v48
	v_cvt_pk_bf16_f32 v41, v41, v65
	ds_write_b16 v61, v41 offset:826
	v_mul_f32_e32 v41, v43, v48
	v_cvt_pk_bf16_f32 v41, v41, v65
	ds_write_b16 v61, v41 offset:1098
	v_mul_f32_e32 v41, v44, v48
	v_cvt_pk_bf16_f32 v41, v41, v65
	ds_write_b16 v61, v41 offset:1370
	v_mul_f32_e32 v41, v45, v48
	v_mul_f32_e32 v40, v40, v48
	v_cvt_pk_bf16_f32 v41, v41, v65
	ds_write_b16 v61, v41 offset:1642
	v_cvt_pk_bf16_f32 v40, v40, v65
	ds_write_b16 v61, v40 offset:1914
.LBB0_417:
	s_or_b64 exec, exec, s[0:1]
	v_lshlrev_b32_e32 v40, 16, v36
	v_mul_f32_e32 v41, 0x3d372713, v40
	v_mul_f32_e32 v41, v41, v40
	v_fma_f32 v41, v41, v40, v40
	v_mul_f32_e32 v41, 0x3f4c422a, v41
	v_add_f32_e32 v41, v41, v41
	v_mul_f32_e32 v41, 0x3fb8aa3b, v41
	v_exp_f32_e32 v41, v41
	v_lshlrev_b32_e32 v43, 16, v38
	v_and_b32_e32 v36, 0xffff0000, v36
	v_and_b32_e32 v38, 0xffff0000, v38
	v_add_f32_e32 v41, 1.0, v41
	v_div_scale_f32 v44, s[0:1], v41, v41, 2.0
	v_rcp_f32_e32 v45, v44
	v_lshlrev_b32_e32 v42, 16, v37
	v_lshlrev_b32_e32 v46, 16, v39
	v_and_b32_e32 v37, 0xffff0000, v37
	v_fma_f32 v47, -v44, v45, 1.0
	v_fmac_f32_e32 v45, v47, v45
	v_div_scale_f32 v47, vcc, 2.0, v41, 2.0
	v_mul_f32_e32 v48, v47, v45
	s_waitcnt lgkmcnt(0)
	v_fma_f32 v49, -v44, v48, v47
	v_fmac_f32_e32 v48, v49, v45
	v_fma_f32 v44, -v44, v48, v47
	v_mul_f32_e32 v47, 0x3d372713, v43
	v_mul_f32_e32 v47, v47, v43
	v_fma_f32 v47, v47, v43, v43
	v_mul_f32_e32 v47, 0x3f4c422a, v47
	v_add_f32_e32 v47, v47, v47
	v_mul_f32_e32 v47, 0x3fb8aa3b, v47
	v_exp_f32_e32 v47, v47
	v_div_fmas_f32 v44, v44, v45, v48
	v_div_fixup_f32 v41, v44, v41, 2.0
	v_and_b32_e32 v39, 0xffff0000, v39
	v_add_f32_e32 v44, 1.0, v47
	v_div_scale_f32 v45, s[0:1], v44, v44, 2.0
	v_rcp_f32_e32 v47, v45
	v_sub_f32_e32 v41, 1.0, v41
	v_mul_f32_e32 v40, 0.5, v40
	v_add_f32_e32 v41, 1.0, v41
	v_fma_f32 v48, -v45, v47, 1.0
	v_fmac_f32_e32 v47, v48, v47
	v_div_scale_f32 v48, vcc, 2.0, v44, 2.0
	v_mul_f32_e32 v49, v48, v47
	v_fma_f32 v50, -v45, v49, v48
	v_fmac_f32_e32 v49, v50, v47
	v_fma_f32 v45, -v45, v49, v48
	v_mul_f32_e32 v48, 0x3d372713, v36
	v_mul_f32_e32 v48, v48, v36
	v_fma_f32 v48, v48, v36, v36
	v_mul_f32_e32 v48, 0x3f4c422a, v48
	v_add_f32_e32 v48, v48, v48
	v_mul_f32_e32 v48, 0x3fb8aa3b, v48
	v_exp_f32_e32 v48, v48
	v_div_fmas_f32 v45, v45, v47, v49
	v_div_fixup_f32 v44, v45, v44, 2.0
	v_mul_f32_e32 v49, 0.5, v43
	v_add_f32_e32 v45, 1.0, v48
	v_div_scale_f32 v47, s[0:1], v45, v45, 2.0
	v_rcp_f32_e32 v48, v47
	v_sub_f32_e32 v44, 1.0, v44
	v_add_f32_e32 v44, 1.0, v44
	v_fma_f32 v43, -v47, v48, 1.0
	v_fmac_f32_e32 v48, v43, v48
	v_div_scale_f32 v43, vcc, 2.0, v45, 2.0
	v_mul_f32_e32 v50, v43, v48
	v_fma_f32 v51, -v47, v50, v43
	v_fmac_f32_e32 v50, v51, v48
	v_fma_f32 v43, -v47, v50, v43
	v_mul_f32_e32 v47, 0x3d372713, v38
	v_mul_f32_e32 v47, v47, v38
	v_fma_f32 v47, v47, v38, v38
	v_mul_f32_e32 v47, 0x3f4c422a, v47
	v_add_f32_e32 v47, v47, v47
	v_mul_f32_e32 v47, 0x3fb8aa3b, v47
	v_exp_f32_e32 v47, v47
	v_div_fmas_f32 v43, v43, v48, v50
	v_div_fixup_f32 v43, v43, v45, 2.0
	v_mul_f32_e32 v50, 0.5, v36
	v_add_f32_e32 v45, 1.0, v47
	v_div_scale_f32 v47, s[0:1], v45, v45, 2.0
	v_rcp_f32_e32 v48, v47
	v_sub_f32_e32 v43, 1.0, v43
	v_add_f32_e32 v51, 1.0, v43
	v_fma_f32 v36, -v47, v48, 1.0
	v_fmac_f32_e32 v48, v36, v48
	v_div_scale_f32 v36, vcc, 2.0, v45, 2.0
	v_mul_f32_e32 v43, v36, v48
	v_fma_f32 v52, -v47, v43, v36
	v_fmac_f32_e32 v43, v52, v48
	v_fma_f32 v36, -v47, v43, v36
	v_mul_f32_e32 v47, 0x3d372713, v42
	v_mul_f32_e32 v47, v47, v42
	v_fma_f32 v47, v47, v42, v42
	v_mul_f32_e32 v47, 0x3f4c422a, v47
	v_add_f32_e32 v47, v47, v47
	v_mul_f32_e32 v47, 0x3fb8aa3b, v47
	v_exp_f32_e32 v47, v47
	v_div_fmas_f32 v36, v36, v48, v43
	v_div_fixup_f32 v36, v36, v45, 2.0
	v_sub_f32_e32 v36, 1.0, v36
	v_add_f32_e32 v43, 1.0, v47
	v_div_scale_f32 v45, s[0:1], v43, v43, 2.0
	v_rcp_f32_e32 v47, v45
	v_add_f32_e32 v52, 1.0, v36
	v_mul_f32_e32 v48, 0.5, v38
	v_fma_f32 v36, -v45, v47, 1.0
	v_fmac_f32_e32 v47, v36, v47
	v_div_scale_f32 v36, vcc, 2.0, v43, 2.0
	v_mul_f32_e32 v38, v36, v47
	v_fma_f32 v53, -v45, v38, v36
	v_fmac_f32_e32 v38, v53, v47
	v_fma_f32 v36, -v45, v38, v36
	v_mul_f32_e32 v45, 0x3d372713, v46
	v_mul_f32_e32 v45, v45, v46
	v_fma_f32 v45, v45, v46, v46
	v_mul_f32_e32 v45, 0x3f4c422a, v45
	v_add_f32_e32 v45, v45, v45
	v_mul_f32_e32 v45, 0x3fb8aa3b, v45
	v_exp_f32_e32 v45, v45
	v_div_fmas_f32 v36, v36, v47, v38
	v_div_fixup_f32 v36, v36, v43, 2.0
	v_sub_f32_e32 v36, 1.0, v36
	v_add_f32_e32 v38, 1.0, v45
	v_div_scale_f32 v43, s[0:1], v38, v38, 2.0
	v_rcp_f32_e32 v45, v43
	v_add_f32_e32 v53, 1.0, v36
	v_mul_f32_e32 v47, 0.5, v42
	v_fma_f32 v36, -v43, v45, 1.0
	v_fmac_f32_e32 v45, v36, v45
	v_div_scale_f32 v36, vcc, 2.0, v38, 2.0
	v_mul_f32_e32 v42, v36, v45
	v_fma_f32 v54, -v43, v42, v36
	v_fmac_f32_e32 v42, v54, v45
	v_fma_f32 v36, -v43, v42, v36
	v_mul_f32_e32 v43, 0x3d372713, v37
	v_mul_f32_e32 v43, v43, v37
	v_fma_f32 v43, v43, v37, v37
	v_mul_f32_e32 v43, 0x3f4c422a, v43
	v_add_f32_e32 v43, v43, v43
	v_mul_f32_e32 v43, 0x3fb8aa3b, v43
	v_exp_f32_e32 v43, v43
	v_div_fmas_f32 v36, v36, v45, v42
	v_div_fixup_f32 v36, v36, v38, 2.0
	v_sub_f32_e32 v36, 1.0, v36
	v_add_f32_e32 v38, 1.0, v43
	v_div_scale_f32 v42, s[0:1], v38, v38, 2.0
	v_rcp_f32_e32 v43, v42
	v_mul_f32_e32 v45, 0.5, v46
	v_add_f32_e32 v46, 1.0, v36
	v_fma_f32 v36, -v42, v43, 1.0
	v_fmac_f32_e32 v43, v36, v43
	v_div_scale_f32 v36, vcc, 2.0, v38, 2.0
	v_mul_f32_e32 v54, v36, v43
	v_fma_f32 v55, -v42, v54, v36
	v_fmac_f32_e32 v54, v55, v43
	v_fma_f32 v36, -v42, v54, v36
	v_mul_f32_e32 v42, 0x3d372713, v39
	v_mul_f32_e32 v42, v42, v39
	v_fma_f32 v42, v42, v39, v39
	v_mul_f32_e32 v42, 0x3f4c422a, v42
	v_add_f32_e32 v42, v42, v42
	v_mul_f32_e32 v42, 0x3fb8aa3b, v42
	v_exp_f32_e32 v42, v42
	v_div_fmas_f32 v36, v36, v43, v54
	v_div_fixup_f32 v36, v36, v38, 2.0
	v_sub_f32_e32 v36, 1.0, v36
	v_add_f32_e32 v38, 1.0, v42
	v_div_scale_f32 v42, s[0:1], v38, v38, 2.0
	v_rcp_f32_e32 v43, v42
	v_add_f32_e32 v55, 1.0, v36
	v_mul_f32_e32 v54, 0.5, v37
	v_fma_f32 v36, -v42, v43, 1.0
	v_fmac_f32_e32 v43, v36, v43
	v_div_scale_f32 v36, vcc, 2.0, v38, 2.0
	v_mul_f32_e32 v37, v36, v43
	v_fma_f32 v56, -v42, v37, v36
	v_fmac_f32_e32 v37, v56, v43
	v_fma_f32 v36, -v42, v37, v36
	v_div_fmas_f32 v36, v36, v43, v37
	v_div_fixup_f32 v36, v36, v38, 2.0
	v_sub_f32_e32 v36, 1.0, v36
	v_add_f32_e32 v57, 1.0, v36
	v_fma_f32 v36, v40, v41, 0
	v_fmac_f32_e32 v36, v50, v51
	v_fmac_f32_e32 v36, v47, v53
	v_fmac_f32_e32 v36, v54, v55
	v_fmac_f32_e32 v36, v49, v44
	v_fmac_f32_e32 v36, v48, v52
	v_mul_f32_e32 v56, 0.5, v39
	v_fmac_f32_e32 v36, v45, v46
	v_fmac_f32_e32 v36, v56, v57
	s_nop 1
	v_add_f32_dpp v36, v36, v36 quad_perm:[1,0,3,2] row_mask:0xf bank_mask:0xf
	s_nop 1
	v_add_f32_dpp v36, v36, v36 quad_perm:[2,3,0,1] row_mask:0xf bank_mask:0xf
	s_nop 1
	v_add_f32_dpp v36, v36, v36 row_half_mirror row_mask:0xf bank_mask:0xf
	s_nop 1
	v_add_f32_dpp v36, v36, v36 row_mirror row_mask:0xf bank_mask:0xf
	s_nop 1
	v_add_f32_dpp v36, v36, v36 row_bcast:15 row_mask:0xa bank_mask:0xf
	s_nop 1
	v_add_f32_dpp v36, v36, v36 row_bcast:31 row_mask:0xc bank_mask:0xf
	s_nop 1
	v_readlane_b32 s98, v36, 63
	s_nop 1
	v_mov_b32_e32 v36, s98
	v_mul_f32_e32 v36, 0xbb000000, v36
	v_fma_f32 v42, v50, v51, v36
	v_fma_f32 v43, v40, v41, v36
	v_mul_f32_e32 v50, v42, v42
	v_fmac_f32_e32 v50, v43, v43
	v_fma_f32 v37, v47, v53, v36
	v_fmac_f32_e32 v50, v37, v37
	v_fma_f32 v38, v54, v55, v36
	v_fmac_f32_e32 v50, v38, v38
	v_fma_f32 v39, v49, v44, v36
	v_fmac_f32_e32 v50, v39, v39
	v_fma_f32 v40, v48, v52, v36
	v_fmac_f32_e32 v50, v40, v40
	v_fma_f32 v41, v45, v46, v36
	v_fmac_f32_e32 v50, v41, v41
	v_fmac_f32_e32 v36, v56, v57
	v_fmac_f32_e32 v50, v36, v36
	s_nop 1
	v_add_f32_dpp v44, v50, v50 quad_perm:[1,0,3,2] row_mask:0xf bank_mask:0xf
	s_nop 1
	v_add_f32_dpp v44, v44, v44 quad_perm:[2,3,0,1] row_mask:0xf bank_mask:0xf
	s_nop 1
	v_add_f32_dpp v44, v44, v44 row_half_mirror row_mask:0xf bank_mask:0xf
	s_nop 1
	v_add_f32_dpp v44, v44, v44 row_mirror row_mask:0xf bank_mask:0xf
	s_nop 1
	v_add_f32_dpp v44, v44, v44 row_bcast:15 row_mask:0xa bank_mask:0xf
	s_nop 1
	v_add_f32_dpp v44, v44, v44 row_bcast:31 row_mask:0xc bank_mask:0xf
	s_nop 1
	v_readlane_b32 s98, v44, 63
	s_nop 1
	v_mov_b32_e32 v44, s98
	v_mov_b32_e32 v45, 0
	s_and_saveexec_b64 s[0:1], s[38:39]
	s_cbranch_execz .LBB0_419
	s_waitcnt lgkmcnt(0)
	v_add_f32_e32 v44, v44, v45
	v_fmamk_f32 v44, v44, 0x3b000000, v189
	v_mul_f32_e32 v45, 0x4b800000, v44
	v_cmp_gt_f32_e32 vcc, s33, v44
	s_nop 1
	v_cndmask_b32_e32 v44, v44, v45, vcc
	v_rsq_f32_e32 v44, v44
	s_nop 0
	v_mul_f32_e32 v45, 0x45800000, v44
	v_cndmask_b32_e32 v44, v44, v45, vcc
	v_mul_f32_e32 v43, v43, v44
	v_mul_f32_e32 v42, v42, v44
	v_mul_f32_e32 v37, v37, v44
	v_cvt_pk_bf16_f32 v43, v43, v65
	ds_write_b16 v61, v43 offset:12
	v_cvt_pk_bf16_f32 v42, v42, v65
	ds_write_b16 v61, v42 offset:284
	v_cvt_pk_bf16_f32 v37, v37, v65
	ds_write_b16 v61, v37 offset:556
	v_mul_f32_e32 v37, v38, v44
	v_cvt_pk_bf16_f32 v37, v37, v65
	ds_write_b16 v61, v37 offset:828
	v_mul_f32_e32 v37, v39, v44
	v_cvt_pk_bf16_f32 v37, v37, v65
	ds_write_b16 v61, v37 offset:1100
	v_mul_f32_e32 v37, v40, v44
	v_cvt_pk_bf16_f32 v37, v37, v65
	ds_write_b16 v61, v37 offset:1372
	v_mul_f32_e32 v37, v41, v44
	v_mul_f32_e32 v36, v36, v44
	v_cvt_pk_bf16_f32 v37, v37, v65
	ds_write_b16 v61, v37 offset:1644
	v_cvt_pk_bf16_f32 v36, v36, v65
	ds_write_b16 v61, v36 offset:1916
.LBB0_419:
	s_or_b64 exec, exec, s[0:1]
	v_lshlrev_b32_e32 v36, 16, v32
	v_mul_f32_e32 v37, 0x3d372713, v36
	v_mul_f32_e32 v37, v37, v36
	v_fma_f32 v37, v37, v36, v36
	v_mul_f32_e32 v37, 0x3f4c422a, v37
	v_add_f32_e32 v37, v37, v37
	v_mul_f32_e32 v37, 0x3fb8aa3b, v37
	v_exp_f32_e32 v37, v37
	v_lshlrev_b32_e32 v39, 16, v34
	v_and_b32_e32 v32, 0xffff0000, v32
	v_and_b32_e32 v34, 0xffff0000, v34
	v_add_f32_e32 v37, 1.0, v37
	v_div_scale_f32 v40, s[0:1], v37, v37, 2.0
	v_rcp_f32_e32 v41, v40
	v_lshlrev_b32_e32 v38, 16, v33
	v_lshlrev_b32_e32 v42, 16, v35
	v_and_b32_e32 v33, 0xffff0000, v33
	v_fma_f32 v43, -v40, v41, 1.0
	v_fmac_f32_e32 v41, v43, v41
	v_div_scale_f32 v43, vcc, 2.0, v37, 2.0
	v_mul_f32_e32 v44, v43, v41
	s_waitcnt lgkmcnt(0)
	v_fma_f32 v45, -v40, v44, v43
	v_fmac_f32_e32 v44, v45, v41
	v_fma_f32 v40, -v40, v44, v43
	v_mul_f32_e32 v43, 0x3d372713, v39
	v_mul_f32_e32 v43, v43, v39
	v_fma_f32 v43, v43, v39, v39
	v_mul_f32_e32 v43, 0x3f4c422a, v43
	v_add_f32_e32 v43, v43, v43
	v_mul_f32_e32 v43, 0x3fb8aa3b, v43
	v_exp_f32_e32 v43, v43
	v_div_fmas_f32 v40, v40, v41, v44
	v_div_fixup_f32 v37, v40, v37, 2.0
	v_and_b32_e32 v35, 0xffff0000, v35
	v_add_f32_e32 v40, 1.0, v43
	v_div_scale_f32 v41, s[0:1], v40, v40, 2.0
	v_rcp_f32_e32 v43, v41
	v_sub_f32_e32 v37, 1.0, v37
	v_mul_f32_e32 v36, 0.5, v36
	v_add_f32_e32 v37, 1.0, v37
	v_fma_f32 v44, -v41, v43, 1.0
	v_fmac_f32_e32 v43, v44, v43
	v_div_scale_f32 v44, vcc, 2.0, v40, 2.0
	v_mul_f32_e32 v45, v44, v43
	v_fma_f32 v46, -v41, v45, v44
	v_fmac_f32_e32 v45, v46, v43
	v_fma_f32 v41, -v41, v45, v44
	v_mul_f32_e32 v44, 0x3d372713, v32
	v_mul_f32_e32 v44, v44, v32
	v_fma_f32 v44, v44, v32, v32
	v_mul_f32_e32 v44, 0x3f4c422a, v44
	v_add_f32_e32 v44, v44, v44
	v_mul_f32_e32 v44, 0x3fb8aa3b, v44
	v_exp_f32_e32 v44, v44
	v_div_fmas_f32 v41, v41, v43, v45
	v_div_fixup_f32 v40, v41, v40, 2.0
	v_mul_f32_e32 v45, 0.5, v39
	v_add_f32_e32 v41, 1.0, v44
	v_div_scale_f32 v43, s[0:1], v41, v41, 2.0
	v_rcp_f32_e32 v44, v43
	v_sub_f32_e32 v40, 1.0, v40
	v_add_f32_e32 v40, 1.0, v40
	v_fma_f32 v39, -v43, v44, 1.0
	v_fmac_f32_e32 v44, v39, v44
	v_div_scale_f32 v39, vcc, 2.0, v41, 2.0
	v_mul_f32_e32 v46, v39, v44
	v_fma_f32 v47, -v43, v46, v39
	v_fmac_f32_e32 v46, v47, v44
	v_fma_f32 v39, -v43, v46, v39
	v_mul_f32_e32 v43, 0x3d372713, v34
	v_mul_f32_e32 v43, v43, v34
	v_fma_f32 v43, v43, v34, v34
	v_mul_f32_e32 v43, 0x3f4c422a, v43
	v_add_f32_e32 v43, v43, v43
	v_mul_f32_e32 v43, 0x3fb8aa3b, v43
	v_exp_f32_e32 v43, v43
	v_div_fmas_f32 v39, v39, v44, v46
	v_div_fixup_f32 v39, v39, v41, 2.0
	v_mul_f32_e32 v46, 0.5, v32
	v_add_f32_e32 v41, 1.0, v43
	v_div_scale_f32 v43, s[0:1], v41, v41, 2.0
	v_rcp_f32_e32 v44, v43
	v_sub_f32_e32 v39, 1.0, v39
	v_add_f32_e32 v47, 1.0, v39
	v_fma_f32 v32, -v43, v44, 1.0
	v_fmac_f32_e32 v44, v32, v44
	v_div_scale_f32 v32, vcc, 2.0, v41, 2.0
	v_mul_f32_e32 v39, v32, v44
	v_fma_f32 v48, -v43, v39, v32
	v_fmac_f32_e32 v39, v48, v44
	v_fma_f32 v32, -v43, v39, v32
	v_mul_f32_e32 v43, 0x3d372713, v38
	v_mul_f32_e32 v43, v43, v38
	v_fma_f32 v43, v43, v38, v38
	v_mul_f32_e32 v43, 0x3f4c422a, v43
	v_add_f32_e32 v43, v43, v43
	v_mul_f32_e32 v43, 0x3fb8aa3b, v43
	v_exp_f32_e32 v43, v43
	v_div_fmas_f32 v32, v32, v44, v39
	v_div_fixup_f32 v32, v32, v41, 2.0
	v_sub_f32_e32 v32, 1.0, v32
	v_add_f32_e32 v39, 1.0, v43
	v_div_scale_f32 v41, s[0:1], v39, v39, 2.0
	v_rcp_f32_e32 v43, v41
	v_add_f32_e32 v48, 1.0, v32
	v_mul_f32_e32 v44, 0.5, v34
	v_fma_f32 v32, -v41, v43, 1.0
	v_fmac_f32_e32 v43, v32, v43
	v_div_scale_f32 v32, vcc, 2.0, v39, 2.0
	v_mul_f32_e32 v34, v32, v43
	v_fma_f32 v49, -v41, v34, v32
	v_fmac_f32_e32 v34, v49, v43
	v_fma_f32 v32, -v41, v34, v32
	v_mul_f32_e32 v41, 0x3d372713, v42
	v_mul_f32_e32 v41, v41, v42
	v_fma_f32 v41, v41, v42, v42
	v_mul_f32_e32 v41, 0x3f4c422a, v41
	v_add_f32_e32 v41, v41, v41
	v_mul_f32_e32 v41, 0x3fb8aa3b, v41
	v_exp_f32_e32 v41, v41
	v_div_fmas_f32 v32, v32, v43, v34
	v_div_fixup_f32 v32, v32, v39, 2.0
	v_sub_f32_e32 v32, 1.0, v32
	v_add_f32_e32 v34, 1.0, v41
	v_div_scale_f32 v39, s[0:1], v34, v34, 2.0
	v_rcp_f32_e32 v41, v39
	v_add_f32_e32 v49, 1.0, v32
	v_mul_f32_e32 v43, 0.5, v38
	v_fma_f32 v32, -v39, v41, 1.0
	v_fmac_f32_e32 v41, v32, v41
	v_div_scale_f32 v32, vcc, 2.0, v34, 2.0
	v_mul_f32_e32 v38, v32, v41
	v_fma_f32 v50, -v39, v38, v32
	v_fmac_f32_e32 v38, v50, v41
	v_fma_f32 v32, -v39, v38, v32
	v_mul_f32_e32 v39, 0x3d372713, v33
	v_mul_f32_e32 v39, v39, v33
	v_fma_f32 v39, v39, v33, v33
	v_mul_f32_e32 v39, 0x3f4c422a, v39
	v_add_f32_e32 v39, v39, v39
	v_mul_f32_e32 v39, 0x3fb8aa3b, v39
	v_exp_f32_e32 v39, v39
	v_div_fmas_f32 v32, v32, v41, v38
	v_div_fixup_f32 v32, v32, v34, 2.0
	v_sub_f32_e32 v32, 1.0, v32
	v_add_f32_e32 v34, 1.0, v39
	v_div_scale_f32 v38, s[0:1], v34, v34, 2.0
	v_rcp_f32_e32 v39, v38
	v_mul_f32_e32 v41, 0.5, v42
	v_add_f32_e32 v42, 1.0, v32
	v_fma_f32 v32, -v38, v39, 1.0
	v_fmac_f32_e32 v39, v32, v39
	v_div_scale_f32 v32, vcc, 2.0, v34, 2.0
	v_mul_f32_e32 v50, v32, v39
	v_fma_f32 v51, -v38, v50, v32
	v_fmac_f32_e32 v50, v51, v39
	v_fma_f32 v32, -v38, v50, v32
	v_mul_f32_e32 v38, 0x3d372713, v35
	v_mul_f32_e32 v38, v38, v35
	v_fma_f32 v38, v38, v35, v35
	v_mul_f32_e32 v38, 0x3f4c422a, v38
	v_add_f32_e32 v38, v38, v38
	v_mul_f32_e32 v38, 0x3fb8aa3b, v38
	v_exp_f32_e32 v38, v38
	v_div_fmas_f32 v32, v32, v39, v50
	v_div_fixup_f32 v32, v32, v34, 2.0
	v_sub_f32_e32 v32, 1.0, v32
	v_add_f32_e32 v34, 1.0, v38
	v_div_scale_f32 v38, s[0:1], v34, v34, 2.0
	v_rcp_f32_e32 v39, v38
	v_add_f32_e32 v51, 1.0, v32
	v_mul_f32_e32 v50, 0.5, v33
	v_fma_f32 v32, -v38, v39, 1.0
	v_fmac_f32_e32 v39, v32, v39
	v_div_scale_f32 v32, vcc, 2.0, v34, 2.0
	v_mul_f32_e32 v33, v32, v39
	v_fma_f32 v52, -v38, v33, v32
	v_fmac_f32_e32 v33, v52, v39
	v_fma_f32 v32, -v38, v33, v32
	v_div_fmas_f32 v32, v32, v39, v33
	v_div_fixup_f32 v32, v32, v34, 2.0
	v_sub_f32_e32 v32, 1.0, v32
	v_add_f32_e32 v53, 1.0, v32
	v_fma_f32 v32, v36, v37, 0
	v_fmac_f32_e32 v32, v46, v47
	v_fmac_f32_e32 v32, v43, v49
	v_fmac_f32_e32 v32, v50, v51
	v_fmac_f32_e32 v32, v45, v40
	v_fmac_f32_e32 v32, v44, v48
	v_mul_f32_e32 v52, 0.5, v35
	v_fmac_f32_e32 v32, v41, v42
	v_fmac_f32_e32 v32, v52, v53
	s_nop 1
	v_add_f32_dpp v32, v32, v32 quad_perm:[1,0,3,2] row_mask:0xf bank_mask:0xf
	s_nop 1
	v_add_f32_dpp v32, v32, v32 quad_perm:[2,3,0,1] row_mask:0xf bank_mask:0xf
	s_nop 1
	v_add_f32_dpp v32, v32, v32 row_half_mirror row_mask:0xf bank_mask:0xf
	s_nop 1
	v_add_f32_dpp v32, v32, v32 row_mirror row_mask:0xf bank_mask:0xf
	s_nop 1
	v_add_f32_dpp v32, v32, v32 row_bcast:15 row_mask:0xa bank_mask:0xf
	s_nop 1
	v_add_f32_dpp v32, v32, v32 row_bcast:31 row_mask:0xc bank_mask:0xf
	s_nop 1
	v_readlane_b32 s98, v32, 63
	s_nop 1
	v_mov_b32_e32 v32, s98
	v_mul_f32_e32 v32, 0xbb000000, v32
	v_fma_f32 v38, v46, v47, v32
	v_fma_f32 v39, v36, v37, v32
	v_mul_f32_e32 v46, v38, v38
	v_fmac_f32_e32 v46, v39, v39
	v_fma_f32 v33, v43, v49, v32
	v_fmac_f32_e32 v46, v33, v33
	v_fma_f32 v34, v50, v51, v32
	v_fmac_f32_e32 v46, v34, v34
	v_fma_f32 v35, v45, v40, v32
	v_fmac_f32_e32 v46, v35, v35
	v_fma_f32 v36, v44, v48, v32
	v_fmac_f32_e32 v46, v36, v36
	v_fma_f32 v37, v41, v42, v32
	v_fmac_f32_e32 v46, v37, v37
	v_fmac_f32_e32 v32, v52, v53
	v_fmac_f32_e32 v46, v32, v32
	s_nop 1
	v_add_f32_dpp v40, v46, v46 quad_perm:[1,0,3,2] row_mask:0xf bank_mask:0xf
	s_nop 1
	v_add_f32_dpp v40, v40, v40 quad_perm:[2,3,0,1] row_mask:0xf bank_mask:0xf
	s_nop 1
	v_add_f32_dpp v40, v40, v40 row_half_mirror row_mask:0xf bank_mask:0xf
	s_nop 1
	v_add_f32_dpp v40, v40, v40 row_mirror row_mask:0xf bank_mask:0xf
	s_nop 1
	v_add_f32_dpp v40, v40, v40 row_bcast:15 row_mask:0xa bank_mask:0xf
	s_nop 1
	v_add_f32_dpp v40, v40, v40 row_bcast:31 row_mask:0xc bank_mask:0xf
	s_nop 1
	v_readlane_b32 s98, v40, 63
	s_nop 1
	v_mov_b32_e32 v40, s98
	v_mov_b32_e32 v41, 0
	s_and_saveexec_b64 s[0:1], s[38:39]
	s_cbranch_execz .LBB0_421
	s_waitcnt lgkmcnt(0)
	v_add_f32_e32 v40, v40, v41
	v_fmamk_f32 v40, v40, 0x3b000000, v189
	v_mul_f32_e32 v41, 0x4b800000, v40
	v_cmp_gt_f32_e32 vcc, s33, v40
	s_nop 1
	v_cndmask_b32_e32 v40, v40, v41, vcc
	v_rsq_f32_e32 v40, v40
	s_nop 0
	v_mul_f32_e32 v41, 0x45800000, v40
	v_cndmask_b32_e32 v40, v40, v41, vcc
	v_mul_f32_e32 v39, v39, v40
	v_mul_f32_e32 v38, v38, v40
	v_mul_f32_e32 v33, v33, v40
	v_cvt_pk_bf16_f32 v39, v39, v65
	ds_write_b16 v61, v39 offset:14
	v_cvt_pk_bf16_f32 v38, v38, v65
	ds_write_b16 v61, v38 offset:286
	v_cvt_pk_bf16_f32 v33, v33, v65
	ds_write_b16 v61, v33 offset:558
	v_mul_f32_e32 v33, v34, v40
	v_cvt_pk_bf16_f32 v33, v33, v65
	ds_write_b16 v61, v33 offset:830
	v_mul_f32_e32 v33, v35, v40
	v_cvt_pk_bf16_f32 v33, v33, v65
	ds_write_b16 v61, v33 offset:1102
	v_mul_f32_e32 v33, v36, v40
	v_cvt_pk_bf16_f32 v33, v33, v65
	ds_write_b16 v61, v33 offset:1374
	v_mul_f32_e32 v33, v37, v40
	v_mul_f32_e32 v32, v32, v40
	v_cvt_pk_bf16_f32 v33, v33, v65
	ds_write_b16 v61, v33 offset:1646
	v_cvt_pk_bf16_f32 v32, v32, v65
	ds_write_b16 v61, v32 offset:1918
.LBB0_421:
	s_or_b64 exec, exec, s[0:1]
	v_lshlrev_b32_e32 v32, 16, v28
	v_mul_f32_e32 v33, 0x3d372713, v32
	v_mul_f32_e32 v33, v33, v32
	v_fma_f32 v33, v33, v32, v32
	v_mul_f32_e32 v33, 0x3f4c422a, v33
	v_add_f32_e32 v33, v33, v33
	v_mul_f32_e32 v33, 0x3fb8aa3b, v33
	v_exp_f32_e32 v33, v33
	v_lshlrev_b32_e32 v35, 16, v30
	v_and_b32_e32 v28, 0xffff0000, v28
	v_and_b32_e32 v30, 0xffff0000, v30
	v_add_f32_e32 v33, 1.0, v33
	v_div_scale_f32 v36, s[0:1], v33, v33, 2.0
	v_rcp_f32_e32 v37, v36
	v_lshlrev_b32_e32 v34, 16, v29
	v_lshlrev_b32_e32 v38, 16, v31
	v_and_b32_e32 v29, 0xffff0000, v29
	v_fma_f32 v39, -v36, v37, 1.0
	v_fmac_f32_e32 v37, v39, v37
	v_div_scale_f32 v39, vcc, 2.0, v33, 2.0
	v_mul_f32_e32 v40, v39, v37
	s_waitcnt lgkmcnt(0)
	v_fma_f32 v41, -v36, v40, v39
	v_fmac_f32_e32 v40, v41, v37
	v_fma_f32 v36, -v36, v40, v39
	v_mul_f32_e32 v39, 0x3d372713, v35
	v_mul_f32_e32 v39, v39, v35
	v_fma_f32 v39, v39, v35, v35
	v_mul_f32_e32 v39, 0x3f4c422a, v39
	v_add_f32_e32 v39, v39, v39
	v_mul_f32_e32 v39, 0x3fb8aa3b, v39
	v_exp_f32_e32 v39, v39
	v_div_fmas_f32 v36, v36, v37, v40
	v_div_fixup_f32 v33, v36, v33, 2.0
	v_and_b32_e32 v31, 0xffff0000, v31
	v_add_f32_e32 v36, 1.0, v39
	v_div_scale_f32 v37, s[0:1], v36, v36, 2.0
	v_rcp_f32_e32 v39, v37
	v_sub_f32_e32 v33, 1.0, v33
	v_mul_f32_e32 v32, 0.5, v32
	v_add_f32_e32 v33, 1.0, v33
	v_fma_f32 v40, -v37, v39, 1.0
	v_fmac_f32_e32 v39, v40, v39
	v_div_scale_f32 v40, vcc, 2.0, v36, 2.0
	v_mul_f32_e32 v41, v40, v39
	v_fma_f32 v42, -v37, v41, v40
	v_fmac_f32_e32 v41, v42, v39
	v_fma_f32 v37, -v37, v41, v40
	v_mul_f32_e32 v40, 0x3d372713, v28
	v_mul_f32_e32 v40, v40, v28
	v_fma_f32 v40, v40, v28, v28
	v_mul_f32_e32 v40, 0x3f4c422a, v40
	v_add_f32_e32 v40, v40, v40
	v_mul_f32_e32 v40, 0x3fb8aa3b, v40
	v_exp_f32_e32 v40, v40
	v_div_fmas_f32 v37, v37, v39, v41
	v_div_fixup_f32 v36, v37, v36, 2.0
	v_mul_f32_e32 v41, 0.5, v35
	v_add_f32_e32 v37, 1.0, v40
	v_div_scale_f32 v39, s[0:1], v37, v37, 2.0
	v_rcp_f32_e32 v40, v39
	v_sub_f32_e32 v36, 1.0, v36
	v_add_f32_e32 v36, 1.0, v36
	v_fma_f32 v35, -v39, v40, 1.0
	v_fmac_f32_e32 v40, v35, v40
	v_div_scale_f32 v35, vcc, 2.0, v37, 2.0
	v_mul_f32_e32 v42, v35, v40
	v_fma_f32 v43, -v39, v42, v35
	v_fmac_f32_e32 v42, v43, v40
	v_fma_f32 v35, -v39, v42, v35
	v_mul_f32_e32 v39, 0x3d372713, v30
	v_mul_f32_e32 v39, v39, v30
	v_fma_f32 v39, v39, v30, v30
	v_mul_f32_e32 v39, 0x3f4c422a, v39
	v_add_f32_e32 v39, v39, v39
	v_mul_f32_e32 v39, 0x3fb8aa3b, v39
	v_exp_f32_e32 v39, v39
	v_div_fmas_f32 v35, v35, v40, v42
	v_div_fixup_f32 v35, v35, v37, 2.0
	v_mul_f32_e32 v42, 0.5, v28
	v_add_f32_e32 v37, 1.0, v39
	v_div_scale_f32 v39, s[0:1], v37, v37, 2.0
	v_rcp_f32_e32 v40, v39
	v_sub_f32_e32 v35, 1.0, v35
	v_add_f32_e32 v43, 1.0, v35
	v_fma_f32 v28, -v39, v40, 1.0
	v_fmac_f32_e32 v40, v28, v40
	v_div_scale_f32 v28, vcc, 2.0, v37, 2.0
	v_mul_f32_e32 v35, v28, v40
	v_fma_f32 v44, -v39, v35, v28
	v_fmac_f32_e32 v35, v44, v40
	v_fma_f32 v28, -v39, v35, v28
	v_mul_f32_e32 v39, 0x3d372713, v34
	v_mul_f32_e32 v39, v39, v34
	v_fma_f32 v39, v39, v34, v34
	v_mul_f32_e32 v39, 0x3f4c422a, v39
	v_add_f32_e32 v39, v39, v39
	v_mul_f32_e32 v39, 0x3fb8aa3b, v39
	v_exp_f32_e32 v39, v39
	v_div_fmas_f32 v28, v28, v40, v35
	v_div_fixup_f32 v28, v28, v37, 2.0
	v_sub_f32_e32 v28, 1.0, v28
	v_add_f32_e32 v35, 1.0, v39
	v_div_scale_f32 v37, s[0:1], v35, v35, 2.0
	v_rcp_f32_e32 v39, v37
	v_add_f32_e32 v44, 1.0, v28
	v_mul_f32_e32 v40, 0.5, v30
	v_fma_f32 v28, -v37, v39, 1.0
	v_fmac_f32_e32 v39, v28, v39
	v_div_scale_f32 v28, vcc, 2.0, v35, 2.0
	v_mul_f32_e32 v30, v28, v39
	v_fma_f32 v45, -v37, v30, v28
	v_fmac_f32_e32 v30, v45, v39
	v_fma_f32 v28, -v37, v30, v28
	v_mul_f32_e32 v37, 0x3d372713, v38
	v_mul_f32_e32 v37, v37, v38
	v_fma_f32 v37, v37, v38, v38
	v_mul_f32_e32 v37, 0x3f4c422a, v37
	v_add_f32_e32 v37, v37, v37
	v_mul_f32_e32 v37, 0x3fb8aa3b, v37
	v_exp_f32_e32 v37, v37
	v_div_fmas_f32 v28, v28, v39, v30
	v_div_fixup_f32 v28, v28, v35, 2.0
	v_sub_f32_e32 v28, 1.0, v28
	v_add_f32_e32 v30, 1.0, v37
	v_div_scale_f32 v35, s[0:1], v30, v30, 2.0
	v_rcp_f32_e32 v37, v35
	v_add_f32_e32 v45, 1.0, v28
	v_mul_f32_e32 v39, 0.5, v34
	v_fma_f32 v28, -v35, v37, 1.0
	v_fmac_f32_e32 v37, v28, v37
	v_div_scale_f32 v28, vcc, 2.0, v30, 2.0
	v_mul_f32_e32 v34, v28, v37
	v_fma_f32 v46, -v35, v34, v28
	v_fmac_f32_e32 v34, v46, v37
	v_fma_f32 v28, -v35, v34, v28
	v_mul_f32_e32 v35, 0x3d372713, v29
	v_mul_f32_e32 v35, v35, v29
	v_fma_f32 v35, v35, v29, v29
	v_mul_f32_e32 v35, 0x3f4c422a, v35
	v_add_f32_e32 v35, v35, v35
	v_mul_f32_e32 v35, 0x3fb8aa3b, v35
	v_exp_f32_e32 v35, v35
	v_div_fmas_f32 v28, v28, v37, v34
	v_div_fixup_f32 v28, v28, v30, 2.0
	v_sub_f32_e32 v28, 1.0, v28
	v_add_f32_e32 v30, 1.0, v35
	v_div_scale_f32 v34, s[0:1], v30, v30, 2.0
	v_rcp_f32_e32 v35, v34
	v_mul_f32_e32 v37, 0.5, v38
	v_add_f32_e32 v38, 1.0, v28
	v_fma_f32 v28, -v34, v35, 1.0
	v_fmac_f32_e32 v35, v28, v35
	v_div_scale_f32 v28, vcc, 2.0, v30, 2.0
	v_mul_f32_e32 v46, v28, v35
	v_fma_f32 v47, -v34, v46, v28
	v_fmac_f32_e32 v46, v47, v35
	v_fma_f32 v28, -v34, v46, v28
	v_mul_f32_e32 v34, 0x3d372713, v31
	v_mul_f32_e32 v34, v34, v31
	v_fma_f32 v34, v34, v31, v31
	v_mul_f32_e32 v34, 0x3f4c422a, v34
	v_add_f32_e32 v34, v34, v34
	v_mul_f32_e32 v34, 0x3fb8aa3b, v34
	v_exp_f32_e32 v34, v34
	v_div_fmas_f32 v28, v28, v35, v46
	v_div_fixup_f32 v28, v28, v30, 2.0
	v_sub_f32_e32 v28, 1.0, v28
	v_add_f32_e32 v30, 1.0, v34
	v_div_scale_f32 v34, s[0:1], v30, v30, 2.0
	v_rcp_f32_e32 v35, v34
	v_add_f32_e32 v47, 1.0, v28
	v_mul_f32_e32 v46, 0.5, v29
	v_fma_f32 v28, -v34, v35, 1.0
	v_fmac_f32_e32 v35, v28, v35
	v_div_scale_f32 v28, vcc, 2.0, v30, 2.0
	v_mul_f32_e32 v29, v28, v35
	v_fma_f32 v48, -v34, v29, v28
	v_fmac_f32_e32 v29, v48, v35
	v_fma_f32 v28, -v34, v29, v28
	v_div_fmas_f32 v28, v28, v35, v29
	v_div_fixup_f32 v28, v28, v30, 2.0
	v_sub_f32_e32 v28, 1.0, v28
	v_add_f32_e32 v49, 1.0, v28
	v_fma_f32 v28, v32, v33, 0
	v_fmac_f32_e32 v28, v42, v43
	v_fmac_f32_e32 v28, v39, v45
	v_fmac_f32_e32 v28, v46, v47
	v_fmac_f32_e32 v28, v41, v36
	v_fmac_f32_e32 v28, v40, v44
	v_mul_f32_e32 v48, 0.5, v31
	v_fmac_f32_e32 v28, v37, v38
	v_fmac_f32_e32 v28, v48, v49
	s_nop 1
	v_add_f32_dpp v28, v28, v28 quad_perm:[1,0,3,2] row_mask:0xf bank_mask:0xf
	s_nop 1
	v_add_f32_dpp v28, v28, v28 quad_perm:[2,3,0,1] row_mask:0xf bank_mask:0xf
	s_nop 1
	v_add_f32_dpp v28, v28, v28 row_half_mirror row_mask:0xf bank_mask:0xf
	s_nop 1
	v_add_f32_dpp v28, v28, v28 row_mirror row_mask:0xf bank_mask:0xf
	s_nop 1
	v_add_f32_dpp v28, v28, v28 row_bcast:15 row_mask:0xa bank_mask:0xf
	s_nop 1
	v_add_f32_dpp v28, v28, v28 row_bcast:31 row_mask:0xc bank_mask:0xf
	s_nop 1
	v_readlane_b32 s98, v28, 63
	s_nop 1
	v_mov_b32_e32 v28, s98
	v_mul_f32_e32 v28, 0xbb000000, v28
	v_fma_f32 v34, v42, v43, v28
	v_fma_f32 v35, v32, v33, v28
	v_mul_f32_e32 v42, v34, v34
	v_fmac_f32_e32 v42, v35, v35
	v_fma_f32 v29, v39, v45, v28
	v_fmac_f32_e32 v42, v29, v29
	v_fma_f32 v30, v46, v47, v28
	v_fmac_f32_e32 v42, v30, v30
	v_fma_f32 v31, v41, v36, v28
	v_fmac_f32_e32 v42, v31, v31
	v_fma_f32 v32, v40, v44, v28
	v_fmac_f32_e32 v42, v32, v32
	v_fma_f32 v33, v37, v38, v28
	v_fmac_f32_e32 v42, v33, v33
	v_fmac_f32_e32 v28, v48, v49
	v_fmac_f32_e32 v42, v28, v28
	s_nop 1
	v_add_f32_dpp v36, v42, v42 quad_perm:[1,0,3,2] row_mask:0xf bank_mask:0xf
	s_nop 1
	v_add_f32_dpp v36, v36, v36 quad_perm:[2,3,0,1] row_mask:0xf bank_mask:0xf
	s_nop 1
	v_add_f32_dpp v36, v36, v36 row_half_mirror row_mask:0xf bank_mask:0xf
	s_nop 1
	v_add_f32_dpp v36, v36, v36 row_mirror row_mask:0xf bank_mask:0xf
	s_nop 1
	v_add_f32_dpp v36, v36, v36 row_bcast:15 row_mask:0xa bank_mask:0xf
	s_nop 1
	v_add_f32_dpp v36, v36, v36 row_bcast:31 row_mask:0xc bank_mask:0xf
	s_nop 1
	v_readlane_b32 s98, v36, 63
	s_nop 1
	v_mov_b32_e32 v36, s98
	v_mov_b32_e32 v37, 0
	s_and_saveexec_b64 s[0:1], s[38:39]
	s_cbranch_execz .LBB0_423
	s_waitcnt lgkmcnt(0)
	v_add_f32_e32 v36, v36, v37
	v_fmamk_f32 v36, v36, 0x3b000000, v189
	v_mul_f32_e32 v37, 0x4b800000, v36
	v_cmp_gt_f32_e32 vcc, s33, v36
	s_nop 1
	v_cndmask_b32_e32 v36, v36, v37, vcc
	v_rsq_f32_e32 v36, v36
	s_nop 0
	v_mul_f32_e32 v37, 0x45800000, v36
	v_cndmask_b32_e32 v36, v36, v37, vcc
	v_mul_f32_e32 v35, v35, v36
	v_mul_f32_e32 v34, v34, v36
	v_mul_f32_e32 v29, v29, v36
	v_cvt_pk_bf16_f32 v35, v35, v65
	ds_write_b16 v61, v35 offset:16
	v_cvt_pk_bf16_f32 v34, v34, v65
	ds_write_b16 v61, v34 offset:288
	v_cvt_pk_bf16_f32 v29, v29, v65
	ds_write_b16 v61, v29 offset:560
	v_mul_f32_e32 v29, v30, v36
	v_cvt_pk_bf16_f32 v29, v29, v65
	ds_write_b16 v61, v29 offset:832
	v_mul_f32_e32 v29, v31, v36
	v_cvt_pk_bf16_f32 v29, v29, v65
	ds_write_b16 v61, v29 offset:1104
	v_mul_f32_e32 v29, v32, v36
	v_cvt_pk_bf16_f32 v29, v29, v65
	ds_write_b16 v61, v29 offset:1376
	v_mul_f32_e32 v29, v33, v36
	v_mul_f32_e32 v28, v28, v36
	v_cvt_pk_bf16_f32 v29, v29, v65
	ds_write_b16 v61, v29 offset:1648
	v_cvt_pk_bf16_f32 v28, v28, v65
	ds_write_b16 v61, v28 offset:1920
.LBB0_423:
	s_or_b64 exec, exec, s[0:1]
	v_lshlrev_b32_e32 v28, 16, v24
	v_mul_f32_e32 v29, 0x3d372713, v28
	v_mul_f32_e32 v29, v29, v28
	v_fma_f32 v29, v29, v28, v28
	v_mul_f32_e32 v29, 0x3f4c422a, v29
	v_add_f32_e32 v29, v29, v29
	v_mul_f32_e32 v29, 0x3fb8aa3b, v29
	v_exp_f32_e32 v29, v29
	v_lshlrev_b32_e32 v31, 16, v26
	v_and_b32_e32 v24, 0xffff0000, v24
	v_and_b32_e32 v26, 0xffff0000, v26
	v_add_f32_e32 v29, 1.0, v29
	v_div_scale_f32 v32, s[0:1], v29, v29, 2.0
	v_rcp_f32_e32 v33, v32
	v_lshlrev_b32_e32 v30, 16, v25
	v_lshlrev_b32_e32 v34, 16, v27
	v_and_b32_e32 v25, 0xffff0000, v25
	v_fma_f32 v35, -v32, v33, 1.0
	v_fmac_f32_e32 v33, v35, v33
	v_div_scale_f32 v35, vcc, 2.0, v29, 2.0
	v_mul_f32_e32 v36, v35, v33
	s_waitcnt lgkmcnt(0)
	v_fma_f32 v37, -v32, v36, v35
	v_fmac_f32_e32 v36, v37, v33
	v_fma_f32 v32, -v32, v36, v35
	v_mul_f32_e32 v35, 0x3d372713, v31
	v_mul_f32_e32 v35, v35, v31
	v_fma_f32 v35, v35, v31, v31
	v_mul_f32_e32 v35, 0x3f4c422a, v35
	v_add_f32_e32 v35, v35, v35
	v_mul_f32_e32 v35, 0x3fb8aa3b, v35
	v_exp_f32_e32 v35, v35
	v_div_fmas_f32 v32, v32, v33, v36
	v_div_fixup_f32 v29, v32, v29, 2.0
	v_and_b32_e32 v27, 0xffff0000, v27
	v_add_f32_e32 v32, 1.0, v35
	v_div_scale_f32 v33, s[0:1], v32, v32, 2.0
	v_rcp_f32_e32 v35, v33
	v_sub_f32_e32 v29, 1.0, v29
	v_mul_f32_e32 v28, 0.5, v28
	v_add_f32_e32 v29, 1.0, v29
	v_fma_f32 v36, -v33, v35, 1.0
	v_fmac_f32_e32 v35, v36, v35
	v_div_scale_f32 v36, vcc, 2.0, v32, 2.0
	v_mul_f32_e32 v37, v36, v35
	v_fma_f32 v38, -v33, v37, v36
	v_fmac_f32_e32 v37, v38, v35
	v_fma_f32 v33, -v33, v37, v36
	v_mul_f32_e32 v36, 0x3d372713, v24
	v_mul_f32_e32 v36, v36, v24
	v_fma_f32 v36, v36, v24, v24
	v_mul_f32_e32 v36, 0x3f4c422a, v36
	v_add_f32_e32 v36, v36, v36
	v_mul_f32_e32 v36, 0x3fb8aa3b, v36
	v_exp_f32_e32 v36, v36
	v_div_fmas_f32 v33, v33, v35, v37
	v_div_fixup_f32 v32, v33, v32, 2.0
	v_mul_f32_e32 v37, 0.5, v31
	v_add_f32_e32 v33, 1.0, v36
	v_div_scale_f32 v35, s[0:1], v33, v33, 2.0
	v_rcp_f32_e32 v36, v35
	v_sub_f32_e32 v32, 1.0, v32
	v_add_f32_e32 v32, 1.0, v32
	v_fma_f32 v31, -v35, v36, 1.0
	v_fmac_f32_e32 v36, v31, v36
	v_div_scale_f32 v31, vcc, 2.0, v33, 2.0
	v_mul_f32_e32 v38, v31, v36
	v_fma_f32 v39, -v35, v38, v31
	v_fmac_f32_e32 v38, v39, v36
	v_fma_f32 v31, -v35, v38, v31
	v_mul_f32_e32 v35, 0x3d372713, v26
	v_mul_f32_e32 v35, v35, v26
	v_fma_f32 v35, v35, v26, v26
	v_mul_f32_e32 v35, 0x3f4c422a, v35
	v_add_f32_e32 v35, v35, v35
	v_mul_f32_e32 v35, 0x3fb8aa3b, v35
	v_exp_f32_e32 v35, v35
	v_div_fmas_f32 v31, v31, v36, v38
	v_div_fixup_f32 v31, v31, v33, 2.0
	v_mul_f32_e32 v38, 0.5, v24
	v_add_f32_e32 v33, 1.0, v35
	v_div_scale_f32 v35, s[0:1], v33, v33, 2.0
	v_rcp_f32_e32 v36, v35
	v_sub_f32_e32 v31, 1.0, v31
	v_add_f32_e32 v39, 1.0, v31
	v_fma_f32 v24, -v35, v36, 1.0
	v_fmac_f32_e32 v36, v24, v36
	v_div_scale_f32 v24, vcc, 2.0, v33, 2.0
	v_mul_f32_e32 v31, v24, v36
	v_fma_f32 v40, -v35, v31, v24
	v_fmac_f32_e32 v31, v40, v36
	v_fma_f32 v24, -v35, v31, v24
	v_mul_f32_e32 v35, 0x3d372713, v30
	v_mul_f32_e32 v35, v35, v30
	v_fma_f32 v35, v35, v30, v30
	v_mul_f32_e32 v35, 0x3f4c422a, v35
	v_add_f32_e32 v35, v35, v35
	v_mul_f32_e32 v35, 0x3fb8aa3b, v35
	v_exp_f32_e32 v35, v35
	v_div_fmas_f32 v24, v24, v36, v31
	v_div_fixup_f32 v24, v24, v33, 2.0
	v_sub_f32_e32 v24, 1.0, v24
	v_add_f32_e32 v31, 1.0, v35
	v_div_scale_f32 v33, s[0:1], v31, v31, 2.0
	v_rcp_f32_e32 v35, v33
	v_add_f32_e32 v40, 1.0, v24
	v_mul_f32_e32 v36, 0.5, v26
	v_fma_f32 v24, -v33, v35, 1.0
	v_fmac_f32_e32 v35, v24, v35
	v_div_scale_f32 v24, vcc, 2.0, v31, 2.0
	v_mul_f32_e32 v26, v24, v35
	v_fma_f32 v41, -v33, v26, v24
	v_fmac_f32_e32 v26, v41, v35
	v_fma_f32 v24, -v33, v26, v24
	v_mul_f32_e32 v33, 0x3d372713, v34
	v_mul_f32_e32 v33, v33, v34
	v_fma_f32 v33, v33, v34, v34
	v_mul_f32_e32 v33, 0x3f4c422a, v33
	v_add_f32_e32 v33, v33, v33
	v_mul_f32_e32 v33, 0x3fb8aa3b, v33
	v_exp_f32_e32 v33, v33
	v_div_fmas_f32 v24, v24, v35, v26
	v_div_fixup_f32 v24, v24, v31, 2.0
	v_sub_f32_e32 v24, 1.0, v24
	v_add_f32_e32 v26, 1.0, v33
	v_div_scale_f32 v31, s[0:1], v26, v26, 2.0
	v_rcp_f32_e32 v33, v31
	v_add_f32_e32 v41, 1.0, v24
	v_mul_f32_e32 v35, 0.5, v30
	v_fma_f32 v24, -v31, v33, 1.0
	v_fmac_f32_e32 v33, v24, v33
	v_div_scale_f32 v24, vcc, 2.0, v26, 2.0
	v_mul_f32_e32 v30, v24, v33
	v_fma_f32 v42, -v31, v30, v24
	v_fmac_f32_e32 v30, v42, v33
	v_fma_f32 v24, -v31, v30, v24
	v_mul_f32_e32 v31, 0x3d372713, v25
	v_mul_f32_e32 v31, v31, v25
	v_fma_f32 v31, v31, v25, v25
	v_mul_f32_e32 v31, 0x3f4c422a, v31
	v_add_f32_e32 v31, v31, v31
	v_mul_f32_e32 v31, 0x3fb8aa3b, v31
	v_exp_f32_e32 v31, v31
	v_div_fmas_f32 v24, v24, v33, v30
	v_div_fixup_f32 v24, v24, v26, 2.0
	v_sub_f32_e32 v24, 1.0, v24
	v_add_f32_e32 v26, 1.0, v31
	v_div_scale_f32 v30, s[0:1], v26, v26, 2.0
	v_rcp_f32_e32 v31, v30
	v_mul_f32_e32 v33, 0.5, v34
	v_add_f32_e32 v34, 1.0, v24
	v_fma_f32 v24, -v30, v31, 1.0
	v_fmac_f32_e32 v31, v24, v31
	v_div_scale_f32 v24, vcc, 2.0, v26, 2.0
	v_mul_f32_e32 v42, v24, v31
	v_fma_f32 v43, -v30, v42, v24
	v_fmac_f32_e32 v42, v43, v31
	v_fma_f32 v24, -v30, v42, v24
	v_mul_f32_e32 v30, 0x3d372713, v27
	v_mul_f32_e32 v30, v30, v27
	v_fma_f32 v30, v30, v27, v27
	v_mul_f32_e32 v30, 0x3f4c422a, v30
	v_add_f32_e32 v30, v30, v30
	v_mul_f32_e32 v30, 0x3fb8aa3b, v30
	v_exp_f32_e32 v30, v30
	v_div_fmas_f32 v24, v24, v31, v42
	v_div_fixup_f32 v24, v24, v26, 2.0
	v_sub_f32_e32 v24, 1.0, v24
	v_add_f32_e32 v26, 1.0, v30
	v_div_scale_f32 v30, s[0:1], v26, v26, 2.0
	v_rcp_f32_e32 v31, v30
	v_add_f32_e32 v43, 1.0, v24
	v_mul_f32_e32 v42, 0.5, v25
	v_fma_f32 v24, -v30, v31, 1.0
	v_fmac_f32_e32 v31, v24, v31
	v_div_scale_f32 v24, vcc, 2.0, v26, 2.0
	v_mul_f32_e32 v25, v24, v31
	v_fma_f32 v44, -v30, v25, v24
	v_fmac_f32_e32 v25, v44, v31
	v_fma_f32 v24, -v30, v25, v24
	v_div_fmas_f32 v24, v24, v31, v25
	v_div_fixup_f32 v24, v24, v26, 2.0
	v_sub_f32_e32 v24, 1.0, v24
	v_add_f32_e32 v45, 1.0, v24
	v_fma_f32 v24, v28, v29, 0
	v_fmac_f32_e32 v24, v38, v39
	v_fmac_f32_e32 v24, v35, v41
	v_fmac_f32_e32 v24, v42, v43
	v_fmac_f32_e32 v24, v37, v32
	v_fmac_f32_e32 v24, v36, v40
	v_mul_f32_e32 v44, 0.5, v27
	v_fmac_f32_e32 v24, v33, v34
	v_fmac_f32_e32 v24, v44, v45
	s_nop 1
	v_add_f32_dpp v24, v24, v24 quad_perm:[1,0,3,2] row_mask:0xf bank_mask:0xf
	s_nop 1
	v_add_f32_dpp v24, v24, v24 quad_perm:[2,3,0,1] row_mask:0xf bank_mask:0xf
	s_nop 1
	v_add_f32_dpp v24, v24, v24 row_half_mirror row_mask:0xf bank_mask:0xf
	s_nop 1
	v_add_f32_dpp v24, v24, v24 row_mirror row_mask:0xf bank_mask:0xf
	s_nop 1
	v_add_f32_dpp v24, v24, v24 row_bcast:15 row_mask:0xa bank_mask:0xf
	s_nop 1
	v_add_f32_dpp v24, v24, v24 row_bcast:31 row_mask:0xc bank_mask:0xf
	s_nop 1
	v_readlane_b32 s98, v24, 63
	s_nop 1
	v_mov_b32_e32 v24, s98
	v_mul_f32_e32 v24, 0xbb000000, v24
	v_fma_f32 v30, v38, v39, v24
	v_fma_f32 v31, v28, v29, v24
	v_mul_f32_e32 v38, v30, v30
	v_fmac_f32_e32 v38, v31, v31
	v_fma_f32 v25, v35, v41, v24
	v_fmac_f32_e32 v38, v25, v25
	v_fma_f32 v26, v42, v43, v24
	v_fmac_f32_e32 v38, v26, v26
	v_fma_f32 v27, v37, v32, v24
	v_fmac_f32_e32 v38, v27, v27
	v_fma_f32 v28, v36, v40, v24
	v_fmac_f32_e32 v38, v28, v28
	v_fma_f32 v29, v33, v34, v24
	v_fmac_f32_e32 v38, v29, v29
	v_fmac_f32_e32 v24, v44, v45
	v_fmac_f32_e32 v38, v24, v24
	s_nop 1
	v_add_f32_dpp v32, v38, v38 quad_perm:[1,0,3,2] row_mask:0xf bank_mask:0xf
	s_nop 1
	v_add_f32_dpp v32, v32, v32 quad_perm:[2,3,0,1] row_mask:0xf bank_mask:0xf
	s_nop 1
	v_add_f32_dpp v32, v32, v32 row_half_mirror row_mask:0xf bank_mask:0xf
	s_nop 1
	v_add_f32_dpp v32, v32, v32 row_mirror row_mask:0xf bank_mask:0xf
	s_nop 1
	v_add_f32_dpp v32, v32, v32 row_bcast:15 row_mask:0xa bank_mask:0xf
	s_nop 1
	v_add_f32_dpp v32, v32, v32 row_bcast:31 row_mask:0xc bank_mask:0xf
	s_nop 1
	v_readlane_b32 s98, v32, 63
	s_nop 1
	v_mov_b32_e32 v32, s98
	v_mov_b32_e32 v33, 0
	s_and_saveexec_b64 s[0:1], s[38:39]
	s_cbranch_execz .LBB0_425
	s_waitcnt lgkmcnt(0)
	v_add_f32_e32 v32, v32, v33
	v_fmamk_f32 v32, v32, 0x3b000000, v189
	v_mul_f32_e32 v33, 0x4b800000, v32
	v_cmp_gt_f32_e32 vcc, s33, v32
	s_nop 1
	v_cndmask_b32_e32 v32, v32, v33, vcc
	v_rsq_f32_e32 v32, v32
	s_nop 0
	v_mul_f32_e32 v33, 0x45800000, v32
	v_cndmask_b32_e32 v32, v32, v33, vcc
	v_mul_f32_e32 v31, v31, v32
	v_mul_f32_e32 v30, v30, v32
	v_mul_f32_e32 v25, v25, v32
	v_cvt_pk_bf16_f32 v31, v31, v65
	ds_write_b16 v61, v31 offset:18
	v_cvt_pk_bf16_f32 v30, v30, v65
	ds_write_b16 v61, v30 offset:290
	v_cvt_pk_bf16_f32 v25, v25, v65
	ds_write_b16 v61, v25 offset:562
	v_mul_f32_e32 v25, v26, v32
	v_cvt_pk_bf16_f32 v25, v25, v65
	ds_write_b16 v61, v25 offset:834
	v_mul_f32_e32 v25, v27, v32
	v_cvt_pk_bf16_f32 v25, v25, v65
	ds_write_b16 v61, v25 offset:1106
	v_mul_f32_e32 v25, v28, v32
	v_cvt_pk_bf16_f32 v25, v25, v65
	ds_write_b16 v61, v25 offset:1378
	v_mul_f32_e32 v25, v29, v32
	v_mul_f32_e32 v24, v24, v32
	v_cvt_pk_bf16_f32 v25, v25, v65
	ds_write_b16 v61, v25 offset:1650
	v_cvt_pk_bf16_f32 v24, v24, v65
	ds_write_b16 v61, v24 offset:1922
.LBB0_425:
	s_or_b64 exec, exec, s[0:1]
	s_waitcnt vmcnt(5)
	v_lshlrev_b32_e32 v24, 16, v20
	v_mul_f32_e32 v25, 0x3d372713, v24
	v_mul_f32_e32 v25, v25, v24
	v_fma_f32 v25, v25, v24, v24
	v_mul_f32_e32 v25, 0x3f4c422a, v25
	v_add_f32_e32 v25, v25, v25
	v_mul_f32_e32 v25, 0x3fb8aa3b, v25
	v_exp_f32_e32 v25, v25
	v_lshlrev_b32_e32 v27, 16, v22
	v_and_b32_e32 v20, 0xffff0000, v20
	v_and_b32_e32 v22, 0xffff0000, v22
	v_add_f32_e32 v25, 1.0, v25
	v_div_scale_f32 v28, s[0:1], v25, v25, 2.0
	v_rcp_f32_e32 v29, v28
	v_lshlrev_b32_e32 v26, 16, v21
	v_lshlrev_b32_e32 v30, 16, v23
	v_and_b32_e32 v21, 0xffff0000, v21
	v_fma_f32 v31, -v28, v29, 1.0
	v_fmac_f32_e32 v29, v31, v29
	v_div_scale_f32 v31, vcc, 2.0, v25, 2.0
	v_mul_f32_e32 v32, v31, v29
	s_waitcnt lgkmcnt(0)
	v_fma_f32 v33, -v28, v32, v31
	v_fmac_f32_e32 v32, v33, v29
	v_fma_f32 v28, -v28, v32, v31
	v_mul_f32_e32 v31, 0x3d372713, v27
	v_mul_f32_e32 v31, v31, v27
	v_fma_f32 v31, v31, v27, v27
	v_mul_f32_e32 v31, 0x3f4c422a, v31
	v_add_f32_e32 v31, v31, v31
	v_mul_f32_e32 v31, 0x3fb8aa3b, v31
	v_exp_f32_e32 v31, v31
	v_div_fmas_f32 v28, v28, v29, v32
	v_div_fixup_f32 v25, v28, v25, 2.0
	v_and_b32_e32 v23, 0xffff0000, v23
	v_add_f32_e32 v28, 1.0, v31
	v_div_scale_f32 v29, s[0:1], v28, v28, 2.0
	v_rcp_f32_e32 v31, v29
	v_sub_f32_e32 v25, 1.0, v25
	v_mul_f32_e32 v24, 0.5, v24
	v_add_f32_e32 v25, 1.0, v25
	v_fma_f32 v32, -v29, v31, 1.0
	v_fmac_f32_e32 v31, v32, v31
	v_div_scale_f32 v32, vcc, 2.0, v28, 2.0
	v_mul_f32_e32 v33, v32, v31
	v_fma_f32 v34, -v29, v33, v32
	v_fmac_f32_e32 v33, v34, v31
	v_fma_f32 v29, -v29, v33, v32
	v_mul_f32_e32 v32, 0x3d372713, v20
	v_mul_f32_e32 v32, v32, v20
	v_fma_f32 v32, v32, v20, v20
	v_mul_f32_e32 v32, 0x3f4c422a, v32
	v_add_f32_e32 v32, v32, v32
	v_mul_f32_e32 v32, 0x3fb8aa3b, v32
	v_exp_f32_e32 v32, v32
	v_div_fmas_f32 v29, v29, v31, v33
	v_div_fixup_f32 v28, v29, v28, 2.0
	v_mul_f32_e32 v33, 0.5, v27
	v_add_f32_e32 v29, 1.0, v32
	v_div_scale_f32 v31, s[0:1], v29, v29, 2.0
	v_rcp_f32_e32 v32, v31
	v_sub_f32_e32 v28, 1.0, v28
	v_add_f32_e32 v28, 1.0, v28
	v_fma_f32 v27, -v31, v32, 1.0
	v_fmac_f32_e32 v32, v27, v32
	v_div_scale_f32 v27, vcc, 2.0, v29, 2.0
	v_mul_f32_e32 v34, v27, v32
	v_fma_f32 v35, -v31, v34, v27
	v_fmac_f32_e32 v34, v35, v32
	v_fma_f32 v27, -v31, v34, v27
	v_mul_f32_e32 v31, 0x3d372713, v22
	v_mul_f32_e32 v31, v31, v22
	v_fma_f32 v31, v31, v22, v22
	v_mul_f32_e32 v31, 0x3f4c422a, v31
	v_add_f32_e32 v31, v31, v31
	v_mul_f32_e32 v31, 0x3fb8aa3b, v31
	v_exp_f32_e32 v31, v31
	v_div_fmas_f32 v27, v27, v32, v34
	v_div_fixup_f32 v27, v27, v29, 2.0
	v_mul_f32_e32 v34, 0.5, v20
	v_add_f32_e32 v29, 1.0, v31
	v_div_scale_f32 v31, s[0:1], v29, v29, 2.0
	v_rcp_f32_e32 v32, v31
	v_sub_f32_e32 v27, 1.0, v27
	v_add_f32_e32 v35, 1.0, v27
	v_fma_f32 v20, -v31, v32, 1.0
	v_fmac_f32_e32 v32, v20, v32
	v_div_scale_f32 v20, vcc, 2.0, v29, 2.0
	v_mul_f32_e32 v27, v20, v32
	v_fma_f32 v36, -v31, v27, v20
	v_fmac_f32_e32 v27, v36, v32
	v_fma_f32 v20, -v31, v27, v20
	v_mul_f32_e32 v31, 0x3d372713, v26
	v_mul_f32_e32 v31, v31, v26
	v_fma_f32 v31, v31, v26, v26
	v_mul_f32_e32 v31, 0x3f4c422a, v31
	v_add_f32_e32 v31, v31, v31
	v_mul_f32_e32 v31, 0x3fb8aa3b, v31
	v_exp_f32_e32 v31, v31
	v_div_fmas_f32 v20, v20, v32, v27
	v_div_fixup_f32 v20, v20, v29, 2.0
	v_sub_f32_e32 v20, 1.0, v20
	v_add_f32_e32 v27, 1.0, v31
	v_div_scale_f32 v29, s[0:1], v27, v27, 2.0
	v_rcp_f32_e32 v31, v29
	v_add_f32_e32 v36, 1.0, v20
	v_mul_f32_e32 v32, 0.5, v22
	v_fma_f32 v20, -v29, v31, 1.0
	v_fmac_f32_e32 v31, v20, v31
	v_div_scale_f32 v20, vcc, 2.0, v27, 2.0
	v_mul_f32_e32 v22, v20, v31
	v_fma_f32 v37, -v29, v22, v20
	v_fmac_f32_e32 v22, v37, v31
	v_fma_f32 v20, -v29, v22, v20
	v_mul_f32_e32 v29, 0x3d372713, v30
	v_mul_f32_e32 v29, v29, v30
	v_fma_f32 v29, v29, v30, v30
	v_mul_f32_e32 v29, 0x3f4c422a, v29
	v_add_f32_e32 v29, v29, v29
	v_mul_f32_e32 v29, 0x3fb8aa3b, v29
	v_exp_f32_e32 v29, v29
	v_div_fmas_f32 v20, v20, v31, v22
	v_div_fixup_f32 v20, v20, v27, 2.0
	v_sub_f32_e32 v20, 1.0, v20
	v_add_f32_e32 v22, 1.0, v29
	v_div_scale_f32 v27, s[0:1], v22, v22, 2.0
	v_rcp_f32_e32 v29, v27
	v_add_f32_e32 v37, 1.0, v20
	v_mul_f32_e32 v31, 0.5, v26
	v_fma_f32 v20, -v27, v29, 1.0
	v_fmac_f32_e32 v29, v20, v29
	v_div_scale_f32 v20, vcc, 2.0, v22, 2.0
	v_mul_f32_e32 v26, v20, v29
	v_fma_f32 v38, -v27, v26, v20
	v_fmac_f32_e32 v26, v38, v29
	v_fma_f32 v20, -v27, v26, v20
	v_mul_f32_e32 v27, 0x3d372713, v21
	v_mul_f32_e32 v27, v27, v21
	v_fma_f32 v27, v27, v21, v21
	v_mul_f32_e32 v27, 0x3f4c422a, v27
	v_add_f32_e32 v27, v27, v27
	v_mul_f32_e32 v27, 0x3fb8aa3b, v27
	v_exp_f32_e32 v27, v27
	v_div_fmas_f32 v20, v20, v29, v26
	v_div_fixup_f32 v20, v20, v22, 2.0
	v_sub_f32_e32 v20, 1.0, v20
	v_add_f32_e32 v22, 1.0, v27
	v_div_scale_f32 v26, s[0:1], v22, v22, 2.0
	v_rcp_f32_e32 v27, v26
	v_mul_f32_e32 v29, 0.5, v30
	v_add_f32_e32 v30, 1.0, v20
	v_fma_f32 v20, -v26, v27, 1.0
	v_fmac_f32_e32 v27, v20, v27
	v_div_scale_f32 v20, vcc, 2.0, v22, 2.0
	v_mul_f32_e32 v38, v20, v27
	v_fma_f32 v39, -v26, v38, v20
	v_fmac_f32_e32 v38, v39, v27
	v_fma_f32 v20, -v26, v38, v20
	v_mul_f32_e32 v26, 0x3d372713, v23
	v_mul_f32_e32 v26, v26, v23
	v_fma_f32 v26, v26, v23, v23
	v_mul_f32_e32 v26, 0x3f4c422a, v26
	v_add_f32_e32 v26, v26, v26
	v_mul_f32_e32 v26, 0x3fb8aa3b, v26
	v_exp_f32_e32 v26, v26
	v_div_fmas_f32 v20, v20, v27, v38
	v_div_fixup_f32 v20, v20, v22, 2.0
	v_sub_f32_e32 v20, 1.0, v20
	v_add_f32_e32 v22, 1.0, v26
	v_div_scale_f32 v26, s[0:1], v22, v22, 2.0
	v_rcp_f32_e32 v27, v26
	v_add_f32_e32 v39, 1.0, v20
	v_mul_f32_e32 v38, 0.5, v21
	v_fma_f32 v20, -v26, v27, 1.0
	v_fmac_f32_e32 v27, v20, v27
	v_div_scale_f32 v20, vcc, 2.0, v22, 2.0
	v_mul_f32_e32 v21, v20, v27
	v_fma_f32 v40, -v26, v21, v20
	v_fmac_f32_e32 v21, v40, v27
	v_fma_f32 v20, -v26, v21, v20
	v_div_fmas_f32 v20, v20, v27, v21
	v_div_fixup_f32 v20, v20, v22, 2.0
	v_sub_f32_e32 v20, 1.0, v20
	v_add_f32_e32 v41, 1.0, v20
	v_fma_f32 v20, v24, v25, 0
	v_fmac_f32_e32 v20, v34, v35
	v_fmac_f32_e32 v20, v31, v37
	v_fmac_f32_e32 v20, v38, v39
	v_fmac_f32_e32 v20, v33, v28
	v_fmac_f32_e32 v20, v32, v36
	v_mul_f32_e32 v40, 0.5, v23
	v_fmac_f32_e32 v20, v29, v30
	v_fmac_f32_e32 v20, v40, v41
	s_nop 1
	v_add_f32_dpp v20, v20, v20 quad_perm:[1,0,3,2] row_mask:0xf bank_mask:0xf
	s_nop 1
	v_add_f32_dpp v20, v20, v20 quad_perm:[2,3,0,1] row_mask:0xf bank_mask:0xf
	s_nop 1
	v_add_f32_dpp v20, v20, v20 row_half_mirror row_mask:0xf bank_mask:0xf
	s_nop 1
	v_add_f32_dpp v20, v20, v20 row_mirror row_mask:0xf bank_mask:0xf
	s_nop 1
	v_add_f32_dpp v20, v20, v20 row_bcast:15 row_mask:0xa bank_mask:0xf
	s_nop 1
	v_add_f32_dpp v20, v20, v20 row_bcast:31 row_mask:0xc bank_mask:0xf
	s_nop 1
	v_readlane_b32 s98, v20, 63
	s_nop 1
	v_mov_b32_e32 v20, s98
	v_mul_f32_e32 v20, 0xbb000000, v20
	v_fma_f32 v26, v34, v35, v20
	v_fma_f32 v27, v24, v25, v20
	v_mul_f32_e32 v34, v26, v26
	v_fmac_f32_e32 v34, v27, v27
	v_fma_f32 v21, v31, v37, v20
	v_fmac_f32_e32 v34, v21, v21
	v_fma_f32 v22, v38, v39, v20
	v_fmac_f32_e32 v34, v22, v22
	v_fma_f32 v23, v33, v28, v20
	v_fmac_f32_e32 v34, v23, v23
	v_fma_f32 v24, v32, v36, v20
	v_fmac_f32_e32 v34, v24, v24
	v_fma_f32 v25, v29, v30, v20
	v_fmac_f32_e32 v34, v25, v25
	v_fmac_f32_e32 v20, v40, v41
	v_fmac_f32_e32 v34, v20, v20
	s_nop 1
	v_add_f32_dpp v28, v34, v34 quad_perm:[1,0,3,2] row_mask:0xf bank_mask:0xf
	s_nop 1
	v_add_f32_dpp v28, v28, v28 quad_perm:[2,3,0,1] row_mask:0xf bank_mask:0xf
	s_nop 1
	v_add_f32_dpp v28, v28, v28 row_half_mirror row_mask:0xf bank_mask:0xf
	s_nop 1
	v_add_f32_dpp v28, v28, v28 row_mirror row_mask:0xf bank_mask:0xf
	s_nop 1
	v_add_f32_dpp v28, v28, v28 row_bcast:15 row_mask:0xa bank_mask:0xf
	s_nop 1
	v_add_f32_dpp v28, v28, v28 row_bcast:31 row_mask:0xc bank_mask:0xf
	s_nop 1
	v_readlane_b32 s98, v28, 63
	s_nop 1
	v_mov_b32_e32 v28, s98
	v_mov_b32_e32 v29, 0
	s_and_saveexec_b64 s[0:1], s[38:39]
	s_cbranch_execz .LBB0_427
	s_waitcnt lgkmcnt(0)
	v_add_f32_e32 v28, v28, v29
	v_fmamk_f32 v28, v28, 0x3b000000, v189
	v_mul_f32_e32 v29, 0x4b800000, v28
	v_cmp_gt_f32_e32 vcc, s33, v28
	s_nop 1
	v_cndmask_b32_e32 v28, v28, v29, vcc
	v_rsq_f32_e32 v28, v28
	s_nop 0
	v_mul_f32_e32 v29, 0x45800000, v28
	v_cndmask_b32_e32 v28, v28, v29, vcc
	v_mul_f32_e32 v27, v27, v28
	v_mul_f32_e32 v26, v26, v28
	v_mul_f32_e32 v21, v21, v28
	v_cvt_pk_bf16_f32 v27, v27, v65
	ds_write_b16 v61, v27 offset:20
	v_cvt_pk_bf16_f32 v26, v26, v65
	ds_write_b16 v61, v26 offset:292
	v_cvt_pk_bf16_f32 v21, v21, v65
	ds_write_b16 v61, v21 offset:564
	v_mul_f32_e32 v21, v22, v28
	v_cvt_pk_bf16_f32 v21, v21, v65
	ds_write_b16 v61, v21 offset:836
	v_mul_f32_e32 v21, v23, v28
	v_cvt_pk_bf16_f32 v21, v21, v65
	ds_write_b16 v61, v21 offset:1108
	v_mul_f32_e32 v21, v24, v28
	v_cvt_pk_bf16_f32 v21, v21, v65
	ds_write_b16 v61, v21 offset:1380
	v_mul_f32_e32 v21, v25, v28
	v_mul_f32_e32 v20, v20, v28
	v_cvt_pk_bf16_f32 v21, v21, v65
	ds_write_b16 v61, v21 offset:1652
	v_cvt_pk_bf16_f32 v20, v20, v65
	ds_write_b16 v61, v20 offset:1924
.LBB0_427:
	s_or_b64 exec, exec, s[0:1]
	s_waitcnt vmcnt(4)
	v_lshlrev_b32_e32 v20, 16, v16
	v_mul_f32_e32 v21, 0x3d372713, v20
	v_mul_f32_e32 v21, v21, v20
	v_fma_f32 v21, v21, v20, v20
	v_mul_f32_e32 v21, 0x3f4c422a, v21
	v_add_f32_e32 v21, v21, v21
	v_mul_f32_e32 v21, 0x3fb8aa3b, v21
	v_exp_f32_e32 v21, v21
	v_lshlrev_b32_e32 v23, 16, v18
	v_and_b32_e32 v16, 0xffff0000, v16
	v_and_b32_e32 v18, 0xffff0000, v18
	v_add_f32_e32 v21, 1.0, v21
	v_div_scale_f32 v24, s[0:1], v21, v21, 2.0
	v_rcp_f32_e32 v25, v24
	v_lshlrev_b32_e32 v22, 16, v17
	v_lshlrev_b32_e32 v26, 16, v19
	v_and_b32_e32 v17, 0xffff0000, v17
	v_fma_f32 v27, -v24, v25, 1.0
	v_fmac_f32_e32 v25, v27, v25
	v_div_scale_f32 v27, vcc, 2.0, v21, 2.0
	v_mul_f32_e32 v28, v27, v25
	s_waitcnt lgkmcnt(0)
	v_fma_f32 v29, -v24, v28, v27
	v_fmac_f32_e32 v28, v29, v25
	v_fma_f32 v24, -v24, v28, v27
	v_mul_f32_e32 v27, 0x3d372713, v23
	v_mul_f32_e32 v27, v27, v23
	v_fma_f32 v27, v27, v23, v23
	v_mul_f32_e32 v27, 0x3f4c422a, v27
	v_add_f32_e32 v27, v27, v27
	v_mul_f32_e32 v27, 0x3fb8aa3b, v27
	v_exp_f32_e32 v27, v27
	v_div_fmas_f32 v24, v24, v25, v28
	v_div_fixup_f32 v21, v24, v21, 2.0
	v_and_b32_e32 v19, 0xffff0000, v19
	v_add_f32_e32 v24, 1.0, v27
	v_div_scale_f32 v25, s[0:1], v24, v24, 2.0
	v_rcp_f32_e32 v27, v25
	v_sub_f32_e32 v21, 1.0, v21
	v_mul_f32_e32 v20, 0.5, v20
	v_add_f32_e32 v21, 1.0, v21
	v_fma_f32 v28, -v25, v27, 1.0
	v_fmac_f32_e32 v27, v28, v27
	v_div_scale_f32 v28, vcc, 2.0, v24, 2.0
	v_mul_f32_e32 v29, v28, v27
	v_fma_f32 v30, -v25, v29, v28
	v_fmac_f32_e32 v29, v30, v27
	v_fma_f32 v25, -v25, v29, v28
	v_mul_f32_e32 v28, 0x3d372713, v16
	v_mul_f32_e32 v28, v28, v16
	v_fma_f32 v28, v28, v16, v16
	v_mul_f32_e32 v28, 0x3f4c422a, v28
	v_add_f32_e32 v28, v28, v28
	v_mul_f32_e32 v28, 0x3fb8aa3b, v28
	v_exp_f32_e32 v28, v28
	v_div_fmas_f32 v25, v25, v27, v29
	v_div_fixup_f32 v24, v25, v24, 2.0
	v_mul_f32_e32 v29, 0.5, v23
	v_add_f32_e32 v25, 1.0, v28
	v_div_scale_f32 v27, s[0:1], v25, v25, 2.0
	v_rcp_f32_e32 v28, v27
	v_sub_f32_e32 v24, 1.0, v24
	v_add_f32_e32 v24, 1.0, v24
	v_fma_f32 v23, -v27, v28, 1.0
	v_fmac_f32_e32 v28, v23, v28
	v_div_scale_f32 v23, vcc, 2.0, v25, 2.0
	v_mul_f32_e32 v30, v23, v28
	v_fma_f32 v31, -v27, v30, v23
	v_fmac_f32_e32 v30, v31, v28
	v_fma_f32 v23, -v27, v30, v23
	v_mul_f32_e32 v27, 0x3d372713, v18
	v_mul_f32_e32 v27, v27, v18
	v_fma_f32 v27, v27, v18, v18
	v_mul_f32_e32 v27, 0x3f4c422a, v27
	v_add_f32_e32 v27, v27, v27
	v_mul_f32_e32 v27, 0x3fb8aa3b, v27
	v_exp_f32_e32 v27, v27
	v_div_fmas_f32 v23, v23, v28, v30
	v_div_fixup_f32 v23, v23, v25, 2.0
	v_mul_f32_e32 v30, 0.5, v16
	v_add_f32_e32 v25, 1.0, v27
	v_div_scale_f32 v27, s[0:1], v25, v25, 2.0
	v_rcp_f32_e32 v28, v27
	v_sub_f32_e32 v23, 1.0, v23
	v_add_f32_e32 v31, 1.0, v23
	v_fma_f32 v16, -v27, v28, 1.0
	v_fmac_f32_e32 v28, v16, v28
	v_div_scale_f32 v16, vcc, 2.0, v25, 2.0
	v_mul_f32_e32 v23, v16, v28
	v_fma_f32 v32, -v27, v23, v16
	v_fmac_f32_e32 v23, v32, v28
	v_fma_f32 v16, -v27, v23, v16
	v_mul_f32_e32 v27, 0x3d372713, v22
	v_mul_f32_e32 v27, v27, v22
	v_fma_f32 v27, v27, v22, v22
	v_mul_f32_e32 v27, 0x3f4c422a, v27
	v_add_f32_e32 v27, v27, v27
	v_mul_f32_e32 v27, 0x3fb8aa3b, v27
	v_exp_f32_e32 v27, v27
	v_div_fmas_f32 v16, v16, v28, v23
	v_div_fixup_f32 v16, v16, v25, 2.0
	v_sub_f32_e32 v16, 1.0, v16
	v_add_f32_e32 v23, 1.0, v27
	v_div_scale_f32 v25, s[0:1], v23, v23, 2.0
	v_rcp_f32_e32 v27, v25
	v_add_f32_e32 v32, 1.0, v16
	v_mul_f32_e32 v28, 0.5, v18
	v_fma_f32 v16, -v25, v27, 1.0
	v_fmac_f32_e32 v27, v16, v27
	v_div_scale_f32 v16, vcc, 2.0, v23, 2.0
	v_mul_f32_e32 v18, v16, v27
	v_fma_f32 v33, -v25, v18, v16
	v_fmac_f32_e32 v18, v33, v27
	v_fma_f32 v16, -v25, v18, v16
	v_mul_f32_e32 v25, 0x3d372713, v26
	v_mul_f32_e32 v25, v25, v26
	v_fma_f32 v25, v25, v26, v26
	v_mul_f32_e32 v25, 0x3f4c422a, v25
	v_add_f32_e32 v25, v25, v25
	v_mul_f32_e32 v25, 0x3fb8aa3b, v25
	v_exp_f32_e32 v25, v25
	v_div_fmas_f32 v16, v16, v27, v18
	v_div_fixup_f32 v16, v16, v23, 2.0
	v_sub_f32_e32 v16, 1.0, v16
	v_add_f32_e32 v18, 1.0, v25
	v_div_scale_f32 v23, s[0:1], v18, v18, 2.0
	v_rcp_f32_e32 v25, v23
	v_add_f32_e32 v33, 1.0, v16
	v_mul_f32_e32 v27, 0.5, v22
	v_fma_f32 v16, -v23, v25, 1.0
	v_fmac_f32_e32 v25, v16, v25
	v_div_scale_f32 v16, vcc, 2.0, v18, 2.0
	v_mul_f32_e32 v22, v16, v25
	v_fma_f32 v34, -v23, v22, v16
	v_fmac_f32_e32 v22, v34, v25
	v_fma_f32 v16, -v23, v22, v16
	v_mul_f32_e32 v23, 0x3d372713, v17
	v_mul_f32_e32 v23, v23, v17
	v_fma_f32 v23, v23, v17, v17
	v_mul_f32_e32 v23, 0x3f4c422a, v23
	v_add_f32_e32 v23, v23, v23
	v_mul_f32_e32 v23, 0x3fb8aa3b, v23
	v_exp_f32_e32 v23, v23
	v_div_fmas_f32 v16, v16, v25, v22
	v_div_fixup_f32 v16, v16, v18, 2.0
	v_sub_f32_e32 v16, 1.0, v16
	v_add_f32_e32 v18, 1.0, v23
	v_div_scale_f32 v22, s[0:1], v18, v18, 2.0
	v_rcp_f32_e32 v23, v22
	v_mul_f32_e32 v25, 0.5, v26
	v_add_f32_e32 v26, 1.0, v16
	v_fma_f32 v16, -v22, v23, 1.0
	v_fmac_f32_e32 v23, v16, v23
	v_div_scale_f32 v16, vcc, 2.0, v18, 2.0
	v_mul_f32_e32 v34, v16, v23
	v_fma_f32 v35, -v22, v34, v16
	v_fmac_f32_e32 v34, v35, v23
	v_fma_f32 v16, -v22, v34, v16
	v_mul_f32_e32 v22, 0x3d372713, v19
	v_mul_f32_e32 v22, v22, v19
	v_fma_f32 v22, v22, v19, v19
	v_mul_f32_e32 v22, 0x3f4c422a, v22
	v_add_f32_e32 v22, v22, v22
	v_mul_f32_e32 v22, 0x3fb8aa3b, v22
	v_exp_f32_e32 v22, v22
	v_div_fmas_f32 v16, v16, v23, v34
	v_div_fixup_f32 v16, v16, v18, 2.0
	v_sub_f32_e32 v16, 1.0, v16
	v_add_f32_e32 v18, 1.0, v22
	v_div_scale_f32 v22, s[0:1], v18, v18, 2.0
	v_rcp_f32_e32 v23, v22
	v_add_f32_e32 v35, 1.0, v16
	v_mul_f32_e32 v34, 0.5, v17
	v_fma_f32 v16, -v22, v23, 1.0
	v_fmac_f32_e32 v23, v16, v23
	v_div_scale_f32 v16, vcc, 2.0, v18, 2.0
	v_mul_f32_e32 v17, v16, v23
	v_fma_f32 v36, -v22, v17, v16
	v_fmac_f32_e32 v17, v36, v23
	v_fma_f32 v16, -v22, v17, v16
	v_div_fmas_f32 v16, v16, v23, v17
	v_div_fixup_f32 v16, v16, v18, 2.0
	v_sub_f32_e32 v16, 1.0, v16
	v_add_f32_e32 v37, 1.0, v16
	v_fma_f32 v16, v20, v21, 0
	v_fmac_f32_e32 v16, v30, v31
	v_fmac_f32_e32 v16, v27, v33
	v_fmac_f32_e32 v16, v34, v35
	v_fmac_f32_e32 v16, v29, v24
	v_fmac_f32_e32 v16, v28, v32
	v_mul_f32_e32 v36, 0.5, v19
	v_fmac_f32_e32 v16, v25, v26
	v_fmac_f32_e32 v16, v36, v37
	s_nop 1
	v_add_f32_dpp v16, v16, v16 quad_perm:[1,0,3,2] row_mask:0xf bank_mask:0xf
	s_nop 1
	v_add_f32_dpp v16, v16, v16 quad_perm:[2,3,0,1] row_mask:0xf bank_mask:0xf
	s_nop 1
	v_add_f32_dpp v16, v16, v16 row_half_mirror row_mask:0xf bank_mask:0xf
	s_nop 1
	v_add_f32_dpp v16, v16, v16 row_mirror row_mask:0xf bank_mask:0xf
	s_nop 1
	v_add_f32_dpp v16, v16, v16 row_bcast:15 row_mask:0xa bank_mask:0xf
	s_nop 1
	v_add_f32_dpp v16, v16, v16 row_bcast:31 row_mask:0xc bank_mask:0xf
	s_nop 1
	v_readlane_b32 s98, v16, 63
	s_nop 1
	v_mov_b32_e32 v16, s98
	v_mul_f32_e32 v16, 0xbb000000, v16
	v_fma_f32 v22, v30, v31, v16
	v_fma_f32 v23, v20, v21, v16
	v_mul_f32_e32 v30, v22, v22
	v_fmac_f32_e32 v30, v23, v23
	v_fma_f32 v17, v27, v33, v16
	v_fmac_f32_e32 v30, v17, v17
	v_fma_f32 v18, v34, v35, v16
	v_fmac_f32_e32 v30, v18, v18
	v_fma_f32 v19, v29, v24, v16
	v_fmac_f32_e32 v30, v19, v19
	v_fma_f32 v20, v28, v32, v16
	v_fmac_f32_e32 v30, v20, v20
	v_fma_f32 v21, v25, v26, v16
	v_fmac_f32_e32 v30, v21, v21
	v_fmac_f32_e32 v16, v36, v37
	v_fmac_f32_e32 v30, v16, v16
	s_nop 1
	v_add_f32_dpp v24, v30, v30 quad_perm:[1,0,3,2] row_mask:0xf bank_mask:0xf
	s_nop 1
	v_add_f32_dpp v24, v24, v24 quad_perm:[2,3,0,1] row_mask:0xf bank_mask:0xf
	s_nop 1
	v_add_f32_dpp v24, v24, v24 row_half_mirror row_mask:0xf bank_mask:0xf
	s_nop 1
	v_add_f32_dpp v24, v24, v24 row_mirror row_mask:0xf bank_mask:0xf
	s_nop 1
	v_add_f32_dpp v24, v24, v24 row_bcast:15 row_mask:0xa bank_mask:0xf
	s_nop 1
	v_add_f32_dpp v24, v24, v24 row_bcast:31 row_mask:0xc bank_mask:0xf
	s_nop 1
	v_readlane_b32 s98, v24, 63
	s_nop 1
	v_mov_b32_e32 v24, s98
	v_mov_b32_e32 v25, 0
	s_and_saveexec_b64 s[0:1], s[38:39]
	s_cbranch_execz .LBB0_429
	s_waitcnt lgkmcnt(0)
	v_add_f32_e32 v24, v24, v25
	v_fmamk_f32 v24, v24, 0x3b000000, v189
	v_mul_f32_e32 v25, 0x4b800000, v24
	v_cmp_gt_f32_e32 vcc, s33, v24
	s_nop 1
	v_cndmask_b32_e32 v24, v24, v25, vcc
	v_rsq_f32_e32 v24, v24
	s_nop 0
	v_mul_f32_e32 v25, 0x45800000, v24
	v_cndmask_b32_e32 v24, v24, v25, vcc
	v_mul_f32_e32 v23, v23, v24
	v_mul_f32_e32 v22, v22, v24
	v_mul_f32_e32 v17, v17, v24
	v_cvt_pk_bf16_f32 v23, v23, v65
	ds_write_b16 v61, v23 offset:22
	v_cvt_pk_bf16_f32 v22, v22, v65
	ds_write_b16 v61, v22 offset:294
	v_cvt_pk_bf16_f32 v17, v17, v65
	ds_write_b16 v61, v17 offset:566
	v_mul_f32_e32 v17, v18, v24
	v_cvt_pk_bf16_f32 v17, v17, v65
	ds_write_b16 v61, v17 offset:838
	v_mul_f32_e32 v17, v19, v24
	v_cvt_pk_bf16_f32 v17, v17, v65
	ds_write_b16 v61, v17 offset:1110
	v_mul_f32_e32 v17, v20, v24
	v_cvt_pk_bf16_f32 v17, v17, v65
	ds_write_b16 v61, v17 offset:1382
	v_mul_f32_e32 v17, v21, v24
	v_mul_f32_e32 v16, v16, v24
	v_cvt_pk_bf16_f32 v17, v17, v65
	ds_write_b16 v61, v17 offset:1654
	v_cvt_pk_bf16_f32 v16, v16, v65
	ds_write_b16 v61, v16 offset:1926
.LBB0_429:
	s_or_b64 exec, exec, s[0:1]
	s_waitcnt vmcnt(3)
	v_lshlrev_b32_e32 v16, 16, v12
	v_mul_f32_e32 v17, 0x3d372713, v16
	v_mul_f32_e32 v17, v17, v16
	v_fma_f32 v17, v17, v16, v16
	v_mul_f32_e32 v17, 0x3f4c422a, v17
	v_add_f32_e32 v17, v17, v17
	v_mul_f32_e32 v17, 0x3fb8aa3b, v17
	v_exp_f32_e32 v17, v17
	v_lshlrev_b32_e32 v19, 16, v14
	v_and_b32_e32 v12, 0xffff0000, v12
	v_and_b32_e32 v14, 0xffff0000, v14
	v_add_f32_e32 v17, 1.0, v17
	v_div_scale_f32 v20, s[0:1], v17, v17, 2.0
	v_rcp_f32_e32 v21, v20
	v_lshlrev_b32_e32 v18, 16, v13
	v_lshlrev_b32_e32 v22, 16, v15
	v_and_b32_e32 v13, 0xffff0000, v13
	v_fma_f32 v23, -v20, v21, 1.0
	v_fmac_f32_e32 v21, v23, v21
	v_div_scale_f32 v23, vcc, 2.0, v17, 2.0
	v_mul_f32_e32 v24, v23, v21
	s_waitcnt lgkmcnt(0)
	v_fma_f32 v25, -v20, v24, v23
	v_fmac_f32_e32 v24, v25, v21
	v_fma_f32 v20, -v20, v24, v23
	v_mul_f32_e32 v23, 0x3d372713, v19
	v_mul_f32_e32 v23, v23, v19
	v_fma_f32 v23, v23, v19, v19
	v_mul_f32_e32 v23, 0x3f4c422a, v23
	v_add_f32_e32 v23, v23, v23
	v_mul_f32_e32 v23, 0x3fb8aa3b, v23
	v_exp_f32_e32 v23, v23
	v_div_fmas_f32 v20, v20, v21, v24
	v_div_fixup_f32 v17, v20, v17, 2.0
	v_and_b32_e32 v15, 0xffff0000, v15
	v_add_f32_e32 v20, 1.0, v23
	v_div_scale_f32 v21, s[0:1], v20, v20, 2.0
	v_rcp_f32_e32 v23, v21
	v_sub_f32_e32 v17, 1.0, v17
	v_mul_f32_e32 v16, 0.5, v16
	v_add_f32_e32 v17, 1.0, v17
	v_fma_f32 v24, -v21, v23, 1.0
	v_fmac_f32_e32 v23, v24, v23
	v_div_scale_f32 v24, vcc, 2.0, v20, 2.0
	v_mul_f32_e32 v25, v24, v23
	v_fma_f32 v26, -v21, v25, v24
	v_fmac_f32_e32 v25, v26, v23
	v_fma_f32 v21, -v21, v25, v24
	v_mul_f32_e32 v24, 0x3d372713, v12
	v_mul_f32_e32 v24, v24, v12
	v_fma_f32 v24, v24, v12, v12
	v_mul_f32_e32 v24, 0x3f4c422a, v24
	v_add_f32_e32 v24, v24, v24
	v_mul_f32_e32 v24, 0x3fb8aa3b, v24
	v_exp_f32_e32 v24, v24
	v_div_fmas_f32 v21, v21, v23, v25
	v_div_fixup_f32 v20, v21, v20, 2.0
	v_mul_f32_e32 v25, 0.5, v19
	v_add_f32_e32 v21, 1.0, v24
	v_div_scale_f32 v23, s[0:1], v21, v21, 2.0
	v_rcp_f32_e32 v24, v23
	v_sub_f32_e32 v20, 1.0, v20
	v_add_f32_e32 v20, 1.0, v20
	v_fma_f32 v19, -v23, v24, 1.0
	v_fmac_f32_e32 v24, v19, v24
	v_div_scale_f32 v19, vcc, 2.0, v21, 2.0
	v_mul_f32_e32 v26, v19, v24
	v_fma_f32 v27, -v23, v26, v19
	v_fmac_f32_e32 v26, v27, v24
	v_fma_f32 v19, -v23, v26, v19
	v_mul_f32_e32 v23, 0x3d372713, v14
	v_mul_f32_e32 v23, v23, v14
	v_fma_f32 v23, v23, v14, v14
	v_mul_f32_e32 v23, 0x3f4c422a, v23
	v_add_f32_e32 v23, v23, v23
	v_mul_f32_e32 v23, 0x3fb8aa3b, v23
	v_exp_f32_e32 v23, v23
	v_div_fmas_f32 v19, v19, v24, v26
	v_div_fixup_f32 v19, v19, v21, 2.0
	v_mul_f32_e32 v26, 0.5, v12
	v_add_f32_e32 v21, 1.0, v23
	v_div_scale_f32 v23, s[0:1], v21, v21, 2.0
	v_rcp_f32_e32 v24, v23
	v_sub_f32_e32 v19, 1.0, v19
	v_add_f32_e32 v27, 1.0, v19
	v_fma_f32 v12, -v23, v24, 1.0
	v_fmac_f32_e32 v24, v12, v24
	v_div_scale_f32 v12, vcc, 2.0, v21, 2.0
	v_mul_f32_e32 v19, v12, v24
	v_fma_f32 v28, -v23, v19, v12
	v_fmac_f32_e32 v19, v28, v24
	v_fma_f32 v12, -v23, v19, v12
	v_mul_f32_e32 v23, 0x3d372713, v18
	v_mul_f32_e32 v23, v23, v18
	v_fma_f32 v23, v23, v18, v18
	v_mul_f32_e32 v23, 0x3f4c422a, v23
	v_add_f32_e32 v23, v23, v23
	v_mul_f32_e32 v23, 0x3fb8aa3b, v23
	v_exp_f32_e32 v23, v23
	v_div_fmas_f32 v12, v12, v24, v19
	v_div_fixup_f32 v12, v12, v21, 2.0
	v_sub_f32_e32 v12, 1.0, v12
	v_add_f32_e32 v19, 1.0, v23
	v_div_scale_f32 v21, s[0:1], v19, v19, 2.0
	v_rcp_f32_e32 v23, v21
	v_add_f32_e32 v28, 1.0, v12
	v_mul_f32_e32 v24, 0.5, v14
	v_fma_f32 v12, -v21, v23, 1.0
	v_fmac_f32_e32 v23, v12, v23
	v_div_scale_f32 v12, vcc, 2.0, v19, 2.0
	v_mul_f32_e32 v14, v12, v23
	v_fma_f32 v29, -v21, v14, v12
	v_fmac_f32_e32 v14, v29, v23
	v_fma_f32 v12, -v21, v14, v12
	v_mul_f32_e32 v21, 0x3d372713, v22
	v_mul_f32_e32 v21, v21, v22
	v_fma_f32 v21, v21, v22, v22
	v_mul_f32_e32 v21, 0x3f4c422a, v21
	v_add_f32_e32 v21, v21, v21
	v_mul_f32_e32 v21, 0x3fb8aa3b, v21
	v_exp_f32_e32 v21, v21
	v_div_fmas_f32 v12, v12, v23, v14
	v_div_fixup_f32 v12, v12, v19, 2.0
	v_sub_f32_e32 v12, 1.0, v12
	v_add_f32_e32 v14, 1.0, v21
	v_div_scale_f32 v19, s[0:1], v14, v14, 2.0
	v_rcp_f32_e32 v21, v19
	v_add_f32_e32 v29, 1.0, v12
	v_mul_f32_e32 v23, 0.5, v18
	v_fma_f32 v12, -v19, v21, 1.0
	v_fmac_f32_e32 v21, v12, v21
	v_div_scale_f32 v12, vcc, 2.0, v14, 2.0
	v_mul_f32_e32 v18, v12, v21
	v_fma_f32 v30, -v19, v18, v12
	v_fmac_f32_e32 v18, v30, v21
	v_fma_f32 v12, -v19, v18, v12
	v_mul_f32_e32 v19, 0x3d372713, v13
	v_mul_f32_e32 v19, v19, v13
	v_fma_f32 v19, v19, v13, v13
	v_mul_f32_e32 v19, 0x3f4c422a, v19
	v_add_f32_e32 v19, v19, v19
	v_mul_f32_e32 v19, 0x3fb8aa3b, v19
	v_exp_f32_e32 v19, v19
	v_div_fmas_f32 v12, v12, v21, v18
	v_div_fixup_f32 v12, v12, v14, 2.0
	v_sub_f32_e32 v12, 1.0, v12
	v_add_f32_e32 v14, 1.0, v19
	v_div_scale_f32 v18, s[0:1], v14, v14, 2.0
	v_rcp_f32_e32 v19, v18
	v_mul_f32_e32 v21, 0.5, v22
	v_add_f32_e32 v22, 1.0, v12
	v_fma_f32 v12, -v18, v19, 1.0
	v_fmac_f32_e32 v19, v12, v19
	v_div_scale_f32 v12, vcc, 2.0, v14, 2.0
	v_mul_f32_e32 v30, v12, v19
	v_fma_f32 v31, -v18, v30, v12
	v_fmac_f32_e32 v30, v31, v19
	v_fma_f32 v12, -v18, v30, v12
	v_mul_f32_e32 v18, 0x3d372713, v15
	v_mul_f32_e32 v18, v18, v15
	v_fma_f32 v18, v18, v15, v15
	v_mul_f32_e32 v18, 0x3f4c422a, v18
	v_add_f32_e32 v18, v18, v18
	v_mul_f32_e32 v18, 0x3fb8aa3b, v18
	v_exp_f32_e32 v18, v18
	v_div_fmas_f32 v12, v12, v19, v30
	v_div_fixup_f32 v12, v12, v14, 2.0
	v_sub_f32_e32 v12, 1.0, v12
	v_add_f32_e32 v14, 1.0, v18
	v_div_scale_f32 v18, s[0:1], v14, v14, 2.0
	v_rcp_f32_e32 v19, v18
	v_add_f32_e32 v31, 1.0, v12
	v_mul_f32_e32 v30, 0.5, v13
	v_fma_f32 v12, -v18, v19, 1.0
	v_fmac_f32_e32 v19, v12, v19
	v_div_scale_f32 v12, vcc, 2.0, v14, 2.0
	v_mul_f32_e32 v13, v12, v19
	v_fma_f32 v32, -v18, v13, v12
	v_fmac_f32_e32 v13, v32, v19
	v_fma_f32 v12, -v18, v13, v12
	v_div_fmas_f32 v12, v12, v19, v13
	v_div_fixup_f32 v12, v12, v14, 2.0
	v_sub_f32_e32 v12, 1.0, v12
	v_add_f32_e32 v33, 1.0, v12
	v_fma_f32 v12, v16, v17, 0
	v_fmac_f32_e32 v12, v26, v27
	v_fmac_f32_e32 v12, v23, v29
	v_fmac_f32_e32 v12, v30, v31
	v_fmac_f32_e32 v12, v25, v20
	v_fmac_f32_e32 v12, v24, v28
	v_mul_f32_e32 v32, 0.5, v15
	v_fmac_f32_e32 v12, v21, v22
	v_fmac_f32_e32 v12, v32, v33
	s_nop 1
	v_add_f32_dpp v12, v12, v12 quad_perm:[1,0,3,2] row_mask:0xf bank_mask:0xf
	s_nop 1
	v_add_f32_dpp v12, v12, v12 quad_perm:[2,3,0,1] row_mask:0xf bank_mask:0xf
	s_nop 1
	v_add_f32_dpp v12, v12, v12 row_half_mirror row_mask:0xf bank_mask:0xf
	s_nop 1
	v_add_f32_dpp v12, v12, v12 row_mirror row_mask:0xf bank_mask:0xf
	s_nop 1
	v_add_f32_dpp v12, v12, v12 row_bcast:15 row_mask:0xa bank_mask:0xf
	s_nop 1
	v_add_f32_dpp v12, v12, v12 row_bcast:31 row_mask:0xc bank_mask:0xf
	s_nop 1
	v_readlane_b32 s98, v12, 63
	s_nop 1
	v_mov_b32_e32 v12, s98
	v_mul_f32_e32 v12, 0xbb000000, v12
	v_fma_f32 v18, v26, v27, v12
	v_fma_f32 v19, v16, v17, v12
	v_mul_f32_e32 v26, v18, v18
	v_fmac_f32_e32 v26, v19, v19
	v_fma_f32 v13, v23, v29, v12
	v_fmac_f32_e32 v26, v13, v13
	v_fma_f32 v14, v30, v31, v12
	v_fmac_f32_e32 v26, v14, v14
	v_fma_f32 v15, v25, v20, v12
	v_fmac_f32_e32 v26, v15, v15
	v_fma_f32 v16, v24, v28, v12
	v_fmac_f32_e32 v26, v16, v16
	v_fma_f32 v17, v21, v22, v12
	v_fmac_f32_e32 v26, v17, v17
	v_fmac_f32_e32 v12, v32, v33
	v_fmac_f32_e32 v26, v12, v12
	s_nop 1
	v_add_f32_dpp v20, v26, v26 quad_perm:[1,0,3,2] row_mask:0xf bank_mask:0xf
	s_nop 1
	v_add_f32_dpp v20, v20, v20 quad_perm:[2,3,0,1] row_mask:0xf bank_mask:0xf
	s_nop 1
	v_add_f32_dpp v20, v20, v20 row_half_mirror row_mask:0xf bank_mask:0xf
	s_nop 1
	v_add_f32_dpp v20, v20, v20 row_mirror row_mask:0xf bank_mask:0xf
	s_nop 1
	v_add_f32_dpp v20, v20, v20 row_bcast:15 row_mask:0xa bank_mask:0xf
	s_nop 1
	v_add_f32_dpp v20, v20, v20 row_bcast:31 row_mask:0xc bank_mask:0xf
	s_nop 1
	v_readlane_b32 s98, v20, 63
	s_nop 1
	v_mov_b32_e32 v20, s98
	v_mov_b32_e32 v21, 0
	s_and_saveexec_b64 s[0:1], s[38:39]
	s_cbranch_execz .LBB0_431
	s_waitcnt lgkmcnt(0)
	v_add_f32_e32 v20, v20, v21
	v_fmamk_f32 v20, v20, 0x3b000000, v189
	v_mul_f32_e32 v21, 0x4b800000, v20
	v_cmp_gt_f32_e32 vcc, s33, v20
	s_nop 1
	v_cndmask_b32_e32 v20, v20, v21, vcc
	v_rsq_f32_e32 v20, v20
	s_nop 0
	v_mul_f32_e32 v21, 0x45800000, v20
	v_cndmask_b32_e32 v20, v20, v21, vcc
	v_mul_f32_e32 v19, v19, v20
	v_mul_f32_e32 v18, v18, v20
	v_mul_f32_e32 v13, v13, v20
	v_cvt_pk_bf16_f32 v19, v19, v65
	ds_write_b16 v61, v19 offset:24
	v_cvt_pk_bf16_f32 v18, v18, v65
	ds_write_b16 v61, v18 offset:296
	v_cvt_pk_bf16_f32 v13, v13, v65
	ds_write_b16 v61, v13 offset:568
	v_mul_f32_e32 v13, v14, v20
	v_cvt_pk_bf16_f32 v13, v13, v65
	ds_write_b16 v61, v13 offset:840
	v_mul_f32_e32 v13, v15, v20
	v_cvt_pk_bf16_f32 v13, v13, v65
	ds_write_b16 v61, v13 offset:1112
	v_mul_f32_e32 v13, v16, v20
	v_cvt_pk_bf16_f32 v13, v13, v65
	ds_write_b16 v61, v13 offset:1384
	v_mul_f32_e32 v13, v17, v20
	v_mul_f32_e32 v12, v12, v20
	v_cvt_pk_bf16_f32 v13, v13, v65
	ds_write_b16 v61, v13 offset:1656
	v_cvt_pk_bf16_f32 v12, v12, v65
	ds_write_b16 v61, v12 offset:1928
.LBB0_431:
	s_or_b64 exec, exec, s[0:1]
	s_waitcnt vmcnt(2)
	v_lshlrev_b32_e32 v12, 16, v8
	v_mul_f32_e32 v13, 0x3d372713, v12
	v_mul_f32_e32 v13, v13, v12
	v_fma_f32 v13, v13, v12, v12
	v_mul_f32_e32 v13, 0x3f4c422a, v13
	v_add_f32_e32 v13, v13, v13
	v_mul_f32_e32 v13, 0x3fb8aa3b, v13
	v_exp_f32_e32 v13, v13
	v_lshlrev_b32_e32 v15, 16, v10
	v_and_b32_e32 v8, 0xffff0000, v8
	v_and_b32_e32 v10, 0xffff0000, v10
	v_add_f32_e32 v13, 1.0, v13
	v_div_scale_f32 v16, s[0:1], v13, v13, 2.0
	v_rcp_f32_e32 v17, v16
	v_lshlrev_b32_e32 v14, 16, v9
	v_lshlrev_b32_e32 v18, 16, v11
	v_and_b32_e32 v9, 0xffff0000, v9
	v_fma_f32 v19, -v16, v17, 1.0
	v_fmac_f32_e32 v17, v19, v17
	v_div_scale_f32 v19, vcc, 2.0, v13, 2.0
	v_mul_f32_e32 v20, v19, v17
	s_waitcnt lgkmcnt(0)
	v_fma_f32 v21, -v16, v20, v19
	v_fmac_f32_e32 v20, v21, v17
	v_fma_f32 v16, -v16, v20, v19
	v_mul_f32_e32 v19, 0x3d372713, v15
	v_mul_f32_e32 v19, v19, v15
	v_fma_f32 v19, v19, v15, v15
	v_mul_f32_e32 v19, 0x3f4c422a, v19
	v_add_f32_e32 v19, v19, v19
	v_mul_f32_e32 v19, 0x3fb8aa3b, v19
	v_exp_f32_e32 v19, v19
	v_div_fmas_f32 v16, v16, v17, v20
	v_div_fixup_f32 v13, v16, v13, 2.0
	v_and_b32_e32 v11, 0xffff0000, v11
	v_add_f32_e32 v16, 1.0, v19
	v_div_scale_f32 v17, s[0:1], v16, v16, 2.0
	v_rcp_f32_e32 v19, v17
	v_sub_f32_e32 v13, 1.0, v13
	v_mul_f32_e32 v12, 0.5, v12
	v_add_f32_e32 v13, 1.0, v13
	v_fma_f32 v20, -v17, v19, 1.0
	v_fmac_f32_e32 v19, v20, v19
	v_div_scale_f32 v20, vcc, 2.0, v16, 2.0
	v_mul_f32_e32 v21, v20, v19
	v_fma_f32 v22, -v17, v21, v20
	v_fmac_f32_e32 v21, v22, v19
	v_fma_f32 v17, -v17, v21, v20
	v_mul_f32_e32 v20, 0x3d372713, v8
	v_mul_f32_e32 v20, v20, v8
	v_fma_f32 v20, v20, v8, v8
	v_mul_f32_e32 v20, 0x3f4c422a, v20
	v_add_f32_e32 v20, v20, v20
	v_mul_f32_e32 v20, 0x3fb8aa3b, v20
	v_exp_f32_e32 v20, v20
	v_div_fmas_f32 v17, v17, v19, v21
	v_div_fixup_f32 v16, v17, v16, 2.0
	v_mul_f32_e32 v21, 0.5, v15
	v_add_f32_e32 v17, 1.0, v20
	v_div_scale_f32 v19, s[0:1], v17, v17, 2.0
	v_rcp_f32_e32 v20, v19
	v_sub_f32_e32 v16, 1.0, v16
	v_add_f32_e32 v16, 1.0, v16
	v_fma_f32 v15, -v19, v20, 1.0
	v_fmac_f32_e32 v20, v15, v20
	v_div_scale_f32 v15, vcc, 2.0, v17, 2.0
	v_mul_f32_e32 v22, v15, v20
	v_fma_f32 v23, -v19, v22, v15
	v_fmac_f32_e32 v22, v23, v20
	v_fma_f32 v15, -v19, v22, v15
	v_mul_f32_e32 v19, 0x3d372713, v10
	v_mul_f32_e32 v19, v19, v10
	v_fma_f32 v19, v19, v10, v10
	v_mul_f32_e32 v19, 0x3f4c422a, v19
	v_add_f32_e32 v19, v19, v19
	v_mul_f32_e32 v19, 0x3fb8aa3b, v19
	v_exp_f32_e32 v19, v19
	v_div_fmas_f32 v15, v15, v20, v22
	v_div_fixup_f32 v15, v15, v17, 2.0
	v_mul_f32_e32 v22, 0.5, v8
	v_add_f32_e32 v17, 1.0, v19
	v_div_scale_f32 v19, s[0:1], v17, v17, 2.0
	v_rcp_f32_e32 v20, v19
	v_sub_f32_e32 v15, 1.0, v15
	v_add_f32_e32 v23, 1.0, v15
	v_fma_f32 v8, -v19, v20, 1.0
	v_fmac_f32_e32 v20, v8, v20
	v_div_scale_f32 v8, vcc, 2.0, v17, 2.0
	v_mul_f32_e32 v15, v8, v20
	v_fma_f32 v24, -v19, v15, v8
	v_fmac_f32_e32 v15, v24, v20
	v_fma_f32 v8, -v19, v15, v8
	v_mul_f32_e32 v19, 0x3d372713, v14
	v_mul_f32_e32 v19, v19, v14
	v_fma_f32 v19, v19, v14, v14
	v_mul_f32_e32 v19, 0x3f4c422a, v19
	v_add_f32_e32 v19, v19, v19
	v_mul_f32_e32 v19, 0x3fb8aa3b, v19
	v_exp_f32_e32 v19, v19
	v_div_fmas_f32 v8, v8, v20, v15
	v_div_fixup_f32 v8, v8, v17, 2.0
	v_sub_f32_e32 v8, 1.0, v8
	v_add_f32_e32 v15, 1.0, v19
	v_div_scale_f32 v17, s[0:1], v15, v15, 2.0
	v_rcp_f32_e32 v19, v17
	v_add_f32_e32 v24, 1.0, v8
	v_mul_f32_e32 v20, 0.5, v10
	v_fma_f32 v8, -v17, v19, 1.0
	v_fmac_f32_e32 v19, v8, v19
	v_div_scale_f32 v8, vcc, 2.0, v15, 2.0
	v_mul_f32_e32 v10, v8, v19
	v_fma_f32 v25, -v17, v10, v8
	v_fmac_f32_e32 v10, v25, v19
	v_fma_f32 v8, -v17, v10, v8
	v_mul_f32_e32 v17, 0x3d372713, v18
	v_mul_f32_e32 v17, v17, v18
	v_fma_f32 v17, v17, v18, v18
	v_mul_f32_e32 v17, 0x3f4c422a, v17
	v_add_f32_e32 v17, v17, v17
	v_mul_f32_e32 v17, 0x3fb8aa3b, v17
	v_exp_f32_e32 v17, v17
	v_div_fmas_f32 v8, v8, v19, v10
	v_div_fixup_f32 v8, v8, v15, 2.0
	v_sub_f32_e32 v8, 1.0, v8
	v_add_f32_e32 v10, 1.0, v17
	v_div_scale_f32 v15, s[0:1], v10, v10, 2.0
	v_rcp_f32_e32 v17, v15
	v_add_f32_e32 v25, 1.0, v8
	v_mul_f32_e32 v19, 0.5, v14
	v_fma_f32 v8, -v15, v17, 1.0
	v_fmac_f32_e32 v17, v8, v17
	v_div_scale_f32 v8, vcc, 2.0, v10, 2.0
	v_mul_f32_e32 v14, v8, v17
	v_fma_f32 v26, -v15, v14, v8
	v_fmac_f32_e32 v14, v26, v17
	v_fma_f32 v8, -v15, v14, v8
	v_mul_f32_e32 v15, 0x3d372713, v9
	v_mul_f32_e32 v15, v15, v9
	v_fma_f32 v15, v15, v9, v9
	v_mul_f32_e32 v15, 0x3f4c422a, v15
	v_add_f32_e32 v15, v15, v15
	v_mul_f32_e32 v15, 0x3fb8aa3b, v15
	v_exp_f32_e32 v15, v15
	v_div_fmas_f32 v8, v8, v17, v14
	v_div_fixup_f32 v8, v8, v10, 2.0
	v_sub_f32_e32 v8, 1.0, v8
	v_add_f32_e32 v10, 1.0, v15
	v_div_scale_f32 v14, s[0:1], v10, v10, 2.0
	v_rcp_f32_e32 v15, v14
	v_mul_f32_e32 v17, 0.5, v18
	v_add_f32_e32 v18, 1.0, v8
	v_fma_f32 v8, -v14, v15, 1.0
	v_fmac_f32_e32 v15, v8, v15
	v_div_scale_f32 v8, vcc, 2.0, v10, 2.0
	v_mul_f32_e32 v26, v8, v15
	v_fma_f32 v27, -v14, v26, v8
	v_fmac_f32_e32 v26, v27, v15
	v_fma_f32 v8, -v14, v26, v8
	v_mul_f32_e32 v14, 0x3d372713, v11
	v_mul_f32_e32 v14, v14, v11
	v_fma_f32 v14, v14, v11, v11
	v_mul_f32_e32 v14, 0x3f4c422a, v14
	v_add_f32_e32 v14, v14, v14
	v_mul_f32_e32 v14, 0x3fb8aa3b, v14
	v_exp_f32_e32 v14, v14
	v_div_fmas_f32 v8, v8, v15, v26
	v_div_fixup_f32 v8, v8, v10, 2.0
	v_sub_f32_e32 v8, 1.0, v8
	v_add_f32_e32 v10, 1.0, v14
	v_div_scale_f32 v14, s[0:1], v10, v10, 2.0
	v_rcp_f32_e32 v15, v14
	v_add_f32_e32 v27, 1.0, v8
	v_mul_f32_e32 v26, 0.5, v9
	v_fma_f32 v8, -v14, v15, 1.0
	v_fmac_f32_e32 v15, v8, v15
	v_div_scale_f32 v8, vcc, 2.0, v10, 2.0
	v_mul_f32_e32 v9, v8, v15
	v_fma_f32 v28, -v14, v9, v8
	v_fmac_f32_e32 v9, v28, v15
	v_fma_f32 v8, -v14, v9, v8
	v_div_fmas_f32 v8, v8, v15, v9
	v_div_fixup_f32 v8, v8, v10, 2.0
	v_sub_f32_e32 v8, 1.0, v8
	v_add_f32_e32 v29, 1.0, v8
	v_fma_f32 v8, v12, v13, 0
	v_fmac_f32_e32 v8, v22, v23
	v_fmac_f32_e32 v8, v19, v25
	v_fmac_f32_e32 v8, v26, v27
	v_fmac_f32_e32 v8, v21, v16
	v_fmac_f32_e32 v8, v20, v24
	v_mul_f32_e32 v28, 0.5, v11
	v_fmac_f32_e32 v8, v17, v18
	v_fmac_f32_e32 v8, v28, v29
	s_nop 1
	v_add_f32_dpp v8, v8, v8 quad_perm:[1,0,3,2] row_mask:0xf bank_mask:0xf
	s_nop 1
	v_add_f32_dpp v8, v8, v8 quad_perm:[2,3,0,1] row_mask:0xf bank_mask:0xf
	s_nop 1
	v_add_f32_dpp v8, v8, v8 row_half_mirror row_mask:0xf bank_mask:0xf
	s_nop 1
	v_add_f32_dpp v8, v8, v8 row_mirror row_mask:0xf bank_mask:0xf
	s_nop 1
	v_add_f32_dpp v8, v8, v8 row_bcast:15 row_mask:0xa bank_mask:0xf
	s_nop 1
	v_add_f32_dpp v8, v8, v8 row_bcast:31 row_mask:0xc bank_mask:0xf
	s_nop 1
	v_readlane_b32 s98, v8, 63
	s_nop 1
	v_mov_b32_e32 v8, s98
	v_mul_f32_e32 v8, 0xbb000000, v8
	v_fma_f32 v14, v22, v23, v8
	v_fma_f32 v15, v12, v13, v8
	v_mul_f32_e32 v22, v14, v14
	v_fmac_f32_e32 v22, v15, v15
	v_fma_f32 v9, v19, v25, v8
	v_fmac_f32_e32 v22, v9, v9
	v_fma_f32 v10, v26, v27, v8
	v_fmac_f32_e32 v22, v10, v10
	v_fma_f32 v11, v21, v16, v8
	v_fmac_f32_e32 v22, v11, v11
	v_fma_f32 v12, v20, v24, v8
	v_fmac_f32_e32 v22, v12, v12
	v_fma_f32 v13, v17, v18, v8
	v_fmac_f32_e32 v22, v13, v13
	v_fmac_f32_e32 v8, v28, v29
	v_fmac_f32_e32 v22, v8, v8
	s_nop 1
	v_add_f32_dpp v16, v22, v22 quad_perm:[1,0,3,2] row_mask:0xf bank_mask:0xf
	s_nop 1
	v_add_f32_dpp v16, v16, v16 quad_perm:[2,3,0,1] row_mask:0xf bank_mask:0xf
	s_nop 1
	v_add_f32_dpp v16, v16, v16 row_half_mirror row_mask:0xf bank_mask:0xf
	s_nop 1
	v_add_f32_dpp v16, v16, v16 row_mirror row_mask:0xf bank_mask:0xf
	s_nop 1
	v_add_f32_dpp v16, v16, v16 row_bcast:15 row_mask:0xa bank_mask:0xf
	s_nop 1
	v_add_f32_dpp v16, v16, v16 row_bcast:31 row_mask:0xc bank_mask:0xf
	s_nop 1
	v_readlane_b32 s98, v16, 63
	s_nop 1
	v_mov_b32_e32 v16, s98
	v_mov_b32_e32 v17, 0
	s_and_saveexec_b64 s[0:1], s[38:39]
	s_cbranch_execz .LBB0_433
	s_waitcnt lgkmcnt(0)
	v_add_f32_e32 v16, v16, v17
	v_fmamk_f32 v16, v16, 0x3b000000, v189
	v_mul_f32_e32 v17, 0x4b800000, v16
	v_cmp_gt_f32_e32 vcc, s33, v16
	s_nop 1
	v_cndmask_b32_e32 v16, v16, v17, vcc
	v_rsq_f32_e32 v16, v16
	s_nop 0
	v_mul_f32_e32 v17, 0x45800000, v16
	v_cndmask_b32_e32 v16, v16, v17, vcc
	v_mul_f32_e32 v15, v15, v16
	v_mul_f32_e32 v14, v14, v16
	v_mul_f32_e32 v9, v9, v16
	v_cvt_pk_bf16_f32 v15, v15, v65
	ds_write_b16 v61, v15 offset:26
	v_cvt_pk_bf16_f32 v14, v14, v65
	ds_write_b16 v61, v14 offset:298
	v_cvt_pk_bf16_f32 v9, v9, v65
	ds_write_b16 v61, v9 offset:570
	v_mul_f32_e32 v9, v10, v16
	v_cvt_pk_bf16_f32 v9, v9, v65
	ds_write_b16 v61, v9 offset:842
	v_mul_f32_e32 v9, v11, v16
	v_cvt_pk_bf16_f32 v9, v9, v65
	ds_write_b16 v61, v9 offset:1114
	v_mul_f32_e32 v9, v12, v16
	v_cvt_pk_bf16_f32 v9, v9, v65
	ds_write_b16 v61, v9 offset:1386
	v_mul_f32_e32 v9, v13, v16
	v_mul_f32_e32 v8, v8, v16
	v_cvt_pk_bf16_f32 v9, v9, v65
	ds_write_b16 v61, v9 offset:1658
	v_cvt_pk_bf16_f32 v8, v8, v65
	ds_write_b16 v61, v8 offset:1930
.LBB0_433:
	s_or_b64 exec, exec, s[0:1]
	s_waitcnt vmcnt(1)
	v_lshlrev_b32_e32 v8, 16, v4
	v_mul_f32_e32 v9, 0x3d372713, v8
	v_mul_f32_e32 v9, v9, v8
	v_fma_f32 v9, v9, v8, v8
	v_mul_f32_e32 v9, 0x3f4c422a, v9
	v_add_f32_e32 v9, v9, v9
	v_mul_f32_e32 v9, 0x3fb8aa3b, v9
	v_exp_f32_e32 v9, v9
	v_lshlrev_b32_e32 v11, 16, v6
	v_and_b32_e32 v4, 0xffff0000, v4
	v_and_b32_e32 v6, 0xffff0000, v6
	v_add_f32_e32 v9, 1.0, v9
	v_div_scale_f32 v12, s[0:1], v9, v9, 2.0
	v_rcp_f32_e32 v13, v12
	v_lshlrev_b32_e32 v10, 16, v5
	v_lshlrev_b32_e32 v14, 16, v7
	v_and_b32_e32 v5, 0xffff0000, v5
	v_fma_f32 v15, -v12, v13, 1.0
	v_fmac_f32_e32 v13, v15, v13
	v_div_scale_f32 v15, vcc, 2.0, v9, 2.0
	v_mul_f32_e32 v16, v15, v13
	s_waitcnt lgkmcnt(0)
	v_fma_f32 v17, -v12, v16, v15
	v_fmac_f32_e32 v16, v17, v13
	v_fma_f32 v12, -v12, v16, v15
	v_mul_f32_e32 v15, 0x3d372713, v11
	v_mul_f32_e32 v15, v15, v11
	v_fma_f32 v15, v15, v11, v11
	v_mul_f32_e32 v15, 0x3f4c422a, v15
	v_add_f32_e32 v15, v15, v15
	v_mul_f32_e32 v15, 0x3fb8aa3b, v15
	v_exp_f32_e32 v15, v15
	v_div_fmas_f32 v12, v12, v13, v16
	v_div_fixup_f32 v9, v12, v9, 2.0
	v_and_b32_e32 v7, 0xffff0000, v7
	v_add_f32_e32 v12, 1.0, v15
	v_div_scale_f32 v13, s[0:1], v12, v12, 2.0
	v_rcp_f32_e32 v15, v13
	v_sub_f32_e32 v9, 1.0, v9
	v_mul_f32_e32 v8, 0.5, v8
	v_add_f32_e32 v9, 1.0, v9
	v_fma_f32 v16, -v13, v15, 1.0
	v_fmac_f32_e32 v15, v16, v15
	v_div_scale_f32 v16, vcc, 2.0, v12, 2.0
	v_mul_f32_e32 v17, v16, v15
	v_fma_f32 v18, -v13, v17, v16
	v_fmac_f32_e32 v17, v18, v15
	v_fma_f32 v13, -v13, v17, v16
	v_mul_f32_e32 v16, 0x3d372713, v4
	v_mul_f32_e32 v16, v16, v4
	v_fma_f32 v16, v16, v4, v4
	v_mul_f32_e32 v16, 0x3f4c422a, v16
	v_add_f32_e32 v16, v16, v16
	v_mul_f32_e32 v16, 0x3fb8aa3b, v16
	v_exp_f32_e32 v16, v16
	v_div_fmas_f32 v13, v13, v15, v17
	v_div_fixup_f32 v12, v13, v12, 2.0
	v_mul_f32_e32 v17, 0.5, v11
	v_add_f32_e32 v13, 1.0, v16
	v_div_scale_f32 v15, s[0:1], v13, v13, 2.0
	v_rcp_f32_e32 v16, v15
	v_sub_f32_e32 v12, 1.0, v12
	v_add_f32_e32 v12, 1.0, v12
	v_fma_f32 v11, -v15, v16, 1.0
	v_fmac_f32_e32 v16, v11, v16
	v_div_scale_f32 v11, vcc, 2.0, v13, 2.0
	v_mul_f32_e32 v18, v11, v16
	v_fma_f32 v19, -v15, v18, v11
	v_fmac_f32_e32 v18, v19, v16
	v_fma_f32 v11, -v15, v18, v11
	v_mul_f32_e32 v15, 0x3d372713, v6
	v_mul_f32_e32 v15, v15, v6
	v_fma_f32 v15, v15, v6, v6
	v_mul_f32_e32 v15, 0x3f4c422a, v15
	v_add_f32_e32 v15, v15, v15
	v_mul_f32_e32 v15, 0x3fb8aa3b, v15
	v_exp_f32_e32 v15, v15
	v_div_fmas_f32 v11, v11, v16, v18
	v_div_fixup_f32 v11, v11, v13, 2.0
	v_mul_f32_e32 v18, 0.5, v4
	v_add_f32_e32 v13, 1.0, v15
	v_div_scale_f32 v15, s[0:1], v13, v13, 2.0
	v_rcp_f32_e32 v16, v15
	v_sub_f32_e32 v11, 1.0, v11
	v_add_f32_e32 v19, 1.0, v11
	v_fma_f32 v4, -v15, v16, 1.0
	v_fmac_f32_e32 v16, v4, v16
	v_div_scale_f32 v4, vcc, 2.0, v13, 2.0
	v_mul_f32_e32 v11, v4, v16
	v_fma_f32 v20, -v15, v11, v4
	v_fmac_f32_e32 v11, v20, v16
	v_fma_f32 v4, -v15, v11, v4
	v_mul_f32_e32 v15, 0x3d372713, v10
	v_mul_f32_e32 v15, v15, v10
	v_fma_f32 v15, v15, v10, v10
	v_mul_f32_e32 v15, 0x3f4c422a, v15
	v_add_f32_e32 v15, v15, v15
	v_mul_f32_e32 v15, 0x3fb8aa3b, v15
	v_exp_f32_e32 v15, v15
	v_div_fmas_f32 v4, v4, v16, v11
	v_div_fixup_f32 v4, v4, v13, 2.0
	v_sub_f32_e32 v4, 1.0, v4
	v_add_f32_e32 v11, 1.0, v15
	v_div_scale_f32 v13, s[0:1], v11, v11, 2.0
	v_rcp_f32_e32 v15, v13
	v_add_f32_e32 v20, 1.0, v4
	v_mul_f32_e32 v16, 0.5, v6
	v_fma_f32 v4, -v13, v15, 1.0
	v_fmac_f32_e32 v15, v4, v15
	v_div_scale_f32 v4, vcc, 2.0, v11, 2.0
	v_mul_f32_e32 v6, v4, v15
	v_fma_f32 v21, -v13, v6, v4
	v_fmac_f32_e32 v6, v21, v15
	v_fma_f32 v4, -v13, v6, v4
	v_mul_f32_e32 v13, 0x3d372713, v14
	v_mul_f32_e32 v13, v13, v14
	v_fma_f32 v13, v13, v14, v14
	v_mul_f32_e32 v13, 0x3f4c422a, v13
	v_add_f32_e32 v13, v13, v13
	v_mul_f32_e32 v13, 0x3fb8aa3b, v13
	v_exp_f32_e32 v13, v13
	v_div_fmas_f32 v4, v4, v15, v6
	v_div_fixup_f32 v4, v4, v11, 2.0
	v_sub_f32_e32 v4, 1.0, v4
	v_add_f32_e32 v6, 1.0, v13
	v_div_scale_f32 v11, s[0:1], v6, v6, 2.0
	v_rcp_f32_e32 v13, v11
	v_add_f32_e32 v21, 1.0, v4
	v_mul_f32_e32 v15, 0.5, v10
	v_fma_f32 v4, -v11, v13, 1.0
	v_fmac_f32_e32 v13, v4, v13
	v_div_scale_f32 v4, vcc, 2.0, v6, 2.0
	v_mul_f32_e32 v10, v4, v13
	v_fma_f32 v22, -v11, v10, v4
	v_fmac_f32_e32 v10, v22, v13
	v_fma_f32 v4, -v11, v10, v4
	v_mul_f32_e32 v11, 0x3d372713, v5
	v_mul_f32_e32 v11, v11, v5
	v_fma_f32 v11, v11, v5, v5
	v_mul_f32_e32 v11, 0x3f4c422a, v11
	v_add_f32_e32 v11, v11, v11
	v_mul_f32_e32 v11, 0x3fb8aa3b, v11
	v_exp_f32_e32 v11, v11
	v_div_fmas_f32 v4, v4, v13, v10
	v_div_fixup_f32 v4, v4, v6, 2.0
	v_sub_f32_e32 v4, 1.0, v4
	v_add_f32_e32 v6, 1.0, v11
	v_div_scale_f32 v10, s[0:1], v6, v6, 2.0
	v_rcp_f32_e32 v11, v10
	v_mul_f32_e32 v13, 0.5, v14
	v_add_f32_e32 v14, 1.0, v4
	v_fma_f32 v4, -v10, v11, 1.0
	v_fmac_f32_e32 v11, v4, v11
	v_div_scale_f32 v4, vcc, 2.0, v6, 2.0
	v_mul_f32_e32 v22, v4, v11
	v_fma_f32 v23, -v10, v22, v4
	v_fmac_f32_e32 v22, v23, v11
	v_fma_f32 v4, -v10, v22, v4
	v_mul_f32_e32 v10, 0x3d372713, v7
	v_mul_f32_e32 v10, v10, v7
	v_fma_f32 v10, v10, v7, v7
	v_mul_f32_e32 v10, 0x3f4c422a, v10
	v_add_f32_e32 v10, v10, v10
	v_mul_f32_e32 v10, 0x3fb8aa3b, v10
	v_exp_f32_e32 v10, v10
	v_div_fmas_f32 v4, v4, v11, v22
	v_div_fixup_f32 v4, v4, v6, 2.0
	v_sub_f32_e32 v4, 1.0, v4
	v_add_f32_e32 v6, 1.0, v10
	v_div_scale_f32 v10, s[0:1], v6, v6, 2.0
	v_rcp_f32_e32 v11, v10
	v_add_f32_e32 v23, 1.0, v4
	v_mul_f32_e32 v22, 0.5, v5
	v_fma_f32 v4, -v10, v11, 1.0
	v_fmac_f32_e32 v11, v4, v11
	v_div_scale_f32 v4, vcc, 2.0, v6, 2.0
	v_mul_f32_e32 v5, v4, v11
	v_fma_f32 v24, -v10, v5, v4
	v_fmac_f32_e32 v5, v24, v11
	v_fma_f32 v4, -v10, v5, v4
	v_div_fmas_f32 v4, v4, v11, v5
	v_div_fixup_f32 v4, v4, v6, 2.0
	v_sub_f32_e32 v4, 1.0, v4
	v_add_f32_e32 v25, 1.0, v4
	v_fma_f32 v4, v8, v9, 0
	v_fmac_f32_e32 v4, v18, v19
	v_fmac_f32_e32 v4, v15, v21
	v_fmac_f32_e32 v4, v22, v23
	v_fmac_f32_e32 v4, v17, v12
	v_fmac_f32_e32 v4, v16, v20
	v_mul_f32_e32 v24, 0.5, v7
	v_fmac_f32_e32 v4, v13, v14
	v_fmac_f32_e32 v4, v24, v25
	s_nop 1
	v_add_f32_dpp v4, v4, v4 quad_perm:[1,0,3,2] row_mask:0xf bank_mask:0xf
	s_nop 1
	v_add_f32_dpp v4, v4, v4 quad_perm:[2,3,0,1] row_mask:0xf bank_mask:0xf
	s_nop 1
	v_add_f32_dpp v4, v4, v4 row_half_mirror row_mask:0xf bank_mask:0xf
	s_nop 1
	v_add_f32_dpp v4, v4, v4 row_mirror row_mask:0xf bank_mask:0xf
	s_nop 1
	v_add_f32_dpp v4, v4, v4 row_bcast:15 row_mask:0xa bank_mask:0xf
	s_nop 1
	v_add_f32_dpp v4, v4, v4 row_bcast:31 row_mask:0xc bank_mask:0xf
	s_nop 1
	v_readlane_b32 s98, v4, 63
	s_nop 1
	v_mov_b32_e32 v4, s98
	v_mul_f32_e32 v4, 0xbb000000, v4
	v_fma_f32 v10, v18, v19, v4
	v_fma_f32 v11, v8, v9, v4
	v_mul_f32_e32 v18, v10, v10
	v_fmac_f32_e32 v18, v11, v11
	v_fma_f32 v5, v15, v21, v4
	v_fmac_f32_e32 v18, v5, v5
	v_fma_f32 v6, v22, v23, v4
	v_fmac_f32_e32 v18, v6, v6
	v_fma_f32 v7, v17, v12, v4
	v_fmac_f32_e32 v18, v7, v7
	v_fma_f32 v8, v16, v20, v4
	v_fmac_f32_e32 v18, v8, v8
	v_fma_f32 v9, v13, v14, v4
	v_fmac_f32_e32 v18, v9, v9
	v_fmac_f32_e32 v4, v24, v25
	v_fmac_f32_e32 v18, v4, v4
	s_nop 1
	v_add_f32_dpp v12, v18, v18 quad_perm:[1,0,3,2] row_mask:0xf bank_mask:0xf
	s_nop 1
	v_add_f32_dpp v12, v12, v12 quad_perm:[2,3,0,1] row_mask:0xf bank_mask:0xf
	s_nop 1
	v_add_f32_dpp v12, v12, v12 row_half_mirror row_mask:0xf bank_mask:0xf
	s_nop 1
	v_add_f32_dpp v12, v12, v12 row_mirror row_mask:0xf bank_mask:0xf
	s_nop 1
	v_add_f32_dpp v12, v12, v12 row_bcast:15 row_mask:0xa bank_mask:0xf
	s_nop 1
	v_add_f32_dpp v12, v12, v12 row_bcast:31 row_mask:0xc bank_mask:0xf
	s_nop 1
	v_readlane_b32 s98, v12, 63
	s_nop 1
	v_mov_b32_e32 v12, s98
	v_mov_b32_e32 v13, 0
	s_and_saveexec_b64 s[0:1], s[38:39]
	s_cbranch_execz .LBB0_435
	s_waitcnt lgkmcnt(0)
	v_add_f32_e32 v12, v12, v13
	v_fmamk_f32 v12, v12, 0x3b000000, v189
	v_mul_f32_e32 v13, 0x4b800000, v12
	v_cmp_gt_f32_e32 vcc, s33, v12
	s_nop 1
	v_cndmask_b32_e32 v12, v12, v13, vcc
	v_rsq_f32_e32 v12, v12
	s_nop 0
	v_mul_f32_e32 v13, 0x45800000, v12
	v_cndmask_b32_e32 v12, v12, v13, vcc
	v_mul_f32_e32 v11, v11, v12
	v_mul_f32_e32 v10, v10, v12
	v_mul_f32_e32 v5, v5, v12
	v_cvt_pk_bf16_f32 v11, v11, v65
	ds_write_b16 v61, v11 offset:28
	v_cvt_pk_bf16_f32 v10, v10, v65
	ds_write_b16 v61, v10 offset:300
	v_cvt_pk_bf16_f32 v5, v5, v65
	ds_write_b16 v61, v5 offset:572
	v_mul_f32_e32 v5, v6, v12
	v_cvt_pk_bf16_f32 v5, v5, v65
	ds_write_b16 v61, v5 offset:844
	v_mul_f32_e32 v5, v7, v12
	v_cvt_pk_bf16_f32 v5, v5, v65
	ds_write_b16 v61, v5 offset:1116
	v_mul_f32_e32 v5, v8, v12
	v_cvt_pk_bf16_f32 v5, v5, v65
	ds_write_b16 v61, v5 offset:1388
	v_mul_f32_e32 v5, v9, v12
	v_mul_f32_e32 v4, v4, v12
	v_cvt_pk_bf16_f32 v5, v5, v65
	ds_write_b16 v61, v5 offset:1660
	v_cvt_pk_bf16_f32 v4, v4, v65
	ds_write_b16 v61, v4 offset:1932
.LBB0_435:
	s_or_b64 exec, exec, s[0:1]
	s_waitcnt vmcnt(0)
	v_lshlrev_b32_e32 v4, 16, v0
	v_mul_f32_e32 v5, 0x3d372713, v4
	v_mul_f32_e32 v5, v5, v4
	v_fma_f32 v5, v5, v4, v4
	v_mul_f32_e32 v5, 0x3f4c422a, v5
	v_add_f32_e32 v5, v5, v5
	v_mul_f32_e32 v5, 0x3fb8aa3b, v5
	v_exp_f32_e32 v5, v5
	v_lshlrev_b32_e32 v7, 16, v2
	v_and_b32_e32 v0, 0xffff0000, v0
	v_and_b32_e32 v2, 0xffff0000, v2
	v_add_f32_e32 v5, 1.0, v5
	v_div_scale_f32 v8, s[0:1], v5, v5, 2.0
	v_rcp_f32_e32 v9, v8
	v_lshlrev_b32_e32 v6, 16, v1
	v_lshlrev_b32_e32 v10, 16, v3
	v_and_b32_e32 v1, 0xffff0000, v1
	v_fma_f32 v11, -v8, v9, 1.0
	v_fmac_f32_e32 v9, v11, v9
	v_div_scale_f32 v11, vcc, 2.0, v5, 2.0
	v_mul_f32_e32 v12, v11, v9
	s_waitcnt lgkmcnt(0)
	v_fma_f32 v13, -v8, v12, v11
	v_fmac_f32_e32 v12, v13, v9
	v_fma_f32 v8, -v8, v12, v11
	v_mul_f32_e32 v11, 0x3d372713, v7
	v_mul_f32_e32 v11, v11, v7
	v_fma_f32 v11, v11, v7, v7
	v_mul_f32_e32 v11, 0x3f4c422a, v11
	v_add_f32_e32 v11, v11, v11
	v_mul_f32_e32 v11, 0x3fb8aa3b, v11
	v_exp_f32_e32 v11, v11
	v_div_fmas_f32 v8, v8, v9, v12
	v_div_fixup_f32 v5, v8, v5, 2.0
	v_and_b32_e32 v3, 0xffff0000, v3
	v_add_f32_e32 v8, 1.0, v11
	v_div_scale_f32 v9, s[0:1], v8, v8, 2.0
	v_rcp_f32_e32 v11, v9
	v_sub_f32_e32 v5, 1.0, v5
	v_mul_f32_e32 v4, 0.5, v4
	v_add_f32_e32 v5, 1.0, v5
	v_fma_f32 v12, -v9, v11, 1.0
	v_fmac_f32_e32 v11, v12, v11
	v_div_scale_f32 v12, vcc, 2.0, v8, 2.0
	v_mul_f32_e32 v13, v12, v11
	v_fma_f32 v14, -v9, v13, v12
	v_fmac_f32_e32 v13, v14, v11
	v_fma_f32 v9, -v9, v13, v12
	v_mul_f32_e32 v12, 0x3d372713, v0
	v_mul_f32_e32 v12, v12, v0
	v_fma_f32 v12, v12, v0, v0
	v_mul_f32_e32 v12, 0x3f4c422a, v12
	v_add_f32_e32 v12, v12, v12
	v_mul_f32_e32 v12, 0x3fb8aa3b, v12
	v_exp_f32_e32 v12, v12
	v_div_fmas_f32 v9, v9, v11, v13
	v_div_fixup_f32 v8, v9, v8, 2.0
	v_mul_f32_e32 v13, 0.5, v7
	v_add_f32_e32 v9, 1.0, v12
	v_div_scale_f32 v11, s[0:1], v9, v9, 2.0
	v_rcp_f32_e32 v12, v11
	v_sub_f32_e32 v8, 1.0, v8
	v_add_f32_e32 v8, 1.0, v8
	v_fma_f32 v7, -v11, v12, 1.0
	v_fmac_f32_e32 v12, v7, v12
	v_div_scale_f32 v7, vcc, 2.0, v9, 2.0
	v_mul_f32_e32 v14, v7, v12
	v_fma_f32 v15, -v11, v14, v7
	v_fmac_f32_e32 v14, v15, v12
	v_fma_f32 v7, -v11, v14, v7
	v_mul_f32_e32 v11, 0x3d372713, v2
	v_mul_f32_e32 v11, v11, v2
	v_fma_f32 v11, v11, v2, v2
	v_mul_f32_e32 v11, 0x3f4c422a, v11
	v_add_f32_e32 v11, v11, v11
	v_mul_f32_e32 v11, 0x3fb8aa3b, v11
	v_exp_f32_e32 v11, v11
	v_div_fmas_f32 v7, v7, v12, v14
	v_div_fixup_f32 v7, v7, v9, 2.0
	v_mul_f32_e32 v14, 0.5, v0
	v_add_f32_e32 v9, 1.0, v11
	v_div_scale_f32 v11, s[0:1], v9, v9, 2.0
	v_rcp_f32_e32 v12, v11
	v_sub_f32_e32 v7, 1.0, v7
	v_add_f32_e32 v15, 1.0, v7
	v_fma_f32 v0, -v11, v12, 1.0
	v_fmac_f32_e32 v12, v0, v12
	v_div_scale_f32 v0, vcc, 2.0, v9, 2.0
	v_mul_f32_e32 v7, v0, v12
	v_fma_f32 v16, -v11, v7, v0
	v_fmac_f32_e32 v7, v16, v12
	v_fma_f32 v0, -v11, v7, v0
	v_mul_f32_e32 v11, 0x3d372713, v6
	v_mul_f32_e32 v11, v11, v6
	v_fma_f32 v11, v11, v6, v6
	v_mul_f32_e32 v11, 0x3f4c422a, v11
	v_add_f32_e32 v11, v11, v11
	v_mul_f32_e32 v11, 0x3fb8aa3b, v11
	v_exp_f32_e32 v11, v11
	v_div_fmas_f32 v0, v0, v12, v7
	v_div_fixup_f32 v0, v0, v9, 2.0
	v_sub_f32_e32 v0, 1.0, v0
	v_add_f32_e32 v7, 1.0, v11
	v_div_scale_f32 v9, s[0:1], v7, v7, 2.0
	v_rcp_f32_e32 v11, v9
	v_add_f32_e32 v16, 1.0, v0
	v_mul_f32_e32 v12, 0.5, v2
	v_fma_f32 v0, -v9, v11, 1.0
	v_fmac_f32_e32 v11, v0, v11
	v_div_scale_f32 v0, vcc, 2.0, v7, 2.0
	v_mul_f32_e32 v2, v0, v11
	v_fma_f32 v17, -v9, v2, v0
	v_fmac_f32_e32 v2, v17, v11
	v_fma_f32 v0, -v9, v2, v0
	v_mul_f32_e32 v9, 0x3d372713, v10
	v_mul_f32_e32 v9, v9, v10
	v_fma_f32 v9, v9, v10, v10
	v_mul_f32_e32 v9, 0x3f4c422a, v9
	v_add_f32_e32 v9, v9, v9
	v_mul_f32_e32 v9, 0x3fb8aa3b, v9
	v_exp_f32_e32 v9, v9
	v_div_fmas_f32 v0, v0, v11, v2
	v_div_fixup_f32 v0, v0, v7, 2.0
	v_sub_f32_e32 v0, 1.0, v0
	v_add_f32_e32 v2, 1.0, v9
	v_div_scale_f32 v7, s[0:1], v2, v2, 2.0
	v_rcp_f32_e32 v9, v7
	v_add_f32_e32 v17, 1.0, v0
	v_mul_f32_e32 v11, 0.5, v6
	v_fma_f32 v0, -v7, v9, 1.0
	v_fmac_f32_e32 v9, v0, v9
	v_div_scale_f32 v0, vcc, 2.0, v2, 2.0
	v_mul_f32_e32 v6, v0, v9
	v_fma_f32 v18, -v7, v6, v0
	v_fmac_f32_e32 v6, v18, v9
	v_fma_f32 v0, -v7, v6, v0
	v_mul_f32_e32 v7, 0x3d372713, v1
	v_mul_f32_e32 v7, v7, v1
	v_fma_f32 v7, v7, v1, v1
	v_mul_f32_e32 v7, 0x3f4c422a, v7
	v_add_f32_e32 v7, v7, v7
	v_mul_f32_e32 v7, 0x3fb8aa3b, v7
	v_exp_f32_e32 v7, v7
	v_div_fmas_f32 v0, v0, v9, v6
	v_div_fixup_f32 v0, v0, v2, 2.0
	v_sub_f32_e32 v0, 1.0, v0
	v_add_f32_e32 v2, 1.0, v7
	v_div_scale_f32 v6, s[0:1], v2, v2, 2.0
	v_rcp_f32_e32 v7, v6
	v_mul_f32_e32 v9, 0.5, v10
	v_add_f32_e32 v10, 1.0, v0
	v_fma_f32 v0, -v6, v7, 1.0
	v_fmac_f32_e32 v7, v0, v7
	v_div_scale_f32 v0, vcc, 2.0, v2, 2.0
	v_mul_f32_e32 v18, v0, v7
	v_fma_f32 v19, -v6, v18, v0
	v_fmac_f32_e32 v18, v19, v7
	v_fma_f32 v0, -v6, v18, v0
	v_mul_f32_e32 v6, 0x3d372713, v3
	v_mul_f32_e32 v6, v6, v3
	v_fma_f32 v6, v6, v3, v3
	v_mul_f32_e32 v6, 0x3f4c422a, v6
	v_add_f32_e32 v6, v6, v6
	v_mul_f32_e32 v6, 0x3fb8aa3b, v6
	v_exp_f32_e32 v6, v6
	v_div_fmas_f32 v0, v0, v7, v18
	v_div_fixup_f32 v0, v0, v2, 2.0
	v_sub_f32_e32 v0, 1.0, v0
	v_add_f32_e32 v2, 1.0, v6
	v_div_scale_f32 v6, s[0:1], v2, v2, 2.0
	v_rcp_f32_e32 v7, v6
	v_add_f32_e32 v19, 1.0, v0
	v_mul_f32_e32 v18, 0.5, v1
	v_fma_f32 v0, -v6, v7, 1.0
	v_fmac_f32_e32 v7, v0, v7
	v_div_scale_f32 v0, vcc, 2.0, v2, 2.0
	v_mul_f32_e32 v1, v0, v7
	v_fma_f32 v20, -v6, v1, v0
	v_fmac_f32_e32 v1, v20, v7
	v_fma_f32 v0, -v6, v1, v0
	v_div_fmas_f32 v0, v0, v7, v1
	v_div_fixup_f32 v0, v0, v2, 2.0
	v_sub_f32_e32 v0, 1.0, v0
	v_add_f32_e32 v21, 1.0, v0
	v_fma_f32 v0, v4, v5, 0
	v_fmac_f32_e32 v0, v14, v15
	v_fmac_f32_e32 v0, v11, v17
	v_fmac_f32_e32 v0, v18, v19
	v_fmac_f32_e32 v0, v13, v8
	v_fmac_f32_e32 v0, v12, v16
	v_mul_f32_e32 v20, 0.5, v3
	v_fmac_f32_e32 v0, v9, v10
	v_fmac_f32_e32 v0, v20, v21
	s_nop 1
	v_add_f32_dpp v0, v0, v0 quad_perm:[1,0,3,2] row_mask:0xf bank_mask:0xf
	s_nop 1
	v_add_f32_dpp v0, v0, v0 quad_perm:[2,3,0,1] row_mask:0xf bank_mask:0xf
	s_nop 1
	v_add_f32_dpp v0, v0, v0 row_half_mirror row_mask:0xf bank_mask:0xf
	s_nop 1
	v_add_f32_dpp v0, v0, v0 row_mirror row_mask:0xf bank_mask:0xf
	s_nop 1
	v_add_f32_dpp v0, v0, v0 row_bcast:15 row_mask:0xa bank_mask:0xf
	s_nop 1
	v_add_f32_dpp v0, v0, v0 row_bcast:31 row_mask:0xc bank_mask:0xf
	s_nop 1
	v_readlane_b32 s98, v0, 63
	s_nop 1
	v_mov_b32_e32 v0, s98
	v_mul_f32_e32 v0, 0xbb000000, v0
	v_fma_f32 v6, v14, v15, v0
	v_fma_f32 v7, v4, v5, v0
	v_mul_f32_e32 v14, v6, v6
	v_fmac_f32_e32 v14, v7, v7
	v_fma_f32 v1, v11, v17, v0
	v_fmac_f32_e32 v14, v1, v1
	v_fma_f32 v2, v18, v19, v0
	v_fmac_f32_e32 v14, v2, v2
	v_fma_f32 v3, v13, v8, v0
	v_fmac_f32_e32 v14, v3, v3
	v_fma_f32 v4, v12, v16, v0
	v_fmac_f32_e32 v14, v4, v4
	v_fma_f32 v5, v9, v10, v0
	v_fmac_f32_e32 v14, v5, v5
	v_fmac_f32_e32 v0, v20, v21
	v_fmac_f32_e32 v14, v0, v0
	s_nop 1
	v_add_f32_dpp v8, v14, v14 quad_perm:[1,0,3,2] row_mask:0xf bank_mask:0xf
	s_nop 1
	v_add_f32_dpp v8, v8, v8 quad_perm:[2,3,0,1] row_mask:0xf bank_mask:0xf
	s_nop 1
	v_add_f32_dpp v8, v8, v8 row_half_mirror row_mask:0xf bank_mask:0xf
	s_nop 1
	v_add_f32_dpp v8, v8, v8 row_mirror row_mask:0xf bank_mask:0xf
	s_nop 1
	v_add_f32_dpp v8, v8, v8 row_bcast:15 row_mask:0xa bank_mask:0xf
	s_nop 1
	v_add_f32_dpp v8, v8, v8 row_bcast:31 row_mask:0xc bank_mask:0xf
	s_nop 1
	v_readlane_b32 s98, v8, 63
	s_nop 1
	v_mov_b32_e32 v8, s98
	v_mov_b32_e32 v9, 0
	s_and_saveexec_b64 s[0:1], s[38:39]
	s_cbranch_execz .LBB0_437
	s_waitcnt lgkmcnt(0)
	v_add_f32_e32 v8, v8, v9
	v_fmamk_f32 v8, v8, 0x3b000000, v189
	v_mul_f32_e32 v9, 0x4b800000, v8
	v_cmp_gt_f32_e32 vcc, s33, v8
	s_nop 1
	v_cndmask_b32_e32 v8, v8, v9, vcc
	v_rsq_f32_e32 v8, v8
	s_nop 0
	v_mul_f32_e32 v9, 0x45800000, v8
	v_cndmask_b32_e32 v8, v8, v9, vcc
	v_mul_f32_e32 v7, v7, v8
	v_mul_f32_e32 v6, v6, v8
	v_mul_f32_e32 v1, v1, v8
	v_cvt_pk_bf16_f32 v7, v7, v65
	ds_write_b16 v61, v7 offset:30
	v_cvt_pk_bf16_f32 v6, v6, v65
	ds_write_b16 v61, v6 offset:302
	v_cvt_pk_bf16_f32 v1, v1, v65
	ds_write_b16 v61, v1 offset:574
	v_mul_f32_e32 v1, v2, v8
	v_cvt_pk_bf16_f32 v1, v1, v65
	ds_write_b16 v61, v1 offset:846
	v_mul_f32_e32 v1, v3, v8
	v_cvt_pk_bf16_f32 v1, v1, v65
	ds_write_b16 v61, v1 offset:1118
	v_mul_f32_e32 v1, v4, v8
	v_cvt_pk_bf16_f32 v1, v1, v65
	ds_write_b16 v61, v1 offset:1390
	v_mul_f32_e32 v1, v5, v8
	v_mul_f32_e32 v0, v0, v8
	v_cvt_pk_bf16_f32 v1, v1, v65
	ds_write_b16 v61, v1 offset:1662
	v_cvt_pk_bf16_f32 v0, v0, v65
	ds_write_b16 v61, v0 offset:1934

.LBB0_439:
	global_load_dwordx4 v[6:9], v[0:1], off offset:-48
	global_load_dwordx4 v[10:13], v[0:1], off offset:-64
	global_load_dwordx4 v[224:227], v[0:1], off offset:16
	global_load_dwordx4 v[228:231], v[0:1], off
	v_add_u32_e32 v14, -16, v5
	v_cmp_le_i32_e64 s[0:1], v14, v2
	v_add_u32_e32 v4, -2, v4
	s_waitcnt vmcnt(2)
	v_cndmask_b32_e64 v10, 0, v10, s[0:1]
	v_cmp_lt_i32_e64 s[0:1], v14, v2
	v_add_u32_e32 v14, -14, v5
	s_nop 0
	v_cndmask_b32_e64 v11, 0, v11, s[0:1]
	v_cmp_le_i32_e64 s[0:1], v14, v2
	v_add_u32_e32 v14, -13, v5
	s_nop 0
	v_cndmask_b32_e64 v12, 0, v12, s[0:1]
	v_cmp_le_i32_e64 s[0:1], v14, v2
	v_add_u32_e32 v14, -12, v5
	s_nop 0
	v_cndmask_b32_e64 v13, 0, v13, s[0:1]
	v_cmp_le_i32_e64 s[0:1], v14, v2
	s_nop 1
	v_cndmask_b32_e64 v14, 0, v6, s[0:1]
	v_add_u32_e32 v6, -11, v5
	v_cmp_le_i32_e64 s[0:1], v6, v2
	v_add_u32_e32 v6, -10, v5
	s_nop 0
	v_cndmask_b32_e64 v15, 0, v7, s[0:1]
	v_cmp_le_i32_e64 s[0:1], v6, v2
	v_add_u32_e32 v6, -9, v5
	s_nop 0
	v_cndmask_b32_e64 v16, 0, v8, s[0:1]
	v_cmp_le_i32_e64 s[0:1], v6, v2
	v_cvt_pk_bf16_f32 v6, v10, v11
	v_cvt_pk_bf16_f32 v7, v12, v13
	v_cvt_pk_bf16_f32 v8, v14, v15
	v_add_u32_e32 v14, 2, v5
	s_nop 0
	v_cndmask_b32_e64 v9, 0, v9, s[0:1]
	v_cvt_pk_bf16_f32 v9, v16, v9
	ds_read_b128 v[10:13], v3
	v_cmp_le_i32_e64 s[0:1], v5, v2
	s_waitcnt lgkmcnt(0)
	v_mfma_f32_32x32x16_bf16 v[48:63], v[6:9], v[10:13], v[48:63]
	ds_read_b128 v[10:13], v3 offset:8704
	s_waitcnt lgkmcnt(0)
	v_mfma_f32_32x32x16_bf16 v[32:47], v[6:9], v[10:13], v[32:47]

	v_lshl_add_u64 v[0:1], v[0:1], 0, s[94:95]
	s_waitcnt vmcnt(0)
	v_mov_b32_e32 v6, v224
	v_mov_b32_e32 v7, v225
	v_mov_b32_e32 v8, v226
	v_mov_b32_e32 v9, v227
	v_mov_b32_e32 v10, v228
	v_mov_b32_e32 v11, v229
	v_mov_b32_e32 v12, v230
	v_mov_b32_e32 v13, v231
	v_cndmask_b32_e64 v10, 0, v10, s[0:1]
	v_cmp_lt_i32_e64 s[0:1], v5, v2
	s_nop 1
	v_cndmask_b32_e64 v11, 0, v11, s[0:1]
	v_cmp_le_i32_e64 s[0:1], v14, v2
	v_add_u32_e32 v14, 3, v5
	s_nop 0
	v_cndmask_b32_e64 v12, 0, v12, s[0:1]
	v_cmp_le_i32_e64 s[0:1], v14, v2
	v_add_u32_e32 v14, 4, v5
	s_nop 0
	v_cndmask_b32_e64 v13, 0, v13, s[0:1]
	v_cmp_le_i32_e64 s[0:1], v14, v2
	s_nop 1
	v_cndmask_b32_e64 v14, 0, v6, s[0:1]
	v_add_u32_e32 v6, 5, v5
	v_cmp_le_i32_e64 s[0:1], v6, v2
	v_add_u32_e32 v6, 6, v5
	s_nop 0
	v_cndmask_b32_e64 v15, 0, v7, s[0:1]
	v_cmp_le_i32_e64 s[0:1], v6, v2
	v_add_u32_e32 v6, 7, v5
	v_add_u32_e32 v5, 32, v5
	v_cndmask_b32_e64 v16, 0, v8, s[0:1]
	v_cmp_le_i32_e64 s[0:1], v6, v2
	v_cvt_pk_bf16_f32 v6, v10, v11
	v_cvt_pk_bf16_f32 v7, v12, v13
	v_cvt_pk_bf16_f32 v8, v14, v15
	s_nop 1
	v_cndmask_b32_e64 v9, 0, v9, s[0:1]
	v_cvt_pk_bf16_f32 v9, v16, v9
	ds_read_b128 v[10:13], v3 offset:32
	v_cmp_eq_u32_e64 s[0:1], 0, v4
	s_waitcnt lgkmcnt(0)
	v_mfma_f32_32x32x16_bf16 v[48:63], v[6:9], v[10:13], v[48:63]
	ds_read_b128 v[10:13], v3 offset:8736
	v_add_u32_e32 v3, 64, v3
	s_or_b64 s[28:29], s[0:1], s[28:29]
	s_waitcnt lgkmcnt(0)
	v_mfma_f32_32x32x16_bf16 v[32:47], v[6:9], v[10:13], v[32:47]
	s_andn2_b64 exec, exec, s[28:29]
	s_cbranch_execnz .LBB0_439
	s_or_b64 exec, exec, s[28:29]

.LBB0_443:
	global_load_dwordx4 v[76:79], v[66:67], off offset:-48
	global_load_dwordx4 v[84:87], v[66:67], off offset:-64
	global_load_dwordx4 v[232:235], v[66:67], off offset:16
	global_load_dwordx4 v[236:239], v[66:67], off
	v_add_u32_e32 v64, -16, v72
	v_cmp_le_i32_e32 vcc, v64, v73
	v_add_u32_e32 v80, -14, v72
	v_add_u32_e32 v81, -13, v72
	v_add_u32_e32 v83, -12, v72
	s_add_i32 s2, s2, 2
	s_waitcnt vmcnt(2)
	v_cndmask_b32_e32 v75, 0, v84, vcc
	v_cmp_lt_i32_e32 vcc, v64, v73
	s_nop 1
	v_cndmask_b32_e32 v64, 0, v85, vcc
	v_cmp_le_i32_e32 vcc, v80, v73
	s_nop 1
	v_cndmask_b32_e32 v80, 0, v86, vcc
	v_cmp_le_i32_e32 vcc, v81, v73
	s_nop 1
	v_cndmask_b32_e32 v81, 0, v87, vcc
	v_cmp_le_i32_e32 vcc, v83, v73
	s_nop 1
	v_cndmask_b32_e32 v83, 0, v76, vcc
	v_add_u32_e32 v76, -11, v72
	v_cmp_le_i32_e32 vcc, v76, v73
	v_add_u32_e32 v76, -10, v72
	s_nop 0
	v_cndmask_b32_e32 v84, 0, v77, vcc
	v_cmp_le_i32_e32 vcc, v76, v73
	v_add_u32_e32 v76, -9, v72
	s_nop 0
	v_cndmask_b32_e32 v85, 0, v78, vcc
	v_cmp_le_i32_e32 vcc, v76, v73
	v_cvt_pk_bf16_f32 v76, v75, v64
	v_cvt_pk_bf16_f32 v77, v80, v81
	v_cvt_pk_bf16_f32 v78, v83, v84
	v_add_u32_e32 v80, 2, v72
	v_add_u32_e32 v81, 3, v72
	v_cndmask_b32_e32 v79, 0, v79, vcc
	v_cvt_pk_bf16_f32 v79, v85, v79
	ds_read_b128 v[84:87], v71
	v_cmp_le_i32_e32 vcc, v72, v73
	s_waitcnt lgkmcnt(0)
	v_mfma_f32_32x32x16_bf16 v[16:31], v[76:79], v[84:87], v[16:31]
	ds_read_b128 v[84:87], v71 offset:8704
	v_add_u32_e32 v83, 4, v72
	s_waitcnt lgkmcnt(0)
	v_mfma_f32_32x32x16_bf16 v[0:15], v[76:79], v[84:87], v[0:15]

	v_lshl_add_u64 v[66:67], v[66:67], 0, s[94:95]
	s_waitcnt vmcnt(0)
	v_mov_b32_e32 v76, v232
	v_mov_b32_e32 v77, v233
	v_mov_b32_e32 v78, v234
	v_mov_b32_e32 v79, v235
	v_mov_b32_e32 v84, v236
	v_mov_b32_e32 v85, v237
	v_mov_b32_e32 v86, v238
	v_mov_b32_e32 v87, v239
	v_cndmask_b32_e32 v64, 0, v84, vcc
	v_cmp_lt_i32_e32 vcc, v72, v73
	s_nop 1
	v_cndmask_b32_e32 v75, 0, v85, vcc
	v_cmp_le_i32_e32 vcc, v80, v73
	s_nop 1
	v_cndmask_b32_e32 v80, 0, v86, vcc
	v_cmp_le_i32_e32 vcc, v81, v73
	s_nop 1
	v_cndmask_b32_e32 v81, 0, v87, vcc
	v_cmp_le_i32_e32 vcc, v83, v73
	s_nop 1
	v_cndmask_b32_e32 v83, 0, v76, vcc
	v_add_u32_e32 v76, 5, v72
	v_cmp_le_i32_e32 vcc, v76, v73
	v_add_u32_e32 v76, 6, v72
	s_nop 0
	v_cndmask_b32_e32 v84, 0, v77, vcc
	v_cmp_le_i32_e32 vcc, v76, v73
	v_add_u32_e32 v76, 7, v72
	v_add_u32_e32 v72, 32, v72
	v_cndmask_b32_e32 v85, 0, v78, vcc
	v_cmp_le_i32_e32 vcc, v76, v73
	v_cvt_pk_bf16_f32 v76, v64, v75
	v_cvt_pk_bf16_f32 v77, v80, v81
	v_cvt_pk_bf16_f32 v78, v83, v84
	s_nop 1
	v_cndmask_b32_e32 v79, 0, v79, vcc
	v_cvt_pk_bf16_f32 v79, v85, v79
	ds_read_b128 v[84:87], v71 offset:32
	v_cmp_ge_i32_e32 vcc, s2, v74
	s_waitcnt lgkmcnt(0)
	v_mfma_f32_32x32x16_bf16 v[16:31], v[76:79], v[84:87], v[16:31]
	ds_read_b128 v[84:87], v71 offset:8736
	v_add_u32_e32 v71, 64, v71
	s_or_b64 s[26:27], vcc, s[26:27]
	s_waitcnt lgkmcnt(0)
	v_mfma_f32_32x32x16_bf16 v[0:15], v[76:79], v[84:87], v[0:15]
	s_andn2_b64 exec, exec, s[26:27]
	s_cbranch_execnz .LBB0_443
	s_or_b64 exec, exec, s[26:27]
	s_branch .LBB0_404
